# MFMA half signals the phase-end barrier one MFMA early; trailing MFMA at raised priority, static priority restored after
# baseline (speedup 1.0000x reference)
.Lg131_noy:
	ds_read_b128 v[152:155], v149
	ds_read_b128 v[156:159], v149 offset:1024
	ds_read_b128 v[160:163], v149 offset:2048
	ds_read_b128 v[164:167], v149 offset:3072
	s_add_u32 s26, s20, 0xfffc0080
	s_addc_u32 s27, s21, -1
	s_cmp_eq_u32 s57, 12
	s_cselect_b32 s29, s13, s27
	s_cselect_b32 s28, s53, s26
	s_cselect_b32 s27, s11, s56
	s_cselect_b32 s26, s54, s55
	s_add_i32 m0, s19, 0xc000
	ds_read_b128 v[168:171], v150
	ds_read_b128 v[172:175], v150 offset:1024
	ds_read_b128 v[176:179], v150 offset:2048
	ds_read_b128 v[180:183], v150 offset:3072
	ds_read_b128 v[184:187], v150 offset:4096
	ds_read_b128 v[188:191], v150 offset:5120
	ds_read_b128 v[192:195], v150 offset:6144
	ds_read_b128 v[196:199], v150 offset:7168
	global_load_lds_dwordx4 v136, s[20:21]
	s_add_i32 m0, s19, 0xe000
	s_nop 0
	global_load_lds_dwordx4 v138, s[20:21]
	s_waitcnt lgkmcnt(8)
	s_barrier
	s_waitcnt lgkmcnt(0)
	s_waitcnt lgkmcnt(0)
	v_mfma_f32_16x16x32_bf16 v[124:127], v[152:155], v[168:171], 0
	v_mfma_f32_16x16x32_bf16 v[120:123], v[160:163], v[168:171], 0
	v_mfma_f32_16x16x32_bf16 v[108:111], v[152:155], v[176:179], 0
	v_mfma_f32_16x16x32_bf16 v[104:107], v[160:163], v[176:179], 0
	v_mfma_f32_16x16x32_bf16 v[92:95], v[152:155], v[184:187], 0
	v_mfma_f32_16x16x32_bf16 v[88:91], v[160:163], v[184:187], 0
	v_mfma_f32_16x16x32_bf16 v[76:79], v[152:155], v[192:195], 0
	v_mfma_f32_16x16x32_bf16 v[72:75], v[160:163], v[192:195], 0
	v_mfma_f32_16x16x32_bf16 v[124:127], v[156:159], v[172:175], v[124:127]
	v_mfma_f32_16x16x32_bf16 v[120:123], v[164:167], v[172:175], v[120:123]
	v_mfma_f32_16x16x32_bf16 v[108:111], v[156:159], v[180:183], v[108:111]
	v_mfma_f32_16x16x32_bf16 v[104:107], v[164:167], v[180:183], v[104:107]
	v_mfma_f32_16x16x32_bf16 v[92:95], v[156:159], v[188:191], v[92:95]
	v_mfma_f32_16x16x32_bf16 v[88:91], v[164:167], v[188:191], v[88:91]
	v_mfma_f32_16x16x32_bf16 v[76:79], v[156:159], v[196:199], v[76:79]
	s_barrier
	s_setprio 3
	v_mfma_f32_16x16x32_bf16 v[72:75], v[164:167], v[196:199], v[72:75]
	s_setprio 0
	s_bitcmp1_b32 s37, 8
	s_cbranch_scc0 .Leb131_72
	s_setprio 1
.Leb131_72:
	s_add_i32 s58, s47, s38
	s_add_u32 s80, s26, 0x80
	s_addc_u32 s81, s27, 0
	s_mov_b32 m0, s58
	ds_read_b128 v[200:203], v151
	ds_read_b128 v[204:207], v151 offset:1024
	ds_read_b128 v[208:211], v151 offset:2048
	ds_read_b128 v[212:215], v151 offset:3072
	global_load_lds_dwordx4 v132, s[26:27]
	s_add_i32 m0, s58, 0x2000
	s_nop 0
	global_load_lds_dwordx4 v128, s[26:27]
	s_waitcnt vmcnt(10)
	s_barrier
	s_waitcnt lgkmcnt(0)
	s_waitcnt lgkmcnt(0)
	v_mfma_f32_16x16x32_bf16 v[116:119], v[200:203], v[168:171], 0
	v_mfma_f32_16x16x32_bf16 v[112:115], v[208:211], v[168:171], 0
	v_mfma_f32_16x16x32_bf16 v[100:103], v[200:203], v[176:179], 0
	v_mfma_f32_16x16x32_bf16 v[96:99], v[208:211], v[176:179], 0
	v_mfma_f32_16x16x32_bf16 v[84:87], v[200:203], v[184:187], 0
	v_mfma_f32_16x16x32_bf16 v[80:83], v[208:211], v[184:187], 0
	v_mfma_f32_16x16x32_bf16 v[68:71], v[200:203], v[192:195], 0
	v_mfma_f32_16x16x32_bf16 v[64:67], v[208:211], v[192:195], 0
	v_mfma_f32_16x16x32_bf16 v[116:119], v[204:207], v[172:175], v[116:119]
	v_mfma_f32_16x16x32_bf16 v[112:115], v[212:215], v[172:175], v[112:115]
	v_mfma_f32_16x16x32_bf16 v[100:103], v[204:207], v[180:183], v[100:103]
	v_mfma_f32_16x16x32_bf16 v[96:99], v[212:215], v[180:183], v[96:99]
	v_mfma_f32_16x16x32_bf16 v[84:87], v[204:207], v[188:191], v[84:87]
	v_mfma_f32_16x16x32_bf16 v[80:83], v[212:215], v[188:191], v[80:83]
	v_mfma_f32_16x16x32_bf16 v[68:71], v[204:207], v[196:199], v[68:71]
	s_barrier
	s_setprio 3
	v_mfma_f32_16x16x32_bf16 v[64:67], v[212:215], v[196:199], v[64:67]
	s_setprio 0
	s_bitcmp1_b32 s37, 8
	s_cbranch_scc0 .Leb131_71
	s_setprio 1
.Leb131_71:
	s_mov_b32 m0, s19
	s_add_u32 s82, s28, 0x80
	s_addc_u32 s83, s29, 0
	ds_read_b128 v[168:171], v150 offset:16384
	ds_read_b128 v[172:175], v150 offset:17408
	ds_read_b128 v[176:179], v150 offset:18432
	ds_read_b128 v[180:183], v150 offset:19456
	ds_read_b128 v[184:187], v150 offset:20480
	ds_read_b128 v[188:191], v150 offset:21504
	ds_read_b128 v[192:195], v150 offset:22528
	ds_read_b128 v[196:199], v150 offset:23552
	global_load_lds_dwordx4 v134, s[28:29]
	s_mov_b32 m0, s42
	s_nop 0
	global_load_lds_dwordx4 v130, s[28:29]
	s_barrier
	s_waitcnt lgkmcnt(0)
	s_waitcnt lgkmcnt(0)
	v_mfma_f32_16x16x32_bf16 v[60:63], v[152:155], v[168:171], 0
	v_mfma_f32_16x16x32_bf16 v[56:59], v[160:163], v[168:171], 0
	v_mfma_f32_16x16x32_bf16 v[44:47], v[152:155], v[176:179], 0
	v_mfma_f32_16x16x32_bf16 v[40:43], v[160:163], v[176:179], 0
	v_mfma_f32_16x16x32_bf16 v[28:31], v[152:155], v[184:187], 0
	v_mfma_f32_16x16x32_bf16 v[24:27], v[160:163], v[184:187], 0
	v_mfma_f32_16x16x32_bf16 v[12:15], v[152:155], v[192:195], 0
	v_mfma_f32_16x16x32_bf16 v[8:11], v[160:163], v[192:195], 0
	v_mfma_f32_16x16x32_bf16 v[60:63], v[156:159], v[172:175], v[60:63]
	v_mfma_f32_16x16x32_bf16 v[56:59], v[164:167], v[172:175], v[56:59]
	v_mfma_f32_16x16x32_bf16 v[44:47], v[156:159], v[180:183], v[44:47]
	v_mfma_f32_16x16x32_bf16 v[40:43], v[164:167], v[180:183], v[40:43]
	v_mfma_f32_16x16x32_bf16 v[28:31], v[156:159], v[188:191], v[28:31]
	v_mfma_f32_16x16x32_bf16 v[24:27], v[164:167], v[188:191], v[24:27]
	v_mfma_f32_16x16x32_bf16 v[12:15], v[156:159], v[196:199], v[12:15]
	s_barrier
	s_setprio 3
	v_mfma_f32_16x16x32_bf16 v[8:11], v[164:167], v[196:199], v[8:11]
	s_setprio 0
	s_bitcmp1_b32 s37, 8
	s_cbranch_scc0 .Leb131_70
	s_setprio 1
.Leb131_70:
	s_add_u32 s58, s26, 0x40000
	s_addc_u32 s59, s27, 0
	s_add_i32 s60, s48, s38
	s_mov_b32 m0, s60
	s_nop 0
	global_load_lds_dwordx4 v132, s[58:59]
	s_add_i32 m0, s60, 0x2000
	s_nop 0
	global_load_lds_dwordx4 v128, s[58:59]
	s_waitcnt vmcnt(8)
	s_barrier
	v_mfma_f32_16x16x32_bf16 v[52:55], v[200:203], v[168:171], 0
	v_mfma_f32_16x16x32_bf16 v[48:51], v[208:211], v[168:171], 0
	v_mfma_f32_16x16x32_bf16 v[36:39], v[200:203], v[176:179], 0
	v_mfma_f32_16x16x32_bf16 v[32:35], v[208:211], v[176:179], 0
	v_mfma_f32_16x16x32_bf16 v[20:23], v[200:203], v[184:187], 0
	v_mfma_f32_16x16x32_bf16 v[16:19], v[208:211], v[184:187], 0
	v_mfma_f32_16x16x32_bf16 v[4:7], v[200:203], v[192:195], 0
	v_mfma_f32_16x16x32_bf16 v[0:3], v[208:211], v[192:195], 0
	v_mfma_f32_16x16x32_bf16 v[52:55], v[204:207], v[172:175], v[52:55]
	v_mfma_f32_16x16x32_bf16 v[48:51], v[212:215], v[172:175], v[48:51]
	v_mfma_f32_16x16x32_bf16 v[36:39], v[204:207], v[180:183], v[36:39]
	v_mfma_f32_16x16x32_bf16 v[32:35], v[212:215], v[180:183], v[32:35]
	v_mfma_f32_16x16x32_bf16 v[20:23], v[204:207], v[188:191], v[20:23]
	v_mfma_f32_16x16x32_bf16 v[16:19], v[212:215], v[188:191], v[16:19]
	v_mfma_f32_16x16x32_bf16 v[4:7], v[204:207], v[196:199], v[4:7]
	s_barrier
	s_setprio 3
	v_mfma_f32_16x16x32_bf16 v[0:3], v[212:215], v[196:199], v[0:3]
	s_setprio 0
	s_bitcmp1_b32 s37, 8
	s_cbranch_scc0 .Leb131_69
	s_setprio 1
.Leb131_69:
	s_add_i32 s58, 0, 0x18000
	v_add_u32_e32 v164, s58, v145
	s_branch .Lg131_mid
.LBB0_131:
	ds_read_b128 v[152:155], v149
	ds_read_b128 v[156:159], v149 offset:1024
	ds_read_b128 v[160:163], v149 offset:2048
	ds_read_b128 v[164:167], v149 offset:3072
	s_add_u32 s26, s20, 0xfffc0080
	s_addc_u32 s27, s21, -1
	s_cmp_eq_u32 s57, 12
	s_cselect_b32 s29, s13, s27
	s_cselect_b32 s28, s53, s26
	s_cselect_b32 s27, s11, s56
	s_cselect_b32 s26, s54, s55
	s_add_i32 m0, s19, 0xc000
	ds_read_b128 v[168:171], v150
	ds_read_b128 v[172:175], v150 offset:1024
	ds_read_b128 v[176:179], v150 offset:2048
	ds_read_b128 v[180:183], v150 offset:3072
	ds_read_b128 v[184:187], v150 offset:4096
	ds_read_b128 v[188:191], v150 offset:5120
	ds_read_b128 v[192:195], v150 offset:6144
	ds_read_b128 v[196:199], v150 offset:7168
	global_load_lds_dwordx4 v136, s[20:21]
	s_add_i32 m0, s19, 0xe000
	s_nop 0
	global_load_lds_dwordx4 v138, s[20:21]
	s_waitcnt lgkmcnt(8)
	s_barrier
	s_waitcnt lgkmcnt(0)
	s_waitcnt lgkmcnt(0)
	v_mfma_f32_16x16x32_bf16 v[124:127], v[152:155], v[168:171], v[124:127]
	v_mfma_f32_16x16x32_bf16 v[120:123], v[160:163], v[168:171], v[120:123]
	v_mfma_f32_16x16x32_bf16 v[108:111], v[152:155], v[176:179], v[108:111]
	v_mfma_f32_16x16x32_bf16 v[104:107], v[160:163], v[176:179], v[104:107]
	v_mfma_f32_16x16x32_bf16 v[92:95], v[152:155], v[184:187], v[92:95]
	v_mfma_f32_16x16x32_bf16 v[88:91], v[160:163], v[184:187], v[88:91]
	v_mfma_f32_16x16x32_bf16 v[76:79], v[152:155], v[192:195], v[76:79]
	v_mfma_f32_16x16x32_bf16 v[72:75], v[160:163], v[192:195], v[72:75]
	v_mfma_f32_16x16x32_bf16 v[124:127], v[156:159], v[172:175], v[124:127]
	v_mfma_f32_16x16x32_bf16 v[120:123], v[164:167], v[172:175], v[120:123]
	v_mfma_f32_16x16x32_bf16 v[108:111], v[156:159], v[180:183], v[108:111]
	v_mfma_f32_16x16x32_bf16 v[104:107], v[164:167], v[180:183], v[104:107]
	v_mfma_f32_16x16x32_bf16 v[92:95], v[156:159], v[188:191], v[92:95]
	v_mfma_f32_16x16x32_bf16 v[88:91], v[164:167], v[188:191], v[88:91]
	v_mfma_f32_16x16x32_bf16 v[76:79], v[156:159], v[196:199], v[76:79]
	s_barrier
	s_setprio 3
	v_mfma_f32_16x16x32_bf16 v[72:75], v[164:167], v[196:199], v[72:75]
	s_setprio 0
	s_bitcmp1_b32 s37, 8
	s_cbranch_scc0 .Leb131_68
	s_setprio 1
.Leb131_68:
	s_add_i32 s58, s47, s38
	s_add_u32 s80, s26, 0x80
	s_addc_u32 s81, s27, 0
	s_mov_b32 m0, s58
	ds_read_b128 v[200:203], v151
	ds_read_b128 v[204:207], v151 offset:1024
	ds_read_b128 v[208:211], v151 offset:2048
	ds_read_b128 v[212:215], v151 offset:3072
	global_load_lds_dwordx4 v132, s[26:27]
	s_add_i32 m0, s58, 0x2000
	s_nop 0
	global_load_lds_dwordx4 v128, s[26:27]
	s_waitcnt vmcnt(10)
	s_barrier
	s_waitcnt lgkmcnt(0)
	s_waitcnt lgkmcnt(0)
	v_mfma_f32_16x16x32_bf16 v[116:119], v[200:203], v[168:171], v[116:119]
	v_mfma_f32_16x16x32_bf16 v[112:115], v[208:211], v[168:171], v[112:115]
	v_mfma_f32_16x16x32_bf16 v[100:103], v[200:203], v[176:179], v[100:103]
	v_mfma_f32_16x16x32_bf16 v[96:99], v[208:211], v[176:179], v[96:99]
	v_mfma_f32_16x16x32_bf16 v[84:87], v[200:203], v[184:187], v[84:87]
	v_mfma_f32_16x16x32_bf16 v[80:83], v[208:211], v[184:187], v[80:83]
	v_mfma_f32_16x16x32_bf16 v[68:71], v[200:203], v[192:195], v[68:71]
	v_mfma_f32_16x16x32_bf16 v[64:67], v[208:211], v[192:195], v[64:67]
	v_mfma_f32_16x16x32_bf16 v[116:119], v[204:207], v[172:175], v[116:119]
	v_mfma_f32_16x16x32_bf16 v[112:115], v[212:215], v[172:175], v[112:115]
	v_mfma_f32_16x16x32_bf16 v[100:103], v[204:207], v[180:183], v[100:103]
	v_mfma_f32_16x16x32_bf16 v[96:99], v[212:215], v[180:183], v[96:99]
	v_mfma_f32_16x16x32_bf16 v[84:87], v[204:207], v[188:191], v[84:87]
	v_mfma_f32_16x16x32_bf16 v[80:83], v[212:215], v[188:191], v[80:83]
	v_mfma_f32_16x16x32_bf16 v[68:71], v[204:207], v[196:199], v[68:71]
	s_barrier
	s_setprio 3
	v_mfma_f32_16x16x32_bf16 v[64:67], v[212:215], v[196:199], v[64:67]
	s_setprio 0
	s_bitcmp1_b32 s37, 8
	s_cbranch_scc0 .Leb131_67
	s_setprio 1
.Leb131_67:
	s_mov_b32 m0, s19
	s_add_u32 s82, s28, 0x80
	s_addc_u32 s83, s29, 0
	ds_read_b128 v[168:171], v150 offset:16384
	ds_read_b128 v[172:175], v150 offset:17408
	ds_read_b128 v[176:179], v150 offset:18432
	ds_read_b128 v[180:183], v150 offset:19456
	ds_read_b128 v[184:187], v150 offset:20480
	ds_read_b128 v[188:191], v150 offset:21504
	ds_read_b128 v[192:195], v150 offset:22528
	ds_read_b128 v[196:199], v150 offset:23552
	global_load_lds_dwordx4 v134, s[28:29]
	s_mov_b32 m0, s42
	s_nop 0
	global_load_lds_dwordx4 v130, s[28:29]
	s_barrier
	s_waitcnt lgkmcnt(0)
	s_waitcnt lgkmcnt(0)
	v_mfma_f32_16x16x32_bf16 v[60:63], v[152:155], v[168:171], v[60:63]
	v_mfma_f32_16x16x32_bf16 v[56:59], v[160:163], v[168:171], v[56:59]
	v_mfma_f32_16x16x32_bf16 v[44:47], v[152:155], v[176:179], v[44:47]
	v_mfma_f32_16x16x32_bf16 v[40:43], v[160:163], v[176:179], v[40:43]
	v_mfma_f32_16x16x32_bf16 v[28:31], v[152:155], v[184:187], v[28:31]
	v_mfma_f32_16x16x32_bf16 v[24:27], v[160:163], v[184:187], v[24:27]
	v_mfma_f32_16x16x32_bf16 v[12:15], v[152:155], v[192:195], v[12:15]
	v_mfma_f32_16x16x32_bf16 v[8:11], v[160:163], v[192:195], v[8:11]
	v_mfma_f32_16x16x32_bf16 v[60:63], v[156:159], v[172:175], v[60:63]
	v_mfma_f32_16x16x32_bf16 v[56:59], v[164:167], v[172:175], v[56:59]
	v_mfma_f32_16x16x32_bf16 v[44:47], v[156:159], v[180:183], v[44:47]
	v_mfma_f32_16x16x32_bf16 v[40:43], v[164:167], v[180:183], v[40:43]
	v_mfma_f32_16x16x32_bf16 v[28:31], v[156:159], v[188:191], v[28:31]
	v_mfma_f32_16x16x32_bf16 v[24:27], v[164:167], v[188:191], v[24:27]
	v_mfma_f32_16x16x32_bf16 v[12:15], v[156:159], v[196:199], v[12:15]
	s_barrier
	s_setprio 3
	v_mfma_f32_16x16x32_bf16 v[8:11], v[164:167], v[196:199], v[8:11]
	s_setprio 0
	s_bitcmp1_b32 s37, 8
	s_cbranch_scc0 .Leb131_66
	s_setprio 1
.Leb131_66:
	s_add_u32 s58, s26, 0x40000
	s_addc_u32 s59, s27, 0
	s_add_i32 s60, s48, s38
	s_mov_b32 m0, s60
	s_nop 0
	global_load_lds_dwordx4 v132, s[58:59]
	s_add_i32 m0, s60, 0x2000
	s_nop 0
	global_load_lds_dwordx4 v128, s[58:59]
	s_waitcnt vmcnt(8)
	s_barrier
	v_mfma_f32_16x16x32_bf16 v[52:55], v[200:203], v[168:171], v[52:55]
	v_mfma_f32_16x16x32_bf16 v[48:51], v[208:211], v[168:171], v[48:51]
	v_mfma_f32_16x16x32_bf16 v[36:39], v[200:203], v[176:179], v[36:39]
	v_mfma_f32_16x16x32_bf16 v[32:35], v[208:211], v[176:179], v[32:35]
	v_mfma_f32_16x16x32_bf16 v[20:23], v[200:203], v[184:187], v[20:23]
	v_mfma_f32_16x16x32_bf16 v[16:19], v[208:211], v[184:187], v[16:19]
	v_mfma_f32_16x16x32_bf16 v[4:7], v[200:203], v[192:195], v[4:7]
	v_mfma_f32_16x16x32_bf16 v[0:3], v[208:211], v[192:195], v[0:3]
	v_mfma_f32_16x16x32_bf16 v[52:55], v[204:207], v[172:175], v[52:55]
	v_mfma_f32_16x16x32_bf16 v[48:51], v[212:215], v[172:175], v[48:51]
	v_mfma_f32_16x16x32_bf16 v[36:39], v[204:207], v[180:183], v[36:39]
	v_mfma_f32_16x16x32_bf16 v[32:35], v[212:215], v[180:183], v[32:35]
	v_mfma_f32_16x16x32_bf16 v[20:23], v[204:207], v[188:191], v[20:23]
	v_mfma_f32_16x16x32_bf16 v[16:19], v[212:215], v[188:191], v[16:19]
	v_mfma_f32_16x16x32_bf16 v[4:7], v[204:207], v[196:199], v[4:7]
	s_barrier
	s_setprio 3
	v_mfma_f32_16x16x32_bf16 v[0:3], v[212:215], v[196:199], v[0:3]
	s_setprio 0
	s_bitcmp1_b32 s37, 8
	s_cbranch_scc0 .Leb131_65
	s_setprio 1
.Leb131_65:
	s_add_i32 s58, 0, 0x18000
	v_add_u32_e32 v164, s58, v145
.Lg131_mid:
	ds_read_b128 v[152:155], v164
	ds_read_b128 v[156:159], v164 offset:1024
	ds_read_b128 v[160:163], v164 offset:2048
	ds_read_b128 v[164:167], v164 offset:3072
	s_add_u32 s28, s28, 0x40000
	s_addc_u32 s29, s29, 0
	s_mov_b32 m0, s43
	ds_read_b128 v[168:171], v150 offset:32768
	ds_read_b128 v[172:175], v150 offset:33792
	ds_read_b128 v[176:179], v150 offset:34816
	ds_read_b128 v[180:183], v150 offset:35840
	ds_read_b128 v[184:187], v150 offset:36864
	ds_read_b128 v[188:191], v150 offset:37888
	ds_read_b128 v[192:195], v150 offset:38912
	ds_read_b128 v[196:199], v150 offset:39936
	global_load_lds_dwordx4 v134, s[28:29]
	s_mov_b32 m0, s44
	s_nop 0
	global_load_lds_dwordx4 v130, s[28:29]
	s_waitcnt lgkmcnt(8)
	s_barrier
	s_waitcnt lgkmcnt(0)
	s_waitcnt lgkmcnt(0)
	v_mfma_f32_16x16x32_bf16 v[124:127], v[152:155], v[168:171], v[124:127]
	v_mfma_f32_16x16x32_bf16 v[120:123], v[160:163], v[168:171], v[120:123]
	v_mfma_f32_16x16x32_bf16 v[108:111], v[152:155], v[176:179], v[108:111]
	v_mfma_f32_16x16x32_bf16 v[104:107], v[160:163], v[176:179], v[104:107]
	v_mfma_f32_16x16x32_bf16 v[92:95], v[152:155], v[184:187], v[92:95]
	v_mfma_f32_16x16x32_bf16 v[88:91], v[160:163], v[184:187], v[88:91]
	v_mfma_f32_16x16x32_bf16 v[76:79], v[152:155], v[192:195], v[76:79]
	v_mfma_f32_16x16x32_bf16 v[72:75], v[160:163], v[192:195], v[72:75]
	v_mfma_f32_16x16x32_bf16 v[124:127], v[156:159], v[172:175], v[124:127]
	v_mfma_f32_16x16x32_bf16 v[120:123], v[164:167], v[172:175], v[120:123]
	v_mfma_f32_16x16x32_bf16 v[108:111], v[156:159], v[180:183], v[108:111]
	v_mfma_f32_16x16x32_bf16 v[104:107], v[164:167], v[180:183], v[104:107]
	v_mfma_f32_16x16x32_bf16 v[92:95], v[156:159], v[188:191], v[92:95]
	v_mfma_f32_16x16x32_bf16 v[88:91], v[164:167], v[188:191], v[88:91]
	v_mfma_f32_16x16x32_bf16 v[76:79], v[156:159], v[196:199], v[76:79]
	s_barrier
	s_setprio 3
	v_mfma_f32_16x16x32_bf16 v[72:75], v[164:167], v[196:199], v[72:75]
	s_setprio 0
	s_bitcmp1_b32 s37, 8
	s_cbranch_scc0 .Leb131_64
	s_setprio 1
.Leb131_64:
	s_add_i32 s28, 0, 0x1c000
	s_add_i32 s29, s58, s38
	v_add_u32_e32 v212, s28, v145
	s_mov_b32 m0, s29
	ds_read_b128 v[200:203], v212
	ds_read_b128 v[204:207], v212 offset:1024
	ds_read_b128 v[208:211], v212 offset:2048
	ds_read_b128 v[212:215], v212 offset:3072
	global_load_lds_dwordx4 v132, s[80:81]
	s_add_i32 m0, s29, 0x2000
	s_nop 0
	global_load_lds_dwordx4 v128, s[80:81]
	s_waitcnt vmcnt(10)
	s_barrier
	s_waitcnt lgkmcnt(0)
	s_waitcnt lgkmcnt(0)
	v_mfma_f32_16x16x32_bf16 v[116:119], v[200:203], v[168:171], v[116:119]
	v_mfma_f32_16x16x32_bf16 v[112:115], v[208:211], v[168:171], v[112:115]
	v_mfma_f32_16x16x32_bf16 v[100:103], v[200:203], v[176:179], v[100:103]
	v_mfma_f32_16x16x32_bf16 v[96:99], v[208:211], v[176:179], v[96:99]
	v_mfma_f32_16x16x32_bf16 v[84:87], v[200:203], v[184:187], v[84:87]
	v_mfma_f32_16x16x32_bf16 v[80:83], v[208:211], v[184:187], v[80:83]
	v_mfma_f32_16x16x32_bf16 v[68:71], v[200:203], v[192:195], v[68:71]
	v_mfma_f32_16x16x32_bf16 v[64:67], v[208:211], v[192:195], v[64:67]
	v_mfma_f32_16x16x32_bf16 v[116:119], v[204:207], v[172:175], v[116:119]
	v_mfma_f32_16x16x32_bf16 v[112:115], v[212:215], v[172:175], v[112:115]
	v_mfma_f32_16x16x32_bf16 v[100:103], v[204:207], v[180:183], v[100:103]
	v_mfma_f32_16x16x32_bf16 v[96:99], v[212:215], v[180:183], v[96:99]
	v_mfma_f32_16x16x32_bf16 v[84:87], v[204:207], v[188:191], v[84:87]
	v_mfma_f32_16x16x32_bf16 v[80:83], v[212:215], v[188:191], v[80:83]
	v_mfma_f32_16x16x32_bf16 v[68:71], v[204:207], v[196:199], v[68:71]
	s_barrier
	s_setprio 3
	v_mfma_f32_16x16x32_bf16 v[64:67], v[212:215], v[196:199], v[64:67]
	s_setprio 0
	s_bitcmp1_b32 s37, 8
	s_cbranch_scc0 .Leb131_63
	s_setprio 1
.Leb131_63:
	s_mov_b32 m0, s45
	ds_read_b128 v[168:171], v150 offset:49152
	ds_read_b128 v[172:175], v150 offset:50176
	ds_read_b128 v[176:179], v150 offset:51200
	ds_read_b128 v[180:183], v150 offset:52224
	ds_read_b128 v[184:187], v150 offset:53248
	ds_read_b128 v[188:191], v150 offset:54272
	ds_read_b128 v[192:195], v150 offset:55296
	ds_read_b128 v[196:199], v150 offset:56320
	global_load_lds_dwordx4 v134, s[82:83]
	s_mov_b32 m0, s46
	s_nop 0
	global_load_lds_dwordx4 v130, s[82:83]
	s_barrier
	s_waitcnt lgkmcnt(0)
	s_waitcnt lgkmcnt(0)
	v_mfma_f32_16x16x32_bf16 v[60:63], v[152:155], v[168:171], v[60:63]
	v_mfma_f32_16x16x32_bf16 v[56:59], v[160:163], v[168:171], v[56:59]
	v_mfma_f32_16x16x32_bf16 v[44:47], v[152:155], v[176:179], v[44:47]
	v_mfma_f32_16x16x32_bf16 v[40:43], v[160:163], v[176:179], v[40:43]
	v_mfma_f32_16x16x32_bf16 v[28:31], v[152:155], v[184:187], v[28:31]
	v_mfma_f32_16x16x32_bf16 v[24:27], v[160:163], v[184:187], v[24:27]
	v_mfma_f32_16x16x32_bf16 v[12:15], v[152:155], v[192:195], v[12:15]
	v_mfma_f32_16x16x32_bf16 v[8:11], v[160:163], v[192:195], v[8:11]
	v_mfma_f32_16x16x32_bf16 v[60:63], v[156:159], v[172:175], v[60:63]
	v_mfma_f32_16x16x32_bf16 v[56:59], v[164:167], v[172:175], v[56:59]
	v_mfma_f32_16x16x32_bf16 v[44:47], v[156:159], v[180:183], v[44:47]
	v_mfma_f32_16x16x32_bf16 v[40:43], v[164:167], v[180:183], v[40:43]
	v_mfma_f32_16x16x32_bf16 v[28:31], v[156:159], v[188:191], v[28:31]
	v_mfma_f32_16x16x32_bf16 v[24:27], v[164:167], v[188:191], v[24:27]
	v_mfma_f32_16x16x32_bf16 v[12:15], v[156:159], v[196:199], v[12:15]
	s_barrier
	s_setprio 3
	v_mfma_f32_16x16x32_bf16 v[8:11], v[164:167], v[196:199], v[8:11]
	s_setprio 0
	s_bitcmp1_b32 s37, 8
	s_cbranch_scc0 .Leb131_62
	s_setprio 1
.Leb131_62:
	s_add_u32 s26, s26, 0x40080
	s_addc_u32 s27, s27, 0
	s_add_i32 s28, s28, s38
	s_mov_b32 m0, s28
	s_nop 0
	global_load_lds_dwordx4 v132, s[26:27]
	s_add_i32 m0, s28, 0x2000
	s_nop 0
	global_load_lds_dwordx4 v128, s[26:27]
	s_waitcnt vmcnt(8)
	s_barrier
	v_mfma_f32_16x16x32_bf16 v[52:55], v[200:203], v[168:171], v[52:55]
	v_mfma_f32_16x16x32_bf16 v[48:51], v[208:211], v[168:171], v[48:51]
	v_mfma_f32_16x16x32_bf16 v[36:39], v[200:203], v[176:179], v[36:39]
	v_mfma_f32_16x16x32_bf16 v[32:35], v[208:211], v[176:179], v[32:35]
	v_mfma_f32_16x16x32_bf16 v[20:23], v[200:203], v[184:187], v[20:23]
	v_mfma_f32_16x16x32_bf16 v[16:19], v[208:211], v[184:187], v[16:19]
	v_mfma_f32_16x16x32_bf16 v[4:7], v[200:203], v[192:195], v[4:7]
	v_mfma_f32_16x16x32_bf16 v[0:3], v[208:211], v[192:195], v[0:3]
	v_mfma_f32_16x16x32_bf16 v[52:55], v[204:207], v[172:175], v[52:55]
	v_mfma_f32_16x16x32_bf16 v[48:51], v[212:215], v[172:175], v[48:51]
	v_mfma_f32_16x16x32_bf16 v[36:39], v[204:207], v[180:183], v[36:39]
	v_mfma_f32_16x16x32_bf16 v[32:35], v[212:215], v[180:183], v[32:35]
	v_mfma_f32_16x16x32_bf16 v[20:23], v[204:207], v[188:191], v[20:23]
	v_mfma_f32_16x16x32_bf16 v[16:19], v[212:215], v[188:191], v[16:19]
	v_mfma_f32_16x16x32_bf16 v[4:7], v[204:207], v[196:199], v[4:7]
	s_barrier
	s_setprio 3
	v_mfma_f32_16x16x32_bf16 v[0:3], v[212:215], v[196:199], v[0:3]
	s_setprio 0
	s_bitcmp1_b32 s37, 8
	s_cbranch_scc0 .Leb131_61
	s_setprio 1
.Leb131_61:
	s_add_i32 s57, s57, 2
	s_add_u32 s20, s20, 0x100
	s_addc_u32 s21, s21, 0
	s_add_u32 s55, s55, 0x100
	s_addc_u32 s56, s56, 0
	s_cmp_gt_u32 s57, 13
	s_cbranch_scc0 .LBB0_131
	s_nop 7
	s_nop 7
	s_setprio 0
	s_cmpk_gt_u32 s37, 0xff
	s_cbranch_scc1 .Lg131_nox
	s_barrier
	s_setprio 1

.Lg248_noy:
	ds_read_b128 v[144:147], v151
	ds_read_b128 v[156:159], v151 offset:1024
	ds_read_b128 v[160:163], v151 offset:2048
	ds_read_b128 v[164:167], v151 offset:3072
	s_add_u32 s26, s20, 0x100
	s_addc_u32 s27, s21, 0
	s_cmp_eq_u32 s59, 40
	s_cselect_b32 s31, s9, s27
	s_cselect_b32 s30, s8, s26
	s_cselect_b32 s29, s11, s58
	s_cselect_b32 s28, s10, s57
	s_add_i32 m0, s41, 0xc000
	ds_read_b128 v[168:171], v152
	ds_read_b128 v[172:175], v152 offset:1024
	ds_read_b128 v[176:179], v152 offset:2048
	ds_read_b128 v[180:183], v152 offset:3072
	ds_read_b128 v[184:187], v152 offset:4096
	ds_read_b128 v[188:191], v152 offset:5120
	ds_read_b128 v[192:195], v152 offset:6144
	ds_read_b128 v[196:199], v152 offset:7168
	global_load_lds_dwordx4 v136, s[20:21]
	s_add_i32 m0, s41, 0xe000
	s_nop 0
	global_load_lds_dwordx4 v138, s[20:21]
	s_waitcnt lgkmcnt(8)
	s_barrier
	s_waitcnt lgkmcnt(0)
	s_waitcnt lgkmcnt(0)
	v_mfma_f32_16x16x32_bf16 v[124:127], v[144:147], v[168:171], 0
	v_mfma_f32_16x16x32_bf16 v[120:123], v[160:163], v[168:171], 0
	v_mfma_f32_16x16x32_bf16 v[108:111], v[144:147], v[176:179], 0
	v_mfma_f32_16x16x32_bf16 v[104:107], v[160:163], v[176:179], 0
	v_mfma_f32_16x16x32_bf16 v[92:95], v[144:147], v[184:187], 0
	v_mfma_f32_16x16x32_bf16 v[88:91], v[160:163], v[184:187], 0
	v_mfma_f32_16x16x32_bf16 v[76:79], v[144:147], v[192:195], 0
	v_mfma_f32_16x16x32_bf16 v[72:75], v[160:163], v[192:195], 0
	v_mfma_f32_16x16x32_bf16 v[124:127], v[156:159], v[172:175], v[124:127]
	v_mfma_f32_16x16x32_bf16 v[120:123], v[164:167], v[172:175], v[120:123]
	v_mfma_f32_16x16x32_bf16 v[108:111], v[156:159], v[180:183], v[108:111]
	v_mfma_f32_16x16x32_bf16 v[104:107], v[164:167], v[180:183], v[104:107]
	v_mfma_f32_16x16x32_bf16 v[92:95], v[156:159], v[188:191], v[92:95]
	v_mfma_f32_16x16x32_bf16 v[88:91], v[164:167], v[188:191], v[88:91]
	v_mfma_f32_16x16x32_bf16 v[76:79], v[156:159], v[196:199], v[76:79]
	s_barrier
	s_setprio 3
	v_mfma_f32_16x16x32_bf16 v[72:75], v[164:167], v[196:199], v[72:75]
	s_setprio 0
	s_bitcmp1_b32 s35, 8
	s_cbranch_scc0 .Leb248_60
	s_setprio 1
.Leb248_60:
	s_add_i32 s20, s51, s40
	s_add_u32 s80, s28, 0x80
	s_addc_u32 s81, s29, 0
	s_mov_b32 m0, s20
	ds_read_b128 v[200:203], v153
	ds_read_b128 v[204:207], v153 offset:1024
	ds_read_b128 v[208:211], v153 offset:2048
	ds_read_b128 v[212:215], v153 offset:3072
	global_load_lds_dwordx4 v130, s[28:29]
	s_add_i32 m0, s20, 0x2000
	s_nop 0
	global_load_lds_dwordx4 v134, s[28:29]
	s_waitcnt vmcnt(10)
	s_barrier
	s_waitcnt lgkmcnt(0)
	s_waitcnt lgkmcnt(0)
	v_mfma_f32_16x16x32_bf16 v[116:119], v[200:203], v[168:171], 0
	v_mfma_f32_16x16x32_bf16 v[112:115], v[208:211], v[168:171], 0
	v_mfma_f32_16x16x32_bf16 v[100:103], v[200:203], v[176:179], 0
	v_mfma_f32_16x16x32_bf16 v[96:99], v[208:211], v[176:179], 0
	v_mfma_f32_16x16x32_bf16 v[84:87], v[200:203], v[184:187], 0
	v_mfma_f32_16x16x32_bf16 v[80:83], v[208:211], v[184:187], 0
	v_mfma_f32_16x16x32_bf16 v[68:71], v[200:203], v[192:195], 0
	v_mfma_f32_16x16x32_bf16 v[64:67], v[208:211], v[192:195], 0
	v_mfma_f32_16x16x32_bf16 v[116:119], v[204:207], v[172:175], v[116:119]
	v_mfma_f32_16x16x32_bf16 v[112:115], v[212:215], v[172:175], v[112:115]
	v_mfma_f32_16x16x32_bf16 v[100:103], v[204:207], v[180:183], v[100:103]
	v_mfma_f32_16x16x32_bf16 v[96:99], v[212:215], v[180:183], v[96:99]
	v_mfma_f32_16x16x32_bf16 v[84:87], v[204:207], v[188:191], v[84:87]
	v_mfma_f32_16x16x32_bf16 v[80:83], v[212:215], v[188:191], v[80:83]
	v_mfma_f32_16x16x32_bf16 v[68:71], v[204:207], v[196:199], v[68:71]
	s_barrier
	s_setprio 3
	v_mfma_f32_16x16x32_bf16 v[64:67], v[212:215], v[196:199], v[64:67]
	s_setprio 0
	s_bitcmp1_b32 s35, 8
	s_cbranch_scc0 .Leb248_59
	s_setprio 1
.Leb248_59:
	s_mov_b32 m0, s41
	s_add_u32 s82, s30, 0x80
	s_addc_u32 s83, s31, 0
	ds_read_b128 v[168:171], v152 offset:16384
	ds_read_b128 v[172:175], v152 offset:17408
	ds_read_b128 v[176:179], v152 offset:18432
	ds_read_b128 v[180:183], v152 offset:19456
	ds_read_b128 v[184:187], v152 offset:20480
	ds_read_b128 v[188:191], v152 offset:21504
	ds_read_b128 v[192:195], v152 offset:22528
	ds_read_b128 v[196:199], v152 offset:23552
	global_load_lds_dwordx4 v128, s[30:31]
	s_mov_b32 m0, s42
	s_nop 0
	global_load_lds_dwordx4 v132, s[30:31]
	s_barrier
	s_waitcnt lgkmcnt(0)
	s_waitcnt lgkmcnt(0)
	v_mfma_f32_16x16x32_bf16 v[60:63], v[144:147], v[168:171], 0
	v_mfma_f32_16x16x32_bf16 v[56:59], v[160:163], v[168:171], 0
	v_mfma_f32_16x16x32_bf16 v[44:47], v[144:147], v[176:179], 0
	v_mfma_f32_16x16x32_bf16 v[40:43], v[160:163], v[176:179], 0
	v_mfma_f32_16x16x32_bf16 v[28:31], v[144:147], v[184:187], 0
	v_mfma_f32_16x16x32_bf16 v[24:27], v[160:163], v[184:187], 0
	v_mfma_f32_16x16x32_bf16 v[12:15], v[144:147], v[192:195], 0
	v_mfma_f32_16x16x32_bf16 v[8:11], v[160:163], v[192:195], 0
	v_mfma_f32_16x16x32_bf16 v[60:63], v[156:159], v[172:175], v[60:63]
	v_mfma_f32_16x16x32_bf16 v[56:59], v[164:167], v[172:175], v[56:59]
	v_mfma_f32_16x16x32_bf16 v[44:47], v[156:159], v[180:183], v[44:47]
	v_mfma_f32_16x16x32_bf16 v[40:43], v[164:167], v[180:183], v[40:43]
	v_mfma_f32_16x16x32_bf16 v[28:31], v[156:159], v[188:191], v[28:31]
	v_mfma_f32_16x16x32_bf16 v[24:27], v[164:167], v[188:191], v[24:27]
	v_mfma_f32_16x16x32_bf16 v[12:15], v[156:159], v[196:199], v[12:15]
	s_barrier
	s_setprio 3
	v_mfma_f32_16x16x32_bf16 v[8:11], v[164:167], v[196:199], v[8:11]
	s_setprio 0
	s_bitcmp1_b32 s35, 8
	s_cbranch_scc0 .Leb248_58
	s_setprio 1
.Leb248_58:
	s_add_u32 s20, s28, 0xb0000
	s_addc_u32 s21, s29, 0
	s_add_i32 s60, s52, s40
	s_mov_b32 m0, s60
	s_nop 0
	global_load_lds_dwordx4 v130, s[20:21]
	s_add_i32 m0, s60, 0x2000
	s_nop 0
	global_load_lds_dwordx4 v134, s[20:21]
	s_waitcnt vmcnt(8)
	s_barrier
	v_mfma_f32_16x16x32_bf16 v[52:55], v[200:203], v[168:171], 0
	v_mfma_f32_16x16x32_bf16 v[48:51], v[208:211], v[168:171], 0
	v_mfma_f32_16x16x32_bf16 v[36:39], v[200:203], v[176:179], 0
	v_mfma_f32_16x16x32_bf16 v[32:35], v[208:211], v[176:179], 0
	v_mfma_f32_16x16x32_bf16 v[20:23], v[200:203], v[184:187], 0
	v_mfma_f32_16x16x32_bf16 v[16:19], v[208:211], v[184:187], 0
	v_mfma_f32_16x16x32_bf16 v[4:7], v[200:203], v[192:195], 0
	v_mfma_f32_16x16x32_bf16 v[0:3], v[208:211], v[192:195], 0
	v_mfma_f32_16x16x32_bf16 v[52:55], v[204:207], v[172:175], v[52:55]
	v_mfma_f32_16x16x32_bf16 v[48:51], v[212:215], v[172:175], v[48:51]
	v_mfma_f32_16x16x32_bf16 v[36:39], v[204:207], v[180:183], v[36:39]
	v_mfma_f32_16x16x32_bf16 v[32:35], v[212:215], v[180:183], v[32:35]
	v_mfma_f32_16x16x32_bf16 v[20:23], v[204:207], v[188:191], v[20:23]
	v_mfma_f32_16x16x32_bf16 v[16:19], v[212:215], v[188:191], v[16:19]
	v_mfma_f32_16x16x32_bf16 v[4:7], v[204:207], v[196:199], v[4:7]
	s_barrier
	s_setprio 3
	v_mfma_f32_16x16x32_bf16 v[0:3], v[212:215], v[196:199], v[0:3]
	s_setprio 0
	s_bitcmp1_b32 s35, 8
	s_cbranch_scc0 .Leb248_57
	s_setprio 1
.Leb248_57:
	s_add_i32 s60, 0, 0x18000
	v_add_u32_e32 v155, s60, v149
	s_branch .Lg248_mid
.LBB0_248:
	ds_read_b128 v[144:147], v151
	ds_read_b128 v[156:159], v151 offset:1024
	ds_read_b128 v[160:163], v151 offset:2048
	ds_read_b128 v[164:167], v151 offset:3072
	s_add_u32 s26, s20, 0x100
	s_addc_u32 s27, s21, 0
	s_cmp_eq_u32 s59, 40
	s_cselect_b32 s31, s9, s27
	s_cselect_b32 s30, s8, s26
	s_cselect_b32 s29, s11, s58
	s_cselect_b32 s28, s10, s57
	s_add_i32 m0, s41, 0xc000
	ds_read_b128 v[168:171], v152
	ds_read_b128 v[172:175], v152 offset:1024
	ds_read_b128 v[176:179], v152 offset:2048
	ds_read_b128 v[180:183], v152 offset:3072
	ds_read_b128 v[184:187], v152 offset:4096
	ds_read_b128 v[188:191], v152 offset:5120
	ds_read_b128 v[192:195], v152 offset:6144
	ds_read_b128 v[196:199], v152 offset:7168
	global_load_lds_dwordx4 v136, s[20:21]
	s_add_i32 m0, s41, 0xe000
	s_nop 0
	global_load_lds_dwordx4 v138, s[20:21]
	s_waitcnt lgkmcnt(8)
	s_barrier
	s_waitcnt lgkmcnt(0)
	s_waitcnt lgkmcnt(0)
	v_mfma_f32_16x16x32_bf16 v[124:127], v[144:147], v[168:171], v[124:127]
	v_mfma_f32_16x16x32_bf16 v[120:123], v[160:163], v[168:171], v[120:123]
	v_mfma_f32_16x16x32_bf16 v[108:111], v[144:147], v[176:179], v[108:111]
	v_mfma_f32_16x16x32_bf16 v[104:107], v[160:163], v[176:179], v[104:107]
	v_mfma_f32_16x16x32_bf16 v[92:95], v[144:147], v[184:187], v[92:95]
	v_mfma_f32_16x16x32_bf16 v[88:91], v[160:163], v[184:187], v[88:91]
	v_mfma_f32_16x16x32_bf16 v[76:79], v[144:147], v[192:195], v[76:79]
	v_mfma_f32_16x16x32_bf16 v[72:75], v[160:163], v[192:195], v[72:75]
	v_mfma_f32_16x16x32_bf16 v[124:127], v[156:159], v[172:175], v[124:127]
	v_mfma_f32_16x16x32_bf16 v[120:123], v[164:167], v[172:175], v[120:123]
	v_mfma_f32_16x16x32_bf16 v[108:111], v[156:159], v[180:183], v[108:111]
	v_mfma_f32_16x16x32_bf16 v[104:107], v[164:167], v[180:183], v[104:107]
	v_mfma_f32_16x16x32_bf16 v[92:95], v[156:159], v[188:191], v[92:95]
	v_mfma_f32_16x16x32_bf16 v[88:91], v[164:167], v[188:191], v[88:91]
	v_mfma_f32_16x16x32_bf16 v[76:79], v[156:159], v[196:199], v[76:79]
	s_barrier
	s_setprio 3
	v_mfma_f32_16x16x32_bf16 v[72:75], v[164:167], v[196:199], v[72:75]
	s_setprio 0
	s_bitcmp1_b32 s35, 8
	s_cbranch_scc0 .Leb248_56
	s_setprio 1
.Leb248_56:
	s_add_i32 s20, s51, s40
	s_add_u32 s80, s28, 0x80
	s_addc_u32 s81, s29, 0
	s_mov_b32 m0, s20
	ds_read_b128 v[200:203], v153
	ds_read_b128 v[204:207], v153 offset:1024
	ds_read_b128 v[208:211], v153 offset:2048
	ds_read_b128 v[212:215], v153 offset:3072
	global_load_lds_dwordx4 v130, s[28:29]
	s_add_i32 m0, s20, 0x2000
	s_nop 0
	global_load_lds_dwordx4 v134, s[28:29]
	s_waitcnt vmcnt(10)
	s_barrier
	s_waitcnt lgkmcnt(0)
	s_waitcnt lgkmcnt(0)
	v_mfma_f32_16x16x32_bf16 v[116:119], v[200:203], v[168:171], v[116:119]
	v_mfma_f32_16x16x32_bf16 v[112:115], v[208:211], v[168:171], v[112:115]
	v_mfma_f32_16x16x32_bf16 v[100:103], v[200:203], v[176:179], v[100:103]
	v_mfma_f32_16x16x32_bf16 v[96:99], v[208:211], v[176:179], v[96:99]
	v_mfma_f32_16x16x32_bf16 v[84:87], v[200:203], v[184:187], v[84:87]
	v_mfma_f32_16x16x32_bf16 v[80:83], v[208:211], v[184:187], v[80:83]
	v_mfma_f32_16x16x32_bf16 v[68:71], v[200:203], v[192:195], v[68:71]
	v_mfma_f32_16x16x32_bf16 v[64:67], v[208:211], v[192:195], v[64:67]
	v_mfma_f32_16x16x32_bf16 v[116:119], v[204:207], v[172:175], v[116:119]
	v_mfma_f32_16x16x32_bf16 v[112:115], v[212:215], v[172:175], v[112:115]
	v_mfma_f32_16x16x32_bf16 v[100:103], v[204:207], v[180:183], v[100:103]
	v_mfma_f32_16x16x32_bf16 v[96:99], v[212:215], v[180:183], v[96:99]
	v_mfma_f32_16x16x32_bf16 v[84:87], v[204:207], v[188:191], v[84:87]
	v_mfma_f32_16x16x32_bf16 v[80:83], v[212:215], v[188:191], v[80:83]
	v_mfma_f32_16x16x32_bf16 v[68:71], v[204:207], v[196:199], v[68:71]
	s_barrier
	s_setprio 3
	v_mfma_f32_16x16x32_bf16 v[64:67], v[212:215], v[196:199], v[64:67]
	s_setprio 0
	s_bitcmp1_b32 s35, 8
	s_cbranch_scc0 .Leb248_55
	s_setprio 1
.Leb248_55:
	s_mov_b32 m0, s41
	s_add_u32 s82, s30, 0x80
	s_addc_u32 s83, s31, 0
	ds_read_b128 v[168:171], v152 offset:16384
	ds_read_b128 v[172:175], v152 offset:17408
	ds_read_b128 v[176:179], v152 offset:18432
	ds_read_b128 v[180:183], v152 offset:19456
	ds_read_b128 v[184:187], v152 offset:20480
	ds_read_b128 v[188:191], v152 offset:21504
	ds_read_b128 v[192:195], v152 offset:22528
	ds_read_b128 v[196:199], v152 offset:23552
	global_load_lds_dwordx4 v128, s[30:31]
	s_mov_b32 m0, s42
	s_nop 0
	global_load_lds_dwordx4 v132, s[30:31]
	s_barrier
	s_waitcnt lgkmcnt(0)
	s_waitcnt lgkmcnt(0)
	v_mfma_f32_16x16x32_bf16 v[60:63], v[144:147], v[168:171], v[60:63]
	v_mfma_f32_16x16x32_bf16 v[56:59], v[160:163], v[168:171], v[56:59]
	v_mfma_f32_16x16x32_bf16 v[44:47], v[144:147], v[176:179], v[44:47]
	v_mfma_f32_16x16x32_bf16 v[40:43], v[160:163], v[176:179], v[40:43]
	v_mfma_f32_16x16x32_bf16 v[28:31], v[144:147], v[184:187], v[28:31]
	v_mfma_f32_16x16x32_bf16 v[24:27], v[160:163], v[184:187], v[24:27]
	v_mfma_f32_16x16x32_bf16 v[12:15], v[144:147], v[192:195], v[12:15]
	v_mfma_f32_16x16x32_bf16 v[8:11], v[160:163], v[192:195], v[8:11]
	v_mfma_f32_16x16x32_bf16 v[60:63], v[156:159], v[172:175], v[60:63]
	v_mfma_f32_16x16x32_bf16 v[56:59], v[164:167], v[172:175], v[56:59]
	v_mfma_f32_16x16x32_bf16 v[44:47], v[156:159], v[180:183], v[44:47]
	v_mfma_f32_16x16x32_bf16 v[40:43], v[164:167], v[180:183], v[40:43]
	v_mfma_f32_16x16x32_bf16 v[28:31], v[156:159], v[188:191], v[28:31]
	v_mfma_f32_16x16x32_bf16 v[24:27], v[164:167], v[188:191], v[24:27]
	v_mfma_f32_16x16x32_bf16 v[12:15], v[156:159], v[196:199], v[12:15]
	s_barrier
	s_setprio 3
	v_mfma_f32_16x16x32_bf16 v[8:11], v[164:167], v[196:199], v[8:11]
	s_setprio 0
	s_bitcmp1_b32 s35, 8
	s_cbranch_scc0 .Leb248_54
	s_setprio 1
.Leb248_54:
	s_add_u32 s20, s28, 0xb0000
	s_addc_u32 s21, s29, 0
	s_add_i32 s60, s52, s40
	s_mov_b32 m0, s60
	s_nop 0
	global_load_lds_dwordx4 v130, s[20:21]
	s_add_i32 m0, s60, 0x2000
	s_nop 0
	global_load_lds_dwordx4 v134, s[20:21]
	s_waitcnt vmcnt(8)
	s_barrier
	v_mfma_f32_16x16x32_bf16 v[52:55], v[200:203], v[168:171], v[52:55]
	v_mfma_f32_16x16x32_bf16 v[48:51], v[208:211], v[168:171], v[48:51]
	v_mfma_f32_16x16x32_bf16 v[36:39], v[200:203], v[176:179], v[36:39]
	v_mfma_f32_16x16x32_bf16 v[32:35], v[208:211], v[176:179], v[32:35]
	v_mfma_f32_16x16x32_bf16 v[20:23], v[200:203], v[184:187], v[20:23]
	v_mfma_f32_16x16x32_bf16 v[16:19], v[208:211], v[184:187], v[16:19]
	v_mfma_f32_16x16x32_bf16 v[4:7], v[200:203], v[192:195], v[4:7]
	v_mfma_f32_16x16x32_bf16 v[0:3], v[208:211], v[192:195], v[0:3]
	v_mfma_f32_16x16x32_bf16 v[52:55], v[204:207], v[172:175], v[52:55]
	v_mfma_f32_16x16x32_bf16 v[48:51], v[212:215], v[172:175], v[48:51]
	v_mfma_f32_16x16x32_bf16 v[36:39], v[204:207], v[180:183], v[36:39]
	v_mfma_f32_16x16x32_bf16 v[32:35], v[212:215], v[180:183], v[32:35]
	v_mfma_f32_16x16x32_bf16 v[20:23], v[204:207], v[188:191], v[20:23]
	v_mfma_f32_16x16x32_bf16 v[16:19], v[212:215], v[188:191], v[16:19]
	v_mfma_f32_16x16x32_bf16 v[4:7], v[204:207], v[196:199], v[4:7]
	s_barrier
	s_setprio 3
	v_mfma_f32_16x16x32_bf16 v[0:3], v[212:215], v[196:199], v[0:3]
	s_setprio 0
	s_bitcmp1_b32 s35, 8
	s_cbranch_scc0 .Leb248_53
	s_setprio 1
.Leb248_53:
	s_add_i32 s60, 0, 0x18000
	v_add_u32_e32 v155, s60, v149
.Lg248_mid:
	ds_read_b128 v[144:147], v155
	ds_read_b128 v[156:159], v155 offset:1024
	ds_read_b128 v[160:163], v155 offset:2048
	ds_read_b128 v[164:167], v155 offset:3072
	s_add_u32 s20, s30, 0xb0000
	s_addc_u32 s21, s31, 0
	s_mov_b32 m0, s43
	ds_read_b128 v[168:171], v152 offset:32768
	ds_read_b128 v[172:175], v152 offset:33792
	ds_read_b128 v[176:179], v152 offset:34816
	ds_read_b128 v[180:183], v152 offset:35840
	ds_read_b128 v[184:187], v152 offset:36864
	ds_read_b128 v[188:191], v152 offset:37888
	ds_read_b128 v[192:195], v152 offset:38912
	ds_read_b128 v[196:199], v152 offset:39936
	global_load_lds_dwordx4 v128, s[20:21]
	s_mov_b32 m0, s44
	s_nop 0
	global_load_lds_dwordx4 v132, s[20:21]
	s_waitcnt lgkmcnt(8)
	s_barrier
	s_waitcnt lgkmcnt(0)
	s_waitcnt lgkmcnt(0)
	v_mfma_f32_16x16x32_bf16 v[124:127], v[144:147], v[168:171], v[124:127]
	v_mfma_f32_16x16x32_bf16 v[120:123], v[160:163], v[168:171], v[120:123]
	v_mfma_f32_16x16x32_bf16 v[108:111], v[144:147], v[176:179], v[108:111]
	v_mfma_f32_16x16x32_bf16 v[104:107], v[160:163], v[176:179], v[104:107]
	v_mfma_f32_16x16x32_bf16 v[92:95], v[144:147], v[184:187], v[92:95]
	v_mfma_f32_16x16x32_bf16 v[88:91], v[160:163], v[184:187], v[88:91]
	v_mfma_f32_16x16x32_bf16 v[76:79], v[144:147], v[192:195], v[76:79]
	v_mfma_f32_16x16x32_bf16 v[72:75], v[160:163], v[192:195], v[72:75]
	v_mfma_f32_16x16x32_bf16 v[124:127], v[156:159], v[172:175], v[124:127]
	v_mfma_f32_16x16x32_bf16 v[120:123], v[164:167], v[172:175], v[120:123]
	v_mfma_f32_16x16x32_bf16 v[108:111], v[156:159], v[180:183], v[108:111]
	v_mfma_f32_16x16x32_bf16 v[104:107], v[164:167], v[180:183], v[104:107]
	v_mfma_f32_16x16x32_bf16 v[92:95], v[156:159], v[188:191], v[92:95]
	v_mfma_f32_16x16x32_bf16 v[88:91], v[164:167], v[188:191], v[88:91]
	v_mfma_f32_16x16x32_bf16 v[76:79], v[156:159], v[196:199], v[76:79]
	s_barrier
	s_setprio 3
	v_mfma_f32_16x16x32_bf16 v[72:75], v[164:167], v[196:199], v[72:75]
	s_setprio 0
	s_bitcmp1_b32 s35, 8
	s_cbranch_scc0 .Leb248_52
	s_setprio 1
.Leb248_52:
	s_add_i32 s30, 0, 0x1c000
	s_add_i32 s20, s60, s40
	v_add_u32_e32 v155, s30, v149
	s_mov_b32 m0, s20
	ds_read_b128 v[200:203], v155
	ds_read_b128 v[204:207], v155 offset:1024
	ds_read_b128 v[208:211], v155 offset:2048
	ds_read_b128 v[212:215], v155 offset:3072
	global_load_lds_dwordx4 v130, s[80:81]
	s_add_i32 m0, s20, 0x2000
	s_nop 0
	global_load_lds_dwordx4 v134, s[80:81]
	s_waitcnt vmcnt(10)
	s_barrier
	s_waitcnt lgkmcnt(0)
	s_waitcnt lgkmcnt(0)
	v_mfma_f32_16x16x32_bf16 v[116:119], v[200:203], v[168:171], v[116:119]
	v_mfma_f32_16x16x32_bf16 v[112:115], v[208:211], v[168:171], v[112:115]
	v_mfma_f32_16x16x32_bf16 v[100:103], v[200:203], v[176:179], v[100:103]
	v_mfma_f32_16x16x32_bf16 v[96:99], v[208:211], v[176:179], v[96:99]
	v_mfma_f32_16x16x32_bf16 v[84:87], v[200:203], v[184:187], v[84:87]
	v_mfma_f32_16x16x32_bf16 v[80:83], v[208:211], v[184:187], v[80:83]
	v_mfma_f32_16x16x32_bf16 v[68:71], v[200:203], v[192:195], v[68:71]
	v_mfma_f32_16x16x32_bf16 v[64:67], v[208:211], v[192:195], v[64:67]
	v_mfma_f32_16x16x32_bf16 v[116:119], v[204:207], v[172:175], v[116:119]
	v_mfma_f32_16x16x32_bf16 v[112:115], v[212:215], v[172:175], v[112:115]
	v_mfma_f32_16x16x32_bf16 v[100:103], v[204:207], v[180:183], v[100:103]
	v_mfma_f32_16x16x32_bf16 v[96:99], v[212:215], v[180:183], v[96:99]
	v_mfma_f32_16x16x32_bf16 v[84:87], v[204:207], v[188:191], v[84:87]
	v_mfma_f32_16x16x32_bf16 v[80:83], v[212:215], v[188:191], v[80:83]
	v_mfma_f32_16x16x32_bf16 v[68:71], v[204:207], v[196:199], v[68:71]
	s_barrier
	s_setprio 3
	v_mfma_f32_16x16x32_bf16 v[64:67], v[212:215], v[196:199], v[64:67]
	s_setprio 0
	s_bitcmp1_b32 s35, 8
	s_cbranch_scc0 .Leb248_51
	s_setprio 1
.Leb248_51:
	s_mov_b32 m0, s46
	ds_read_b128 v[168:171], v152 offset:49152
	ds_read_b128 v[172:175], v152 offset:50176
	ds_read_b128 v[176:179], v152 offset:51200
	ds_read_b128 v[180:183], v152 offset:52224
	ds_read_b128 v[184:187], v152 offset:53248
	ds_read_b128 v[188:191], v152 offset:54272
	ds_read_b128 v[192:195], v152 offset:55296
	ds_read_b128 v[196:199], v152 offset:56320
	global_load_lds_dwordx4 v128, s[82:83]
	s_mov_b32 m0, s47
	s_nop 0
	global_load_lds_dwordx4 v132, s[82:83]
	s_barrier
	s_waitcnt lgkmcnt(0)
	s_waitcnt lgkmcnt(0)
	v_mfma_f32_16x16x32_bf16 v[60:63], v[144:147], v[168:171], v[60:63]
	v_mfma_f32_16x16x32_bf16 v[56:59], v[160:163], v[168:171], v[56:59]
	v_mfma_f32_16x16x32_bf16 v[44:47], v[144:147], v[176:179], v[44:47]
	v_mfma_f32_16x16x32_bf16 v[40:43], v[160:163], v[176:179], v[40:43]
	v_mfma_f32_16x16x32_bf16 v[28:31], v[144:147], v[184:187], v[28:31]
	v_mfma_f32_16x16x32_bf16 v[24:27], v[160:163], v[184:187], v[24:27]
	v_mfma_f32_16x16x32_bf16 v[12:15], v[144:147], v[192:195], v[12:15]
	v_mfma_f32_16x16x32_bf16 v[8:11], v[160:163], v[192:195], v[8:11]
	v_mfma_f32_16x16x32_bf16 v[60:63], v[156:159], v[172:175], v[60:63]
	v_mfma_f32_16x16x32_bf16 v[56:59], v[164:167], v[172:175], v[56:59]
	v_mfma_f32_16x16x32_bf16 v[44:47], v[156:159], v[180:183], v[44:47]
	v_mfma_f32_16x16x32_bf16 v[40:43], v[164:167], v[180:183], v[40:43]
	v_mfma_f32_16x16x32_bf16 v[28:31], v[156:159], v[188:191], v[28:31]
	v_mfma_f32_16x16x32_bf16 v[24:27], v[164:167], v[188:191], v[24:27]
	v_mfma_f32_16x16x32_bf16 v[12:15], v[156:159], v[196:199], v[12:15]
	s_barrier
	s_setprio 3
	v_mfma_f32_16x16x32_bf16 v[8:11], v[164:167], v[196:199], v[8:11]
	s_setprio 0
	s_bitcmp1_b32 s35, 8
	s_cbranch_scc0 .Leb248_50
	s_setprio 1
.Leb248_50:
	s_add_u32 s20, s28, 0xb0080
	s_addc_u32 s21, s29, 0
	s_add_i32 s28, s30, s40
	s_mov_b32 m0, s28
	s_nop 0
	global_load_lds_dwordx4 v130, s[20:21]
	s_add_i32 m0, s28, 0x2000
	s_nop 0
	global_load_lds_dwordx4 v134, s[20:21]
	s_waitcnt vmcnt(8)
	s_barrier
	v_mfma_f32_16x16x32_bf16 v[52:55], v[200:203], v[168:171], v[52:55]
	v_mfma_f32_16x16x32_bf16 v[48:51], v[208:211], v[168:171], v[48:51]
	v_mfma_f32_16x16x32_bf16 v[36:39], v[200:203], v[176:179], v[36:39]
	v_mfma_f32_16x16x32_bf16 v[32:35], v[208:211], v[176:179], v[32:35]
	v_mfma_f32_16x16x32_bf16 v[20:23], v[200:203], v[184:187], v[20:23]
	v_mfma_f32_16x16x32_bf16 v[16:19], v[208:211], v[184:187], v[16:19]
	v_mfma_f32_16x16x32_bf16 v[4:7], v[200:203], v[192:195], v[4:7]
	v_mfma_f32_16x16x32_bf16 v[0:3], v[208:211], v[192:195], v[0:3]
	v_mfma_f32_16x16x32_bf16 v[52:55], v[204:207], v[172:175], v[52:55]
	v_mfma_f32_16x16x32_bf16 v[48:51], v[212:215], v[172:175], v[48:51]
	v_mfma_f32_16x16x32_bf16 v[36:39], v[204:207], v[180:183], v[36:39]
	v_mfma_f32_16x16x32_bf16 v[32:35], v[212:215], v[180:183], v[32:35]
	v_mfma_f32_16x16x32_bf16 v[20:23], v[204:207], v[188:191], v[20:23]
	v_mfma_f32_16x16x32_bf16 v[16:19], v[212:215], v[188:191], v[16:19]
	v_mfma_f32_16x16x32_bf16 v[4:7], v[204:207], v[196:199], v[4:7]
	s_barrier
	s_setprio 3
	v_mfma_f32_16x16x32_bf16 v[0:3], v[212:215], v[196:199], v[0:3]
	s_setprio 0
	s_bitcmp1_b32 s35, 8
	s_cbranch_scc0 .Leb248_49
	s_setprio 1
.Leb248_49:
	s_add_i32 s59, s59, 2
	s_add_u32 s57, s57, 0x100
	s_addc_u32 s58, s58, 0
	s_cmp_gt_u32 s59, 41
	s_mov_b64 s[20:21], s[26:27]
	s_cbranch_scc0 .LBB0_248
	s_nop 7
	s_nop 7
	s_setprio 0
	v_lshl_add_u32 v146, s56, 8, v148
	v_ashrrev_i32_e32 v147, 31, v146
	v_lshl_or_b32 v144, s12, 8, v150
	v_lshlrev_b64 v[156:157], 11, v[146:147]
	v_ashrrev_i32_e32 v145, 31, v144
	v_lshl_add_u64 v[156:157], s[14:15], 0, v[156:157]
	v_lshl_add_u64 v[166:167], v[144:145], 1, v[156:157]
	global_load_dwordx4 v[158:161], v[166:167], off
	global_load_dwordx4 v[162:165], v[166:167], off offset:256
	s_mov_b64 s[84:85], 0x8000
	s_mov_b64 s[86:87], 0x28000
	v_lshl_add_u64 v[232:233], v[166:167], 0, s[84:85]
	global_load_dwordx4 v[176:179], v[232:233], off
	global_load_dwordx4 v[180:183], v[232:233], off offset:256
	v_lshl_add_u64 v[232:233], v[232:233], 0, s[84:85]
	global_load_dwordx4 v[184:187], v[232:233], off
	global_load_dwordx4 v[188:191], v[232:233], off offset:256
	v_lshl_add_u64 v[232:233], v[232:233], 0, s[84:85]
	global_load_dwordx4 v[192:195], v[232:233], off
	global_load_dwordx4 v[196:199], v[232:233], off offset:256
	v_lshl_add_u64 v[232:233], v[232:233], 0, s[86:87]
	global_load_dwordx4 v[200:203], v[232:233], off
	global_load_dwordx4 v[204:207], v[232:233], off offset:256
	v_lshl_add_u64 v[232:233], v[232:233], 0, s[84:85]
	global_load_dwordx4 v[208:211], v[232:233], off
	global_load_dwordx4 v[212:215], v[232:233], off offset:256
	v_lshl_add_u64 v[232:233], v[232:233], 0, s[84:85]
	global_load_dwordx4 v[216:219], v[232:233], off
	global_load_dwordx4 v[220:223], v[232:233], off offset:256
	v_lshl_add_u64 v[232:233], v[232:233], 0, s[84:85]
	global_load_dwordx4 v[224:227], v[232:233], off
	global_load_dwordx4 v[228:231], v[232:233], off offset:256
	s_cmpk_gt_u32 s35, 0xff
	s_cbranch_scc1 .Lg248_nox
	s_barrier
	s_setprio 1

.Lg359_noy:
	ds_read_b128 v[128:131], v181
	ds_read_b128 v[132:135], v181 offset:1024
	ds_read_b128 v[136:139], v181 offset:2048
	ds_read_b128 v[166:169], v181 offset:3072
	s_add_u32 s38, s8, 0xfffc0080
	s_addc_u32 s39, s9, -1
	s_cmp_eq_u32 s75, 12
	s_cselect_b32 s41, s21, s39
	s_cselect_b32 s40, s71, s38
	s_cselect_b32 s39, s19, s74
	s_cselect_b32 s38, s72, s73
	s_add_i32 m0, s37, 0xc000
	ds_read_b128 v[170:173], v182
	ds_read_b128 v[174:177], v182 offset:1024
	ds_read_b128 v[192:195], v182 offset:2048
	ds_read_b128 v[196:199], v182 offset:3072
	ds_read_b128 v[200:203], v182 offset:4096
	ds_read_b128 v[204:207], v182 offset:5120
	ds_read_b128 v[208:211], v182 offset:6144
	ds_read_b128 v[212:215], v182 offset:7168
	global_load_lds_dwordx4 v158, s[8:9]
	s_add_i32 m0, s37, 0xe000
	s_nop 0
	global_load_lds_dwordx4 v160, s[8:9]
	s_waitcnt lgkmcnt(8)
	s_barrier
	s_waitcnt lgkmcnt(0)
	s_waitcnt lgkmcnt(0)
	v_mfma_f32_16x16x32_bf16 v[124:127], v[128:131], v[170:173], 0
	v_mfma_f32_16x16x32_bf16 v[116:119], v[136:139], v[170:173], 0
	v_mfma_f32_16x16x32_bf16 v[108:111], v[128:131], v[192:195], 0
	v_mfma_f32_16x16x32_bf16 v[100:103], v[136:139], v[192:195], 0
	v_mfma_f32_16x16x32_bf16 v[92:95], v[128:131], v[200:203], 0
	v_mfma_f32_16x16x32_bf16 v[84:87], v[136:139], v[200:203], 0
	v_mfma_f32_16x16x32_bf16 v[76:79], v[128:131], v[208:211], 0
	v_mfma_f32_16x16x32_bf16 v[68:71], v[136:139], v[208:211], 0
	v_mfma_f32_16x16x32_bf16 v[124:127], v[132:135], v[174:177], v[124:127]
	v_mfma_f32_16x16x32_bf16 v[116:119], v[166:169], v[174:177], v[116:119]
	v_mfma_f32_16x16x32_bf16 v[108:111], v[132:135], v[196:199], v[108:111]
	v_mfma_f32_16x16x32_bf16 v[100:103], v[166:169], v[196:199], v[100:103]
	v_mfma_f32_16x16x32_bf16 v[92:95], v[132:135], v[204:207], v[92:95]
	v_mfma_f32_16x16x32_bf16 v[84:87], v[166:169], v[204:207], v[84:87]
	v_mfma_f32_16x16x32_bf16 v[76:79], v[132:135], v[212:215], v[76:79]
	s_barrier
	s_setprio 3
	v_mfma_f32_16x16x32_bf16 v[68:71], v[166:169], v[212:215], v[68:71]
	s_setprio 0
	s_bitcmp1_b32 s45, 8
	s_cbranch_scc0 .Leb359_48
	s_setprio 1
.Leb359_48:
	s_add_i32 s76, s63, s46
	s_add_u32 s80, s38, 0x80
	s_addc_u32 s81, s39, 0
	s_mov_b32 m0, s76
	ds_read_b128 v[216:219], v183
	ds_read_b128 v[220:223], v183 offset:1024
	ds_read_b128 v[224:227], v183 offset:2048
	ds_read_b128 v[228:231], v183 offset:3072
	global_load_lds_dwordx4 v144, s[38:39]
	s_add_i32 m0, s76, 0x2000
	s_nop 0
	global_load_lds_dwordx4 v148, s[38:39]
	s_waitcnt vmcnt(10)
	s_barrier
	s_waitcnt lgkmcnt(0)
	s_waitcnt lgkmcnt(0)
	v_mfma_f32_16x16x32_bf16 v[120:123], v[216:219], v[170:173], 0
	v_mfma_f32_16x16x32_bf16 v[112:115], v[224:227], v[170:173], 0
	v_mfma_f32_16x16x32_bf16 v[104:107], v[216:219], v[192:195], 0
	v_mfma_f32_16x16x32_bf16 v[96:99], v[224:227], v[192:195], 0
	v_mfma_f32_16x16x32_bf16 v[88:91], v[216:219], v[200:203], 0
	v_mfma_f32_16x16x32_bf16 v[80:83], v[224:227], v[200:203], 0
	v_mfma_f32_16x16x32_bf16 v[72:75], v[216:219], v[208:211], 0
	v_mfma_f32_16x16x32_bf16 v[64:67], v[224:227], v[208:211], 0
	v_mfma_f32_16x16x32_bf16 v[120:123], v[220:223], v[174:177], v[120:123]
	v_mfma_f32_16x16x32_bf16 v[112:115], v[228:231], v[174:177], v[112:115]
	v_mfma_f32_16x16x32_bf16 v[104:107], v[220:223], v[196:199], v[104:107]
	v_mfma_f32_16x16x32_bf16 v[96:99], v[228:231], v[196:199], v[96:99]
	v_mfma_f32_16x16x32_bf16 v[88:91], v[220:223], v[204:207], v[88:91]
	v_mfma_f32_16x16x32_bf16 v[80:83], v[228:231], v[204:207], v[80:83]
	v_mfma_f32_16x16x32_bf16 v[72:75], v[220:223], v[212:215], v[72:75]
	s_barrier
	s_setprio 3
	v_mfma_f32_16x16x32_bf16 v[64:67], v[228:231], v[212:215], v[64:67]
	s_setprio 0
	s_bitcmp1_b32 s45, 8
	s_cbranch_scc0 .Leb359_47
	s_setprio 1
.Leb359_47:
	s_mov_b32 m0, s37
	s_add_u32 s82, s40, 0x80
	s_addc_u32 s83, s41, 0
	ds_read_b128 v[170:173], v182 offset:16384
	ds_read_b128 v[174:177], v182 offset:17408
	ds_read_b128 v[192:195], v182 offset:18432
	ds_read_b128 v[196:199], v182 offset:19456
	ds_read_b128 v[200:203], v182 offset:20480
	ds_read_b128 v[204:207], v182 offset:21504
	ds_read_b128 v[208:211], v182 offset:22528
	ds_read_b128 v[212:215], v182 offset:23552
	global_load_lds_dwordx4 v142, s[40:41]
	s_mov_b32 m0, s51
	s_nop 0
	global_load_lds_dwordx4 v146, s[40:41]
	s_barrier
	s_waitcnt lgkmcnt(0)
	s_waitcnt lgkmcnt(0)
	v_mfma_f32_16x16x32_bf16 v[60:63], v[128:131], v[170:173], 0
	v_mfma_f32_16x16x32_bf16 v[52:55], v[136:139], v[170:173], 0
	v_mfma_f32_16x16x32_bf16 v[44:47], v[128:131], v[192:195], 0
	v_mfma_f32_16x16x32_bf16 v[36:39], v[136:139], v[192:195], 0
	v_mfma_f32_16x16x32_bf16 v[28:31], v[128:131], v[200:203], 0
	v_mfma_f32_16x16x32_bf16 v[20:23], v[136:139], v[200:203], 0
	v_mfma_f32_16x16x32_bf16 v[12:15], v[128:131], v[208:211], 0
	v_mfma_f32_16x16x32_bf16 v[4:7], v[136:139], v[208:211], 0
	v_mfma_f32_16x16x32_bf16 v[60:63], v[132:135], v[174:177], v[60:63]
	v_mfma_f32_16x16x32_bf16 v[52:55], v[166:169], v[174:177], v[52:55]
	v_mfma_f32_16x16x32_bf16 v[44:47], v[132:135], v[196:199], v[44:47]
	v_mfma_f32_16x16x32_bf16 v[36:39], v[166:169], v[196:199], v[36:39]
	v_mfma_f32_16x16x32_bf16 v[28:31], v[132:135], v[204:207], v[28:31]
	v_mfma_f32_16x16x32_bf16 v[20:23], v[166:169], v[204:207], v[20:23]
	v_mfma_f32_16x16x32_bf16 v[12:15], v[132:135], v[212:215], v[12:15]
	s_barrier
	s_setprio 3
	v_mfma_f32_16x16x32_bf16 v[4:7], v[166:169], v[212:215], v[4:7]
	s_setprio 0
	s_bitcmp1_b32 s45, 8
	s_cbranch_scc0 .Leb359_46
	s_setprio 1
.Leb359_46:
	s_add_u32 s76, s38, 0x40000
	s_addc_u32 s77, s39, 0
	s_add_i32 s78, s64, s46
	s_mov_b32 m0, s78
	s_nop 0
	global_load_lds_dwordx4 v144, s[76:77]
	s_add_i32 m0, s78, 0x2000
	s_nop 0
	global_load_lds_dwordx4 v148, s[76:77]
	s_waitcnt vmcnt(8)
	s_barrier
	v_mfma_f32_16x16x32_bf16 v[56:59], v[216:219], v[170:173], 0
	v_mfma_f32_16x16x32_bf16 v[48:51], v[224:227], v[170:173], 0
	v_mfma_f32_16x16x32_bf16 v[40:43], v[216:219], v[192:195], 0
	v_mfma_f32_16x16x32_bf16 v[32:35], v[224:227], v[192:195], 0
	v_mfma_f32_16x16x32_bf16 v[24:27], v[216:219], v[200:203], 0
	v_mfma_f32_16x16x32_bf16 v[16:19], v[224:227], v[200:203], 0
	v_mfma_f32_16x16x32_bf16 v[8:11], v[216:219], v[208:211], 0
	v_mfma_f32_16x16x32_bf16 v[0:3], v[224:227], v[208:211], 0
	v_mfma_f32_16x16x32_bf16 v[56:59], v[220:223], v[174:177], v[56:59]
	v_mfma_f32_16x16x32_bf16 v[48:51], v[228:231], v[174:177], v[48:51]
	v_mfma_f32_16x16x32_bf16 v[40:43], v[220:223], v[196:199], v[40:43]
	v_mfma_f32_16x16x32_bf16 v[32:35], v[228:231], v[196:199], v[32:35]
	v_mfma_f32_16x16x32_bf16 v[24:27], v[220:223], v[204:207], v[24:27]
	v_mfma_f32_16x16x32_bf16 v[16:19], v[228:231], v[204:207], v[16:19]
	v_mfma_f32_16x16x32_bf16 v[8:11], v[220:223], v[212:215], v[8:11]
	s_barrier
	s_setprio 3
	v_mfma_f32_16x16x32_bf16 v[0:3], v[228:231], v[212:215], v[0:3]
	s_setprio 0
	s_bitcmp1_b32 s45, 8
	s_cbranch_scc0 .Leb359_45
	s_setprio 1
.Leb359_45:
	s_add_i32 s76, 0, 0x18000
	v_add_u32_e32 v150, s76, v179
	s_branch .Lg359_mid
.LBB0_359:
	ds_read_b128 v[128:131], v181
	ds_read_b128 v[132:135], v181 offset:1024
	ds_read_b128 v[136:139], v181 offset:2048
	ds_read_b128 v[166:169], v181 offset:3072
	s_add_u32 s38, s8, 0xfffc0080
	s_addc_u32 s39, s9, -1
	s_cmp_eq_u32 s75, 12
	s_cselect_b32 s41, s21, s39
	s_cselect_b32 s40, s71, s38
	s_cselect_b32 s39, s19, s74
	s_cselect_b32 s38, s72, s73
	s_add_i32 m0, s37, 0xc000
	ds_read_b128 v[170:173], v182
	ds_read_b128 v[174:177], v182 offset:1024
	ds_read_b128 v[192:195], v182 offset:2048
	ds_read_b128 v[196:199], v182 offset:3072
	ds_read_b128 v[200:203], v182 offset:4096
	ds_read_b128 v[204:207], v182 offset:5120
	ds_read_b128 v[208:211], v182 offset:6144
	ds_read_b128 v[212:215], v182 offset:7168
	global_load_lds_dwordx4 v158, s[8:9]
	s_add_i32 m0, s37, 0xe000
	s_nop 0
	global_load_lds_dwordx4 v160, s[8:9]
	s_waitcnt lgkmcnt(8)
	s_barrier
	s_waitcnt lgkmcnt(0)
	s_waitcnt lgkmcnt(0)
	v_mfma_f32_16x16x32_bf16 v[124:127], v[128:131], v[170:173], v[124:127]
	v_mfma_f32_16x16x32_bf16 v[116:119], v[136:139], v[170:173], v[116:119]
	v_mfma_f32_16x16x32_bf16 v[108:111], v[128:131], v[192:195], v[108:111]
	v_mfma_f32_16x16x32_bf16 v[100:103], v[136:139], v[192:195], v[100:103]
	v_mfma_f32_16x16x32_bf16 v[92:95], v[128:131], v[200:203], v[92:95]
	v_mfma_f32_16x16x32_bf16 v[84:87], v[136:139], v[200:203], v[84:87]
	v_mfma_f32_16x16x32_bf16 v[76:79], v[128:131], v[208:211], v[76:79]
	v_mfma_f32_16x16x32_bf16 v[68:71], v[136:139], v[208:211], v[68:71]
	v_mfma_f32_16x16x32_bf16 v[124:127], v[132:135], v[174:177], v[124:127]
	v_mfma_f32_16x16x32_bf16 v[116:119], v[166:169], v[174:177], v[116:119]
	v_mfma_f32_16x16x32_bf16 v[108:111], v[132:135], v[196:199], v[108:111]
	v_mfma_f32_16x16x32_bf16 v[100:103], v[166:169], v[196:199], v[100:103]
	v_mfma_f32_16x16x32_bf16 v[92:95], v[132:135], v[204:207], v[92:95]
	v_mfma_f32_16x16x32_bf16 v[84:87], v[166:169], v[204:207], v[84:87]
	v_mfma_f32_16x16x32_bf16 v[76:79], v[132:135], v[212:215], v[76:79]
	s_barrier
	s_setprio 3
	v_mfma_f32_16x16x32_bf16 v[68:71], v[166:169], v[212:215], v[68:71]
	s_setprio 0
	s_bitcmp1_b32 s45, 8
	s_cbranch_scc0 .Leb359_44
	s_setprio 1
.Leb359_44:
	s_add_i32 s76, s63, s46
	s_add_u32 s80, s38, 0x80
	s_addc_u32 s81, s39, 0
	s_mov_b32 m0, s76
	ds_read_b128 v[216:219], v183
	ds_read_b128 v[220:223], v183 offset:1024
	ds_read_b128 v[224:227], v183 offset:2048
	ds_read_b128 v[228:231], v183 offset:3072
	global_load_lds_dwordx4 v144, s[38:39]
	s_add_i32 m0, s76, 0x2000
	s_nop 0
	global_load_lds_dwordx4 v148, s[38:39]
	s_waitcnt vmcnt(10)
	s_barrier
	s_waitcnt lgkmcnt(0)
	s_waitcnt lgkmcnt(0)
	v_mfma_f32_16x16x32_bf16 v[120:123], v[216:219], v[170:173], v[120:123]
	v_mfma_f32_16x16x32_bf16 v[112:115], v[224:227], v[170:173], v[112:115]
	v_mfma_f32_16x16x32_bf16 v[104:107], v[216:219], v[192:195], v[104:107]
	v_mfma_f32_16x16x32_bf16 v[96:99], v[224:227], v[192:195], v[96:99]
	v_mfma_f32_16x16x32_bf16 v[88:91], v[216:219], v[200:203], v[88:91]
	v_mfma_f32_16x16x32_bf16 v[80:83], v[224:227], v[200:203], v[80:83]
	v_mfma_f32_16x16x32_bf16 v[72:75], v[216:219], v[208:211], v[72:75]
	v_mfma_f32_16x16x32_bf16 v[64:67], v[224:227], v[208:211], v[64:67]
	v_mfma_f32_16x16x32_bf16 v[120:123], v[220:223], v[174:177], v[120:123]
	v_mfma_f32_16x16x32_bf16 v[112:115], v[228:231], v[174:177], v[112:115]
	v_mfma_f32_16x16x32_bf16 v[104:107], v[220:223], v[196:199], v[104:107]
	v_mfma_f32_16x16x32_bf16 v[96:99], v[228:231], v[196:199], v[96:99]
	v_mfma_f32_16x16x32_bf16 v[88:91], v[220:223], v[204:207], v[88:91]
	v_mfma_f32_16x16x32_bf16 v[80:83], v[228:231], v[204:207], v[80:83]
	v_mfma_f32_16x16x32_bf16 v[72:75], v[220:223], v[212:215], v[72:75]
	s_barrier
	s_setprio 3
	v_mfma_f32_16x16x32_bf16 v[64:67], v[228:231], v[212:215], v[64:67]
	s_setprio 0
	s_bitcmp1_b32 s45, 8
	s_cbranch_scc0 .Leb359_43
	s_setprio 1
.Leb359_43:
	s_mov_b32 m0, s37
	s_add_u32 s82, s40, 0x80
	s_addc_u32 s83, s41, 0
	ds_read_b128 v[170:173], v182 offset:16384
	ds_read_b128 v[174:177], v182 offset:17408
	ds_read_b128 v[192:195], v182 offset:18432
	ds_read_b128 v[196:199], v182 offset:19456
	ds_read_b128 v[200:203], v182 offset:20480
	ds_read_b128 v[204:207], v182 offset:21504
	ds_read_b128 v[208:211], v182 offset:22528
	ds_read_b128 v[212:215], v182 offset:23552
	global_load_lds_dwordx4 v142, s[40:41]
	s_mov_b32 m0, s51
	s_nop 0
	global_load_lds_dwordx4 v146, s[40:41]
	s_barrier
	s_waitcnt lgkmcnt(0)
	s_waitcnt lgkmcnt(0)
	v_mfma_f32_16x16x32_bf16 v[60:63], v[128:131], v[170:173], v[60:63]
	v_mfma_f32_16x16x32_bf16 v[52:55], v[136:139], v[170:173], v[52:55]
	v_mfma_f32_16x16x32_bf16 v[44:47], v[128:131], v[192:195], v[44:47]
	v_mfma_f32_16x16x32_bf16 v[36:39], v[136:139], v[192:195], v[36:39]
	v_mfma_f32_16x16x32_bf16 v[28:31], v[128:131], v[200:203], v[28:31]
	v_mfma_f32_16x16x32_bf16 v[20:23], v[136:139], v[200:203], v[20:23]
	v_mfma_f32_16x16x32_bf16 v[12:15], v[128:131], v[208:211], v[12:15]
	v_mfma_f32_16x16x32_bf16 v[4:7], v[136:139], v[208:211], v[4:7]
	v_mfma_f32_16x16x32_bf16 v[60:63], v[132:135], v[174:177], v[60:63]
	v_mfma_f32_16x16x32_bf16 v[52:55], v[166:169], v[174:177], v[52:55]
	v_mfma_f32_16x16x32_bf16 v[44:47], v[132:135], v[196:199], v[44:47]
	v_mfma_f32_16x16x32_bf16 v[36:39], v[166:169], v[196:199], v[36:39]
	v_mfma_f32_16x16x32_bf16 v[28:31], v[132:135], v[204:207], v[28:31]
	v_mfma_f32_16x16x32_bf16 v[20:23], v[166:169], v[204:207], v[20:23]
	v_mfma_f32_16x16x32_bf16 v[12:15], v[132:135], v[212:215], v[12:15]
	s_barrier
	s_setprio 3
	v_mfma_f32_16x16x32_bf16 v[4:7], v[166:169], v[212:215], v[4:7]
	s_setprio 0
	s_bitcmp1_b32 s45, 8
	s_cbranch_scc0 .Leb359_42
	s_setprio 1
.Leb359_42:
	s_add_u32 s76, s38, 0x40000
	s_addc_u32 s77, s39, 0
	s_add_i32 s78, s64, s46
	s_mov_b32 m0, s78
	s_nop 0
	global_load_lds_dwordx4 v144, s[76:77]
	s_add_i32 m0, s78, 0x2000
	s_nop 0
	global_load_lds_dwordx4 v148, s[76:77]
	s_waitcnt vmcnt(8)
	s_barrier
	v_mfma_f32_16x16x32_bf16 v[56:59], v[216:219], v[170:173], v[56:59]
	v_mfma_f32_16x16x32_bf16 v[48:51], v[224:227], v[170:173], v[48:51]
	v_mfma_f32_16x16x32_bf16 v[40:43], v[216:219], v[192:195], v[40:43]
	v_mfma_f32_16x16x32_bf16 v[32:35], v[224:227], v[192:195], v[32:35]
	v_mfma_f32_16x16x32_bf16 v[24:27], v[216:219], v[200:203], v[24:27]
	v_mfma_f32_16x16x32_bf16 v[16:19], v[224:227], v[200:203], v[16:19]
	v_mfma_f32_16x16x32_bf16 v[8:11], v[216:219], v[208:211], v[8:11]
	v_mfma_f32_16x16x32_bf16 v[0:3], v[224:227], v[208:211], v[0:3]
	v_mfma_f32_16x16x32_bf16 v[56:59], v[220:223], v[174:177], v[56:59]
	v_mfma_f32_16x16x32_bf16 v[48:51], v[228:231], v[174:177], v[48:51]
	v_mfma_f32_16x16x32_bf16 v[40:43], v[220:223], v[196:199], v[40:43]
	v_mfma_f32_16x16x32_bf16 v[32:35], v[228:231], v[196:199], v[32:35]
	v_mfma_f32_16x16x32_bf16 v[24:27], v[220:223], v[204:207], v[24:27]
	v_mfma_f32_16x16x32_bf16 v[16:19], v[228:231], v[204:207], v[16:19]
	v_mfma_f32_16x16x32_bf16 v[8:11], v[220:223], v[212:215], v[8:11]
	s_barrier
	s_setprio 3
	v_mfma_f32_16x16x32_bf16 v[0:3], v[228:231], v[212:215], v[0:3]
	s_setprio 0
	s_bitcmp1_b32 s45, 8
	s_cbranch_scc0 .Leb359_41
	s_setprio 1
.Leb359_41:
	s_add_i32 s76, 0, 0x18000
	v_add_u32_e32 v150, s76, v179
.Lg359_mid:
	ds_read_b128 v[128:131], v150
	ds_read_b128 v[132:135], v150 offset:1024
	ds_read_b128 v[136:139], v150 offset:2048
	ds_read_b128 v[166:169], v150 offset:3072
	s_add_u32 s40, s40, 0x40000
	s_addc_u32 s41, s41, 0
	s_mov_b32 m0, s52
	ds_read_b128 v[170:173], v182 offset:32768
	ds_read_b128 v[174:177], v182 offset:33792
	ds_read_b128 v[192:195], v182 offset:34816
	ds_read_b128 v[196:199], v182 offset:35840
	ds_read_b128 v[200:203], v182 offset:36864
	ds_read_b128 v[204:207], v182 offset:37888
	ds_read_b128 v[208:211], v182 offset:38912
	ds_read_b128 v[212:215], v182 offset:39936
	global_load_lds_dwordx4 v142, s[40:41]
	s_mov_b32 m0, s53
	s_nop 0
	global_load_lds_dwordx4 v146, s[40:41]
	s_waitcnt lgkmcnt(8)
	s_barrier
	s_waitcnt lgkmcnt(0)
	s_waitcnt lgkmcnt(0)
	v_mfma_f32_16x16x32_bf16 v[124:127], v[128:131], v[170:173], v[124:127]
	v_mfma_f32_16x16x32_bf16 v[116:119], v[136:139], v[170:173], v[116:119]
	v_mfma_f32_16x16x32_bf16 v[108:111], v[128:131], v[192:195], v[108:111]
	v_mfma_f32_16x16x32_bf16 v[100:103], v[136:139], v[192:195], v[100:103]
	v_mfma_f32_16x16x32_bf16 v[92:95], v[128:131], v[200:203], v[92:95]
	v_mfma_f32_16x16x32_bf16 v[84:87], v[136:139], v[200:203], v[84:87]
	v_mfma_f32_16x16x32_bf16 v[76:79], v[128:131], v[208:211], v[76:79]
	v_mfma_f32_16x16x32_bf16 v[68:71], v[136:139], v[208:211], v[68:71]
	v_mfma_f32_16x16x32_bf16 v[124:127], v[132:135], v[174:177], v[124:127]
	v_mfma_f32_16x16x32_bf16 v[116:119], v[166:169], v[174:177], v[116:119]
	v_mfma_f32_16x16x32_bf16 v[108:111], v[132:135], v[196:199], v[108:111]
	v_mfma_f32_16x16x32_bf16 v[100:103], v[166:169], v[196:199], v[100:103]
	v_mfma_f32_16x16x32_bf16 v[92:95], v[132:135], v[204:207], v[92:95]
	v_mfma_f32_16x16x32_bf16 v[84:87], v[166:169], v[204:207], v[84:87]
	v_mfma_f32_16x16x32_bf16 v[76:79], v[132:135], v[212:215], v[76:79]
	s_barrier
	s_setprio 3
	v_mfma_f32_16x16x32_bf16 v[68:71], v[166:169], v[212:215], v[68:71]
	s_setprio 0
	s_bitcmp1_b32 s45, 8
	s_cbranch_scc0 .Leb359_40
	s_setprio 1
.Leb359_40:
	s_add_i32 s40, 0, 0x1c000
	s_add_i32 s41, s76, s46
	v_add_u32_e32 v150, s40, v179
	s_mov_b32 m0, s41
	ds_read_b128 v[216:219], v150
	ds_read_b128 v[220:223], v150 offset:1024
	ds_read_b128 v[224:227], v150 offset:2048
	ds_read_b128 v[228:231], v150 offset:3072
	global_load_lds_dwordx4 v144, s[80:81]
	s_add_i32 m0, s41, 0x2000
	s_nop 0
	global_load_lds_dwordx4 v148, s[80:81]
	s_waitcnt vmcnt(10)
	s_barrier
	s_waitcnt lgkmcnt(0)
	s_waitcnt lgkmcnt(0)
	v_mfma_f32_16x16x32_bf16 v[120:123], v[216:219], v[170:173], v[120:123]
	v_mfma_f32_16x16x32_bf16 v[112:115], v[224:227], v[170:173], v[112:115]
	v_mfma_f32_16x16x32_bf16 v[104:107], v[216:219], v[192:195], v[104:107]
	v_mfma_f32_16x16x32_bf16 v[96:99], v[224:227], v[192:195], v[96:99]
	v_mfma_f32_16x16x32_bf16 v[88:91], v[216:219], v[200:203], v[88:91]
	v_mfma_f32_16x16x32_bf16 v[80:83], v[224:227], v[200:203], v[80:83]
	v_mfma_f32_16x16x32_bf16 v[72:75], v[216:219], v[208:211], v[72:75]
	v_mfma_f32_16x16x32_bf16 v[64:67], v[224:227], v[208:211], v[64:67]
	v_mfma_f32_16x16x32_bf16 v[120:123], v[220:223], v[174:177], v[120:123]
	v_mfma_f32_16x16x32_bf16 v[112:115], v[228:231], v[174:177], v[112:115]
	v_mfma_f32_16x16x32_bf16 v[104:107], v[220:223], v[196:199], v[104:107]
	v_mfma_f32_16x16x32_bf16 v[96:99], v[228:231], v[196:199], v[96:99]
	v_mfma_f32_16x16x32_bf16 v[88:91], v[220:223], v[204:207], v[88:91]
	v_mfma_f32_16x16x32_bf16 v[80:83], v[228:231], v[204:207], v[80:83]
	v_mfma_f32_16x16x32_bf16 v[72:75], v[220:223], v[212:215], v[72:75]
	s_barrier
	s_setprio 3
	v_mfma_f32_16x16x32_bf16 v[64:67], v[228:231], v[212:215], v[64:67]
	s_setprio 0
	s_bitcmp1_b32 s45, 8
	s_cbranch_scc0 .Leb359_39
	s_setprio 1
.Leb359_39:
	s_mov_b32 m0, s55
	ds_read_b128 v[170:173], v182 offset:49152
	ds_read_b128 v[174:177], v182 offset:50176
	ds_read_b128 v[192:195], v182 offset:51200
	ds_read_b128 v[196:199], v182 offset:52224
	ds_read_b128 v[200:203], v182 offset:53248
	ds_read_b128 v[204:207], v182 offset:54272
	ds_read_b128 v[208:211], v182 offset:55296
	ds_read_b128 v[212:215], v182 offset:56320
	global_load_lds_dwordx4 v142, s[82:83]
	s_mov_b32 m0, s56
	s_nop 0
	global_load_lds_dwordx4 v146, s[82:83]
	s_barrier
	s_waitcnt lgkmcnt(0)
	s_waitcnt lgkmcnt(0)
	v_mfma_f32_16x16x32_bf16 v[60:63], v[128:131], v[170:173], v[60:63]
	v_mfma_f32_16x16x32_bf16 v[52:55], v[136:139], v[170:173], v[52:55]
	v_mfma_f32_16x16x32_bf16 v[44:47], v[128:131], v[192:195], v[44:47]
	v_mfma_f32_16x16x32_bf16 v[36:39], v[136:139], v[192:195], v[36:39]
	v_mfma_f32_16x16x32_bf16 v[28:31], v[128:131], v[200:203], v[28:31]
	v_mfma_f32_16x16x32_bf16 v[20:23], v[136:139], v[200:203], v[20:23]
	v_mfma_f32_16x16x32_bf16 v[12:15], v[128:131], v[208:211], v[12:15]
	v_mfma_f32_16x16x32_bf16 v[4:7], v[136:139], v[208:211], v[4:7]
	v_mfma_f32_16x16x32_bf16 v[60:63], v[132:135], v[174:177], v[60:63]
	v_mfma_f32_16x16x32_bf16 v[52:55], v[166:169], v[174:177], v[52:55]
	v_mfma_f32_16x16x32_bf16 v[44:47], v[132:135], v[196:199], v[44:47]
	v_mfma_f32_16x16x32_bf16 v[36:39], v[166:169], v[196:199], v[36:39]
	v_mfma_f32_16x16x32_bf16 v[28:31], v[132:135], v[204:207], v[28:31]
	v_mfma_f32_16x16x32_bf16 v[20:23], v[166:169], v[204:207], v[20:23]
	v_mfma_f32_16x16x32_bf16 v[12:15], v[132:135], v[212:215], v[12:15]
	s_barrier
	s_setprio 3
	v_mfma_f32_16x16x32_bf16 v[4:7], v[166:169], v[212:215], v[4:7]
	s_setprio 0
	s_bitcmp1_b32 s45, 8
	s_cbranch_scc0 .Leb359_38
	s_setprio 1
.Leb359_38:
	s_add_u32 s38, s38, 0x40080
	s_addc_u32 s39, s39, 0
	s_add_i32 s40, s40, s46
	s_mov_b32 m0, s40
	s_nop 0
	global_load_lds_dwordx4 v144, s[38:39]
	s_add_i32 m0, s40, 0x2000
	s_nop 0
	global_load_lds_dwordx4 v148, s[38:39]
	s_waitcnt vmcnt(8)
	s_barrier
	v_mfma_f32_16x16x32_bf16 v[56:59], v[216:219], v[170:173], v[56:59]
	v_mfma_f32_16x16x32_bf16 v[48:51], v[224:227], v[170:173], v[48:51]
	v_mfma_f32_16x16x32_bf16 v[40:43], v[216:219], v[192:195], v[40:43]
	v_mfma_f32_16x16x32_bf16 v[32:35], v[224:227], v[192:195], v[32:35]
	v_mfma_f32_16x16x32_bf16 v[24:27], v[216:219], v[200:203], v[24:27]
	v_mfma_f32_16x16x32_bf16 v[16:19], v[224:227], v[200:203], v[16:19]
	v_mfma_f32_16x16x32_bf16 v[8:11], v[216:219], v[208:211], v[8:11]
	v_mfma_f32_16x16x32_bf16 v[0:3], v[224:227], v[208:211], v[0:3]
	v_mfma_f32_16x16x32_bf16 v[56:59], v[220:223], v[174:177], v[56:59]
	v_mfma_f32_16x16x32_bf16 v[48:51], v[228:231], v[174:177], v[48:51]
	v_mfma_f32_16x16x32_bf16 v[40:43], v[220:223], v[196:199], v[40:43]
	v_mfma_f32_16x16x32_bf16 v[32:35], v[228:231], v[196:199], v[32:35]
	v_mfma_f32_16x16x32_bf16 v[24:27], v[220:223], v[204:207], v[24:27]
	v_mfma_f32_16x16x32_bf16 v[16:19], v[228:231], v[204:207], v[16:19]
	v_mfma_f32_16x16x32_bf16 v[8:11], v[220:223], v[212:215], v[8:11]
	s_barrier
	s_setprio 3
	v_mfma_f32_16x16x32_bf16 v[0:3], v[228:231], v[212:215], v[0:3]
	s_setprio 0
	s_bitcmp1_b32 s45, 8
	s_cbranch_scc0 .Leb359_37
	s_setprio 1
.Leb359_37:
	s_add_i32 s75, s75, 2
	s_add_u32 s8, s8, 0x100
	s_addc_u32 s9, s9, 0
	s_add_u32 s73, s73, 0x100
	s_addc_u32 s74, s74, 0
	s_cmp_gt_u32 s75, 13
	s_cbranch_scc0 .LBB0_359
	s_nop 7
	s_nop 7
	s_setprio 0
	s_cmpk_gt_u32 s45, 0xff
	s_cbranch_scc1 .Lg359_nox
	s_barrier
	s_setprio 1

.Lg786_noy:
	ds_read_b128 v[144:147], v151
	ds_read_b128 v[156:159], v151 offset:1024
	ds_read_b128 v[160:163], v151 offset:2048
	ds_read_b128 v[164:167], v151 offset:3072
	s_add_u32 s30, s28, 0xfffc0080
	s_addc_u32 s31, s29, -1
	s_cmp_eq_u32 s61, 12
	s_cselect_b32 s35, s19, s31
	s_cselect_b32 s34, s57, s30
	s_cselect_b32 s31, s17, s60
	s_cselect_b32 s30, s58, s59
	s_add_i32 m0, s45, 0xc000
	ds_read_b128 v[168:171], v152
	ds_read_b128 v[172:175], v152 offset:1024
	ds_read_b128 v[176:179], v152 offset:2048
	ds_read_b128 v[180:183], v152 offset:3072
	ds_read_b128 v[184:187], v152 offset:4096
	ds_read_b128 v[188:191], v152 offset:5120
	ds_read_b128 v[192:195], v152 offset:6144
	ds_read_b128 v[196:199], v152 offset:7168
	global_load_lds_dwordx4 v136, s[28:29]
	s_add_i32 m0, s45, 0xe000
	s_nop 0
	global_load_lds_dwordx4 v138, s[28:29]
	s_waitcnt lgkmcnt(8)
	s_barrier
	s_waitcnt lgkmcnt(0)
	s_waitcnt lgkmcnt(0)
	v_mfma_f32_16x16x32_bf16 v[124:127], v[144:147], v[168:171], 0
	v_mfma_f32_16x16x32_bf16 v[120:123], v[160:163], v[168:171], 0
	v_mfma_f32_16x16x32_bf16 v[108:111], v[144:147], v[176:179], 0
	v_mfma_f32_16x16x32_bf16 v[104:107], v[160:163], v[176:179], 0
	v_mfma_f32_16x16x32_bf16 v[92:95], v[144:147], v[184:187], 0
	v_mfma_f32_16x16x32_bf16 v[88:91], v[160:163], v[184:187], 0
	v_mfma_f32_16x16x32_bf16 v[76:79], v[144:147], v[192:195], 0
	v_mfma_f32_16x16x32_bf16 v[72:75], v[160:163], v[192:195], 0
	v_mfma_f32_16x16x32_bf16 v[124:127], v[156:159], v[172:175], v[124:127]
	v_mfma_f32_16x16x32_bf16 v[120:123], v[164:167], v[172:175], v[120:123]
	v_mfma_f32_16x16x32_bf16 v[108:111], v[156:159], v[180:183], v[108:111]
	v_mfma_f32_16x16x32_bf16 v[104:107], v[164:167], v[180:183], v[104:107]
	v_mfma_f32_16x16x32_bf16 v[92:95], v[156:159], v[188:191], v[92:95]
	v_mfma_f32_16x16x32_bf16 v[88:91], v[164:167], v[188:191], v[88:91]
	v_mfma_f32_16x16x32_bf16 v[76:79], v[156:159], v[196:199], v[76:79]
	s_barrier
	s_setprio 3
	v_mfma_f32_16x16x32_bf16 v[72:75], v[164:167], v[196:199], v[72:75]
	s_setprio 0
	s_bitcmp1_b32 s37, 8
	s_cbranch_scc0 .Leb786_36
	s_setprio 1
.Leb786_36:
	s_add_i32 s62, s53, s42
	s_add_u32 s80, s30, 0x80
	s_addc_u32 s81, s31, 0
	s_mov_b32 m0, s62
	ds_read_b128 v[200:203], v153
	ds_read_b128 v[204:207], v153 offset:1024
	ds_read_b128 v[208:211], v153 offset:2048
	ds_read_b128 v[212:215], v153 offset:3072
	global_load_lds_dwordx4 v132, s[30:31]
	s_add_i32 m0, s62, 0x2000
	s_nop 0
	global_load_lds_dwordx4 v128, s[30:31]
	s_waitcnt vmcnt(10)
	s_barrier
	s_waitcnt lgkmcnt(0)
	s_waitcnt lgkmcnt(0)
	v_mfma_f32_16x16x32_bf16 v[116:119], v[200:203], v[168:171], 0
	v_mfma_f32_16x16x32_bf16 v[112:115], v[208:211], v[168:171], 0
	v_mfma_f32_16x16x32_bf16 v[100:103], v[200:203], v[176:179], 0
	v_mfma_f32_16x16x32_bf16 v[96:99], v[208:211], v[176:179], 0
	v_mfma_f32_16x16x32_bf16 v[84:87], v[200:203], v[184:187], 0
	v_mfma_f32_16x16x32_bf16 v[80:83], v[208:211], v[184:187], 0
	v_mfma_f32_16x16x32_bf16 v[68:71], v[200:203], v[192:195], 0
	v_mfma_f32_16x16x32_bf16 v[64:67], v[208:211], v[192:195], 0
	v_mfma_f32_16x16x32_bf16 v[116:119], v[204:207], v[172:175], v[116:119]
	v_mfma_f32_16x16x32_bf16 v[112:115], v[212:215], v[172:175], v[112:115]
	v_mfma_f32_16x16x32_bf16 v[100:103], v[204:207], v[180:183], v[100:103]
	v_mfma_f32_16x16x32_bf16 v[96:99], v[212:215], v[180:183], v[96:99]
	v_mfma_f32_16x16x32_bf16 v[84:87], v[204:207], v[188:191], v[84:87]
	v_mfma_f32_16x16x32_bf16 v[80:83], v[212:215], v[188:191], v[80:83]
	v_mfma_f32_16x16x32_bf16 v[68:71], v[204:207], v[196:199], v[68:71]
	s_barrier
	s_setprio 3
	v_mfma_f32_16x16x32_bf16 v[64:67], v[212:215], v[196:199], v[64:67]
	s_setprio 0
	s_bitcmp1_b32 s37, 8
	s_cbranch_scc0 .Leb786_35
	s_setprio 1
.Leb786_35:
	s_mov_b32 m0, s45
	s_add_u32 s82, s34, 0x80
	s_addc_u32 s83, s35, 0
	ds_read_b128 v[168:171], v152 offset:16384
	ds_read_b128 v[172:175], v152 offset:17408
	ds_read_b128 v[176:179], v152 offset:18432
	ds_read_b128 v[180:183], v152 offset:19456
	ds_read_b128 v[184:187], v152 offset:20480
	ds_read_b128 v[188:191], v152 offset:21504
	ds_read_b128 v[192:195], v152 offset:22528
	ds_read_b128 v[196:199], v152 offset:23552
	global_load_lds_dwordx4 v134, s[34:35]
	s_mov_b32 m0, s46
	s_nop 0
	global_load_lds_dwordx4 v130, s[34:35]
	s_barrier
	s_waitcnt lgkmcnt(0)
	s_waitcnt lgkmcnt(0)
	v_mfma_f32_16x16x32_bf16 v[60:63], v[144:147], v[168:171], 0
	v_mfma_f32_16x16x32_bf16 v[56:59], v[160:163], v[168:171], 0
	v_mfma_f32_16x16x32_bf16 v[44:47], v[144:147], v[176:179], 0
	v_mfma_f32_16x16x32_bf16 v[40:43], v[160:163], v[176:179], 0
	v_mfma_f32_16x16x32_bf16 v[28:31], v[144:147], v[184:187], 0
	v_mfma_f32_16x16x32_bf16 v[24:27], v[160:163], v[184:187], 0
	v_mfma_f32_16x16x32_bf16 v[12:15], v[144:147], v[192:195], 0
	v_mfma_f32_16x16x32_bf16 v[8:11], v[160:163], v[192:195], 0
	v_mfma_f32_16x16x32_bf16 v[60:63], v[156:159], v[172:175], v[60:63]
	v_mfma_f32_16x16x32_bf16 v[56:59], v[164:167], v[172:175], v[56:59]
	v_mfma_f32_16x16x32_bf16 v[44:47], v[156:159], v[180:183], v[44:47]
	v_mfma_f32_16x16x32_bf16 v[40:43], v[164:167], v[180:183], v[40:43]
	v_mfma_f32_16x16x32_bf16 v[28:31], v[156:159], v[188:191], v[28:31]
	v_mfma_f32_16x16x32_bf16 v[24:27], v[164:167], v[188:191], v[24:27]
	v_mfma_f32_16x16x32_bf16 v[12:15], v[156:159], v[196:199], v[12:15]
	s_barrier
	s_setprio 3
	v_mfma_f32_16x16x32_bf16 v[8:11], v[164:167], v[196:199], v[8:11]
	s_setprio 0
	s_bitcmp1_b32 s37, 8
	s_cbranch_scc0 .Leb786_34
	s_setprio 1
.Leb786_34:
	s_add_u32 s62, s30, 0x40000
	s_addc_u32 s63, s31, 0
	s_add_i32 s64, s54, s42
	s_mov_b32 m0, s64
	s_nop 0
	global_load_lds_dwordx4 v132, s[62:63]
	s_add_i32 m0, s64, 0x2000
	s_nop 0
	global_load_lds_dwordx4 v128, s[62:63]
	s_waitcnt vmcnt(8)
	s_barrier
	v_mfma_f32_16x16x32_bf16 v[52:55], v[200:203], v[168:171], 0
	v_mfma_f32_16x16x32_bf16 v[48:51], v[208:211], v[168:171], 0
	v_mfma_f32_16x16x32_bf16 v[36:39], v[200:203], v[176:179], 0
	v_mfma_f32_16x16x32_bf16 v[32:35], v[208:211], v[176:179], 0
	v_mfma_f32_16x16x32_bf16 v[20:23], v[200:203], v[184:187], 0
	v_mfma_f32_16x16x32_bf16 v[16:19], v[208:211], v[184:187], 0
	v_mfma_f32_16x16x32_bf16 v[4:7], v[200:203], v[192:195], 0
	v_mfma_f32_16x16x32_bf16 v[0:3], v[208:211], v[192:195], 0
	v_mfma_f32_16x16x32_bf16 v[52:55], v[204:207], v[172:175], v[52:55]
	v_mfma_f32_16x16x32_bf16 v[48:51], v[212:215], v[172:175], v[48:51]
	v_mfma_f32_16x16x32_bf16 v[36:39], v[204:207], v[180:183], v[36:39]
	v_mfma_f32_16x16x32_bf16 v[32:35], v[212:215], v[180:183], v[32:35]
	v_mfma_f32_16x16x32_bf16 v[20:23], v[204:207], v[188:191], v[20:23]
	v_mfma_f32_16x16x32_bf16 v[16:19], v[212:215], v[188:191], v[16:19]
	v_mfma_f32_16x16x32_bf16 v[4:7], v[204:207], v[196:199], v[4:7]
	s_barrier
	s_setprio 3
	v_mfma_f32_16x16x32_bf16 v[0:3], v[212:215], v[196:199], v[0:3]
	s_setprio 0
	s_bitcmp1_b32 s37, 8
	s_cbranch_scc0 .Leb786_33
	s_setprio 1
.Leb786_33:
	s_add_i32 s62, 0, 0x18000
	v_add_u32_e32 v155, s62, v149
	s_branch .Lg786_mid
.LBB0_786:
	ds_read_b128 v[144:147], v151
	ds_read_b128 v[156:159], v151 offset:1024
	ds_read_b128 v[160:163], v151 offset:2048
	ds_read_b128 v[164:167], v151 offset:3072
	s_add_u32 s30, s28, 0xfffc0080
	s_addc_u32 s31, s29, -1
	s_cmp_eq_u32 s61, 12
	s_cselect_b32 s35, s19, s31
	s_cselect_b32 s34, s57, s30
	s_cselect_b32 s31, s17, s60
	s_cselect_b32 s30, s58, s59
	s_add_i32 m0, s45, 0xc000
	ds_read_b128 v[168:171], v152
	ds_read_b128 v[172:175], v152 offset:1024
	ds_read_b128 v[176:179], v152 offset:2048
	ds_read_b128 v[180:183], v152 offset:3072
	ds_read_b128 v[184:187], v152 offset:4096
	ds_read_b128 v[188:191], v152 offset:5120
	ds_read_b128 v[192:195], v152 offset:6144
	ds_read_b128 v[196:199], v152 offset:7168
	global_load_lds_dwordx4 v136, s[28:29]
	s_add_i32 m0, s45, 0xe000
	s_nop 0
	global_load_lds_dwordx4 v138, s[28:29]
	s_waitcnt lgkmcnt(8)
	s_barrier
	s_waitcnt lgkmcnt(0)
	s_waitcnt lgkmcnt(0)
	v_mfma_f32_16x16x32_bf16 v[124:127], v[144:147], v[168:171], v[124:127]
	v_mfma_f32_16x16x32_bf16 v[120:123], v[160:163], v[168:171], v[120:123]
	v_mfma_f32_16x16x32_bf16 v[108:111], v[144:147], v[176:179], v[108:111]
	v_mfma_f32_16x16x32_bf16 v[104:107], v[160:163], v[176:179], v[104:107]
	v_mfma_f32_16x16x32_bf16 v[92:95], v[144:147], v[184:187], v[92:95]
	v_mfma_f32_16x16x32_bf16 v[88:91], v[160:163], v[184:187], v[88:91]
	v_mfma_f32_16x16x32_bf16 v[76:79], v[144:147], v[192:195], v[76:79]
	v_mfma_f32_16x16x32_bf16 v[72:75], v[160:163], v[192:195], v[72:75]
	v_mfma_f32_16x16x32_bf16 v[124:127], v[156:159], v[172:175], v[124:127]
	v_mfma_f32_16x16x32_bf16 v[120:123], v[164:167], v[172:175], v[120:123]
	v_mfma_f32_16x16x32_bf16 v[108:111], v[156:159], v[180:183], v[108:111]
	v_mfma_f32_16x16x32_bf16 v[104:107], v[164:167], v[180:183], v[104:107]
	v_mfma_f32_16x16x32_bf16 v[92:95], v[156:159], v[188:191], v[92:95]
	v_mfma_f32_16x16x32_bf16 v[88:91], v[164:167], v[188:191], v[88:91]
	v_mfma_f32_16x16x32_bf16 v[76:79], v[156:159], v[196:199], v[76:79]
	s_barrier
	s_setprio 3
	v_mfma_f32_16x16x32_bf16 v[72:75], v[164:167], v[196:199], v[72:75]
	s_setprio 0
	s_bitcmp1_b32 s37, 8
	s_cbranch_scc0 .Leb786_32
	s_setprio 1
.Leb786_32:
	s_add_i32 s62, s53, s42
	s_add_u32 s80, s30, 0x80
	s_addc_u32 s81, s31, 0
	s_mov_b32 m0, s62
	ds_read_b128 v[200:203], v153
	ds_read_b128 v[204:207], v153 offset:1024
	ds_read_b128 v[208:211], v153 offset:2048
	ds_read_b128 v[212:215], v153 offset:3072
	global_load_lds_dwordx4 v132, s[30:31]
	s_add_i32 m0, s62, 0x2000
	s_nop 0
	global_load_lds_dwordx4 v128, s[30:31]
	s_waitcnt vmcnt(10)
	s_barrier
	s_waitcnt lgkmcnt(0)
	s_waitcnt lgkmcnt(0)
	v_mfma_f32_16x16x32_bf16 v[116:119], v[200:203], v[168:171], v[116:119]
	v_mfma_f32_16x16x32_bf16 v[112:115], v[208:211], v[168:171], v[112:115]
	v_mfma_f32_16x16x32_bf16 v[100:103], v[200:203], v[176:179], v[100:103]
	v_mfma_f32_16x16x32_bf16 v[96:99], v[208:211], v[176:179], v[96:99]
	v_mfma_f32_16x16x32_bf16 v[84:87], v[200:203], v[184:187], v[84:87]
	v_mfma_f32_16x16x32_bf16 v[80:83], v[208:211], v[184:187], v[80:83]
	v_mfma_f32_16x16x32_bf16 v[68:71], v[200:203], v[192:195], v[68:71]
	v_mfma_f32_16x16x32_bf16 v[64:67], v[208:211], v[192:195], v[64:67]
	v_mfma_f32_16x16x32_bf16 v[116:119], v[204:207], v[172:175], v[116:119]
	v_mfma_f32_16x16x32_bf16 v[112:115], v[212:215], v[172:175], v[112:115]
	v_mfma_f32_16x16x32_bf16 v[100:103], v[204:207], v[180:183], v[100:103]
	v_mfma_f32_16x16x32_bf16 v[96:99], v[212:215], v[180:183], v[96:99]
	v_mfma_f32_16x16x32_bf16 v[84:87], v[204:207], v[188:191], v[84:87]
	v_mfma_f32_16x16x32_bf16 v[80:83], v[212:215], v[188:191], v[80:83]
	v_mfma_f32_16x16x32_bf16 v[68:71], v[204:207], v[196:199], v[68:71]
	s_barrier
	s_setprio 3
	v_mfma_f32_16x16x32_bf16 v[64:67], v[212:215], v[196:199], v[64:67]
	s_setprio 0
	s_bitcmp1_b32 s37, 8
	s_cbranch_scc0 .Leb786_31
	s_setprio 1
.Leb786_31:
	s_mov_b32 m0, s45
	s_add_u32 s82, s34, 0x80
	s_addc_u32 s83, s35, 0
	ds_read_b128 v[168:171], v152 offset:16384
	ds_read_b128 v[172:175], v152 offset:17408
	ds_read_b128 v[176:179], v152 offset:18432
	ds_read_b128 v[180:183], v152 offset:19456
	ds_read_b128 v[184:187], v152 offset:20480
	ds_read_b128 v[188:191], v152 offset:21504
	ds_read_b128 v[192:195], v152 offset:22528
	ds_read_b128 v[196:199], v152 offset:23552
	global_load_lds_dwordx4 v134, s[34:35]
	s_mov_b32 m0, s46
	s_nop 0
	global_load_lds_dwordx4 v130, s[34:35]
	s_barrier
	s_waitcnt lgkmcnt(0)
	s_waitcnt lgkmcnt(0)
	v_mfma_f32_16x16x32_bf16 v[60:63], v[144:147], v[168:171], v[60:63]
	v_mfma_f32_16x16x32_bf16 v[56:59], v[160:163], v[168:171], v[56:59]
	v_mfma_f32_16x16x32_bf16 v[44:47], v[144:147], v[176:179], v[44:47]
	v_mfma_f32_16x16x32_bf16 v[40:43], v[160:163], v[176:179], v[40:43]
	v_mfma_f32_16x16x32_bf16 v[28:31], v[144:147], v[184:187], v[28:31]
	v_mfma_f32_16x16x32_bf16 v[24:27], v[160:163], v[184:187], v[24:27]
	v_mfma_f32_16x16x32_bf16 v[12:15], v[144:147], v[192:195], v[12:15]
	v_mfma_f32_16x16x32_bf16 v[8:11], v[160:163], v[192:195], v[8:11]
	v_mfma_f32_16x16x32_bf16 v[60:63], v[156:159], v[172:175], v[60:63]
	v_mfma_f32_16x16x32_bf16 v[56:59], v[164:167], v[172:175], v[56:59]
	v_mfma_f32_16x16x32_bf16 v[44:47], v[156:159], v[180:183], v[44:47]
	v_mfma_f32_16x16x32_bf16 v[40:43], v[164:167], v[180:183], v[40:43]
	v_mfma_f32_16x16x32_bf16 v[28:31], v[156:159], v[188:191], v[28:31]
	v_mfma_f32_16x16x32_bf16 v[24:27], v[164:167], v[188:191], v[24:27]
	v_mfma_f32_16x16x32_bf16 v[12:15], v[156:159], v[196:199], v[12:15]
	s_barrier
	s_setprio 3
	v_mfma_f32_16x16x32_bf16 v[8:11], v[164:167], v[196:199], v[8:11]
	s_setprio 0
	s_bitcmp1_b32 s37, 8
	s_cbranch_scc0 .Leb786_30
	s_setprio 1
.Leb786_30:
	s_add_u32 s62, s30, 0x40000
	s_addc_u32 s63, s31, 0
	s_add_i32 s64, s54, s42
	s_mov_b32 m0, s64
	s_nop 0
	global_load_lds_dwordx4 v132, s[62:63]
	s_add_i32 m0, s64, 0x2000
	s_nop 0
	global_load_lds_dwordx4 v128, s[62:63]
	s_waitcnt vmcnt(8)
	s_barrier
	v_mfma_f32_16x16x32_bf16 v[52:55], v[200:203], v[168:171], v[52:55]
	v_mfma_f32_16x16x32_bf16 v[48:51], v[208:211], v[168:171], v[48:51]
	v_mfma_f32_16x16x32_bf16 v[36:39], v[200:203], v[176:179], v[36:39]
	v_mfma_f32_16x16x32_bf16 v[32:35], v[208:211], v[176:179], v[32:35]
	v_mfma_f32_16x16x32_bf16 v[20:23], v[200:203], v[184:187], v[20:23]
	v_mfma_f32_16x16x32_bf16 v[16:19], v[208:211], v[184:187], v[16:19]
	v_mfma_f32_16x16x32_bf16 v[4:7], v[200:203], v[192:195], v[4:7]
	v_mfma_f32_16x16x32_bf16 v[0:3], v[208:211], v[192:195], v[0:3]
	v_mfma_f32_16x16x32_bf16 v[52:55], v[204:207], v[172:175], v[52:55]
	v_mfma_f32_16x16x32_bf16 v[48:51], v[212:215], v[172:175], v[48:51]
	v_mfma_f32_16x16x32_bf16 v[36:39], v[204:207], v[180:183], v[36:39]
	v_mfma_f32_16x16x32_bf16 v[32:35], v[212:215], v[180:183], v[32:35]
	v_mfma_f32_16x16x32_bf16 v[20:23], v[204:207], v[188:191], v[20:23]
	v_mfma_f32_16x16x32_bf16 v[16:19], v[212:215], v[188:191], v[16:19]
	v_mfma_f32_16x16x32_bf16 v[4:7], v[204:207], v[196:199], v[4:7]
	s_barrier
	s_setprio 3
	v_mfma_f32_16x16x32_bf16 v[0:3], v[212:215], v[196:199], v[0:3]
	s_setprio 0
	s_bitcmp1_b32 s37, 8
	s_cbranch_scc0 .Leb786_29
	s_setprio 1
.Leb786_29:
	s_add_i32 s62, 0, 0x18000
	v_add_u32_e32 v155, s62, v149
.Lg786_mid:
	ds_read_b128 v[144:147], v155
	ds_read_b128 v[156:159], v155 offset:1024
	ds_read_b128 v[160:163], v155 offset:2048
	ds_read_b128 v[164:167], v155 offset:3072
	s_add_u32 s34, s34, 0x40000
	s_addc_u32 s35, s35, 0
	s_mov_b32 m0, s47
	ds_read_b128 v[168:171], v152 offset:32768
	ds_read_b128 v[172:175], v152 offset:33792
	ds_read_b128 v[176:179], v152 offset:34816
	ds_read_b128 v[180:183], v152 offset:35840
	ds_read_b128 v[184:187], v152 offset:36864
	ds_read_b128 v[188:191], v152 offset:37888
	ds_read_b128 v[192:195], v152 offset:38912
	ds_read_b128 v[196:199], v152 offset:39936
	global_load_lds_dwordx4 v134, s[34:35]
	s_mov_b32 m0, s48
	s_nop 0
	global_load_lds_dwordx4 v130, s[34:35]
	s_waitcnt lgkmcnt(8)
	s_barrier
	s_waitcnt lgkmcnt(0)
	s_waitcnt lgkmcnt(0)
	v_mfma_f32_16x16x32_bf16 v[124:127], v[144:147], v[168:171], v[124:127]
	v_mfma_f32_16x16x32_bf16 v[120:123], v[160:163], v[168:171], v[120:123]
	v_mfma_f32_16x16x32_bf16 v[108:111], v[144:147], v[176:179], v[108:111]
	v_mfma_f32_16x16x32_bf16 v[104:107], v[160:163], v[176:179], v[104:107]
	v_mfma_f32_16x16x32_bf16 v[92:95], v[144:147], v[184:187], v[92:95]
	v_mfma_f32_16x16x32_bf16 v[88:91], v[160:163], v[184:187], v[88:91]
	v_mfma_f32_16x16x32_bf16 v[76:79], v[144:147], v[192:195], v[76:79]
	v_mfma_f32_16x16x32_bf16 v[72:75], v[160:163], v[192:195], v[72:75]
	v_mfma_f32_16x16x32_bf16 v[124:127], v[156:159], v[172:175], v[124:127]
	v_mfma_f32_16x16x32_bf16 v[120:123], v[164:167], v[172:175], v[120:123]
	v_mfma_f32_16x16x32_bf16 v[108:111], v[156:159], v[180:183], v[108:111]
	v_mfma_f32_16x16x32_bf16 v[104:107], v[164:167], v[180:183], v[104:107]
	v_mfma_f32_16x16x32_bf16 v[92:95], v[156:159], v[188:191], v[92:95]
	v_mfma_f32_16x16x32_bf16 v[88:91], v[164:167], v[188:191], v[88:91]
	v_mfma_f32_16x16x32_bf16 v[76:79], v[156:159], v[196:199], v[76:79]
	s_barrier
	s_setprio 3
	v_mfma_f32_16x16x32_bf16 v[72:75], v[164:167], v[196:199], v[72:75]
	s_setprio 0
	s_bitcmp1_b32 s37, 8
	s_cbranch_scc0 .Leb786_28
	s_setprio 1
.Leb786_28:
	s_add_i32 s34, 0, 0x1c000
	s_add_i32 s35, s62, s42
	v_add_u32_e32 v155, s34, v149
	s_mov_b32 m0, s35
	ds_read_b128 v[200:203], v155
	ds_read_b128 v[204:207], v155 offset:1024
	ds_read_b128 v[208:211], v155 offset:2048
	ds_read_b128 v[212:215], v155 offset:3072
	global_load_lds_dwordx4 v132, s[80:81]
	s_add_i32 m0, s35, 0x2000
	s_nop 0
	global_load_lds_dwordx4 v128, s[80:81]
	s_waitcnt vmcnt(10)
	s_barrier
	s_waitcnt lgkmcnt(0)
	s_waitcnt lgkmcnt(0)
	v_mfma_f32_16x16x32_bf16 v[116:119], v[200:203], v[168:171], v[116:119]
	v_mfma_f32_16x16x32_bf16 v[112:115], v[208:211], v[168:171], v[112:115]
	v_mfma_f32_16x16x32_bf16 v[100:103], v[200:203], v[176:179], v[100:103]
	v_mfma_f32_16x16x32_bf16 v[96:99], v[208:211], v[176:179], v[96:99]
	v_mfma_f32_16x16x32_bf16 v[84:87], v[200:203], v[184:187], v[84:87]
	v_mfma_f32_16x16x32_bf16 v[80:83], v[208:211], v[184:187], v[80:83]
	v_mfma_f32_16x16x32_bf16 v[68:71], v[200:203], v[192:195], v[68:71]
	v_mfma_f32_16x16x32_bf16 v[64:67], v[208:211], v[192:195], v[64:67]
	v_mfma_f32_16x16x32_bf16 v[116:119], v[204:207], v[172:175], v[116:119]
	v_mfma_f32_16x16x32_bf16 v[112:115], v[212:215], v[172:175], v[112:115]
	v_mfma_f32_16x16x32_bf16 v[100:103], v[204:207], v[180:183], v[100:103]
	v_mfma_f32_16x16x32_bf16 v[96:99], v[212:215], v[180:183], v[96:99]
	v_mfma_f32_16x16x32_bf16 v[84:87], v[204:207], v[188:191], v[84:87]
	v_mfma_f32_16x16x32_bf16 v[80:83], v[212:215], v[188:191], v[80:83]
	v_mfma_f32_16x16x32_bf16 v[68:71], v[204:207], v[196:199], v[68:71]
	s_barrier
	s_setprio 3
	v_mfma_f32_16x16x32_bf16 v[64:67], v[212:215], v[196:199], v[64:67]
	s_setprio 0
	s_bitcmp1_b32 s37, 8
	s_cbranch_scc0 .Leb786_27
	s_setprio 1
.Leb786_27:
	s_mov_b32 m0, s50
	ds_read_b128 v[168:171], v152 offset:49152
	ds_read_b128 v[172:175], v152 offset:50176
	ds_read_b128 v[176:179], v152 offset:51200
	ds_read_b128 v[180:183], v152 offset:52224
	ds_read_b128 v[184:187], v152 offset:53248
	ds_read_b128 v[188:191], v152 offset:54272
	ds_read_b128 v[192:195], v152 offset:55296
	ds_read_b128 v[196:199], v152 offset:56320
	global_load_lds_dwordx4 v134, s[82:83]
	s_mov_b32 m0, s51
	s_nop 0
	global_load_lds_dwordx4 v130, s[82:83]
	s_barrier
	s_waitcnt lgkmcnt(0)
	s_waitcnt lgkmcnt(0)
	v_mfma_f32_16x16x32_bf16 v[60:63], v[144:147], v[168:171], v[60:63]
	v_mfma_f32_16x16x32_bf16 v[56:59], v[160:163], v[168:171], v[56:59]
	v_mfma_f32_16x16x32_bf16 v[44:47], v[144:147], v[176:179], v[44:47]
	v_mfma_f32_16x16x32_bf16 v[40:43], v[160:163], v[176:179], v[40:43]
	v_mfma_f32_16x16x32_bf16 v[28:31], v[144:147], v[184:187], v[28:31]
	v_mfma_f32_16x16x32_bf16 v[24:27], v[160:163], v[184:187], v[24:27]
	v_mfma_f32_16x16x32_bf16 v[12:15], v[144:147], v[192:195], v[12:15]
	v_mfma_f32_16x16x32_bf16 v[8:11], v[160:163], v[192:195], v[8:11]
	v_mfma_f32_16x16x32_bf16 v[60:63], v[156:159], v[172:175], v[60:63]
	v_mfma_f32_16x16x32_bf16 v[56:59], v[164:167], v[172:175], v[56:59]
	v_mfma_f32_16x16x32_bf16 v[44:47], v[156:159], v[180:183], v[44:47]
	v_mfma_f32_16x16x32_bf16 v[40:43], v[164:167], v[180:183], v[40:43]
	v_mfma_f32_16x16x32_bf16 v[28:31], v[156:159], v[188:191], v[28:31]
	v_mfma_f32_16x16x32_bf16 v[24:27], v[164:167], v[188:191], v[24:27]
	v_mfma_f32_16x16x32_bf16 v[12:15], v[156:159], v[196:199], v[12:15]
	s_barrier
	s_setprio 3
	v_mfma_f32_16x16x32_bf16 v[8:11], v[164:167], v[196:199], v[8:11]
	s_setprio 0
	s_bitcmp1_b32 s37, 8
	s_cbranch_scc0 .Leb786_26
	s_setprio 1
.Leb786_26:
	s_add_u32 s30, s30, 0x40080
	s_addc_u32 s31, s31, 0
	s_add_i32 s34, s34, s42
	s_mov_b32 m0, s34
	s_nop 0
	global_load_lds_dwordx4 v132, s[30:31]
	s_add_i32 m0, s34, 0x2000
	s_nop 0
	global_load_lds_dwordx4 v128, s[30:31]
	s_waitcnt vmcnt(8)
	s_barrier
	v_mfma_f32_16x16x32_bf16 v[52:55], v[200:203], v[168:171], v[52:55]
	v_mfma_f32_16x16x32_bf16 v[48:51], v[208:211], v[168:171], v[48:51]
	v_mfma_f32_16x16x32_bf16 v[36:39], v[200:203], v[176:179], v[36:39]
	v_mfma_f32_16x16x32_bf16 v[32:35], v[208:211], v[176:179], v[32:35]
	v_mfma_f32_16x16x32_bf16 v[20:23], v[200:203], v[184:187], v[20:23]
	v_mfma_f32_16x16x32_bf16 v[16:19], v[208:211], v[184:187], v[16:19]
	v_mfma_f32_16x16x32_bf16 v[4:7], v[200:203], v[192:195], v[4:7]
	v_mfma_f32_16x16x32_bf16 v[0:3], v[208:211], v[192:195], v[0:3]
	v_mfma_f32_16x16x32_bf16 v[52:55], v[204:207], v[172:175], v[52:55]
	v_mfma_f32_16x16x32_bf16 v[48:51], v[212:215], v[172:175], v[48:51]
	v_mfma_f32_16x16x32_bf16 v[36:39], v[204:207], v[180:183], v[36:39]
	v_mfma_f32_16x16x32_bf16 v[32:35], v[212:215], v[180:183], v[32:35]
	v_mfma_f32_16x16x32_bf16 v[20:23], v[204:207], v[188:191], v[20:23]
	v_mfma_f32_16x16x32_bf16 v[16:19], v[212:215], v[188:191], v[16:19]
	v_mfma_f32_16x16x32_bf16 v[4:7], v[204:207], v[196:199], v[4:7]
	s_barrier
	s_setprio 3
	v_mfma_f32_16x16x32_bf16 v[0:3], v[212:215], v[196:199], v[0:3]
	s_setprio 0
	s_bitcmp1_b32 s37, 8
	s_cbranch_scc0 .Leb786_25
	s_setprio 1
.Leb786_25:
	s_add_i32 s61, s61, 2
	s_add_u32 s28, s28, 0x100
	s_addc_u32 s29, s29, 0
	s_add_u32 s59, s59, 0x100
	s_addc_u32 s60, s60, 0
	s_cmp_gt_u32 s61, 13
	s_cbranch_scc0 .LBB0_786
	s_nop 7
	s_nop 7
	s_setprio 0
	v_lshl_add_u32 v146, s8, 8, v148
	v_ashrrev_i32_e32 v147, 31, v146
	v_lshl_or_b32 v144, s56, 8, v150
	v_lshlrev_b64 v[156:157], 11, v[146:147]
	v_ashrrev_i32_e32 v145, 31, v144
	v_lshl_add_u64 v[156:157], s[10:11], 0, v[156:157]
	v_lshl_add_u64 v[166:167], v[144:145], 1, v[156:157]
	global_load_dwordx4 v[158:161], v[166:167], off
	global_load_dwordx4 v[162:165], v[166:167], off offset:256
	s_mov_b64 s[84:85], 0x8000
	s_mov_b64 s[86:87], 0x28000
	v_lshl_add_u64 v[232:233], v[166:167], 0, s[84:85]
	global_load_dwordx4 v[176:179], v[232:233], off
	global_load_dwordx4 v[180:183], v[232:233], off offset:256
	v_lshl_add_u64 v[232:233], v[232:233], 0, s[84:85]
	global_load_dwordx4 v[184:187], v[232:233], off
	global_load_dwordx4 v[188:191], v[232:233], off offset:256
	v_lshl_add_u64 v[232:233], v[232:233], 0, s[84:85]
	global_load_dwordx4 v[192:195], v[232:233], off
	global_load_dwordx4 v[196:199], v[232:233], off offset:256
	v_lshl_add_u64 v[232:233], v[232:233], 0, s[86:87]
	global_load_dwordx4 v[200:203], v[232:233], off
	global_load_dwordx4 v[204:207], v[232:233], off offset:256
	v_lshl_add_u64 v[232:233], v[232:233], 0, s[84:85]
	global_load_dwordx4 v[208:211], v[232:233], off
	global_load_dwordx4 v[212:215], v[232:233], off offset:256
	v_lshl_add_u64 v[232:233], v[232:233], 0, s[84:85]
	global_load_dwordx4 v[216:219], v[232:233], off
	global_load_dwordx4 v[220:223], v[232:233], off offset:256
	v_lshl_add_u64 v[232:233], v[232:233], 0, s[84:85]
	global_load_dwordx4 v[224:227], v[232:233], off
	global_load_dwordx4 v[228:231], v[232:233], off offset:256
	s_cmpk_gt_u32 s37, 0xff
	s_cbranch_scc1 .Lg786_nox
	s_barrier
	s_setprio 1

.Lg893_noy:
	ds_read_b128 v[152:155], v148
	ds_read_b128 v[156:159], v148 offset:1024
	ds_read_b128 v[160:163], v148 offset:2048
	ds_read_b128 v[164:167], v148 offset:3072
	s_add_u32 s26, s20, 0xfffc0080
	s_addc_u32 s27, s21, -1
	s_cmp_eq_u32 s57, 12
	s_cselect_b32 s29, s13, s27
	s_cselect_b32 s28, s53, s26
	s_cselect_b32 s27, s11, s56
	s_cselect_b32 s26, s54, s55
	s_add_i32 m0, s19, 0xc000
	ds_read_b128 v[168:171], v149
	ds_read_b128 v[172:175], v149 offset:1024
	ds_read_b128 v[176:179], v149 offset:2048
	ds_read_b128 v[180:183], v149 offset:3072
	ds_read_b128 v[184:187], v149 offset:4096
	ds_read_b128 v[188:191], v149 offset:5120
	ds_read_b128 v[192:195], v149 offset:6144
	ds_read_b128 v[196:199], v149 offset:7168
	global_load_lds_dwordx4 v136, s[20:21]
	s_add_i32 m0, s19, 0xe000
	s_nop 0
	global_load_lds_dwordx4 v138, s[20:21]
	s_waitcnt lgkmcnt(8)
	s_barrier
	s_waitcnt lgkmcnt(0)
	s_waitcnt lgkmcnt(0)
	v_mfma_f32_16x16x32_bf16 v[124:127], v[152:155], v[168:171], 0
	v_mfma_f32_16x16x32_bf16 v[120:123], v[160:163], v[168:171], 0
	v_mfma_f32_16x16x32_bf16 v[108:111], v[152:155], v[176:179], 0
	v_mfma_f32_16x16x32_bf16 v[104:107], v[160:163], v[176:179], 0
	v_mfma_f32_16x16x32_bf16 v[92:95], v[152:155], v[184:187], 0
	v_mfma_f32_16x16x32_bf16 v[88:91], v[160:163], v[184:187], 0
	v_mfma_f32_16x16x32_bf16 v[76:79], v[152:155], v[192:195], 0
	v_mfma_f32_16x16x32_bf16 v[72:75], v[160:163], v[192:195], 0
	v_mfma_f32_16x16x32_bf16 v[124:127], v[156:159], v[172:175], v[124:127]
	v_mfma_f32_16x16x32_bf16 v[120:123], v[164:167], v[172:175], v[120:123]
	v_mfma_f32_16x16x32_bf16 v[108:111], v[156:159], v[180:183], v[108:111]
	v_mfma_f32_16x16x32_bf16 v[104:107], v[164:167], v[180:183], v[104:107]
	v_mfma_f32_16x16x32_bf16 v[92:95], v[156:159], v[188:191], v[92:95]
	v_mfma_f32_16x16x32_bf16 v[88:91], v[164:167], v[188:191], v[88:91]
	v_mfma_f32_16x16x32_bf16 v[76:79], v[156:159], v[196:199], v[76:79]
	s_barrier
	s_setprio 3
	v_mfma_f32_16x16x32_bf16 v[72:75], v[164:167], v[196:199], v[72:75]
	s_setprio 0
	s_bitcmp1_b32 s30, 8
	s_cbranch_scc0 .Leb893_24
	s_setprio 1
.Leb893_24:
	s_add_i32 s58, s47, s31
	s_add_u32 s80, s26, 0x80
	s_addc_u32 s81, s27, 0
	s_mov_b32 m0, s58
	ds_read_b128 v[200:203], v150
	ds_read_b128 v[204:207], v150 offset:1024
	ds_read_b128 v[208:211], v150 offset:2048
	ds_read_b128 v[212:215], v150 offset:3072
	global_load_lds_dwordx4 v132, s[26:27]
	s_add_i32 m0, s58, 0x2000
	s_nop 0
	global_load_lds_dwordx4 v128, s[26:27]
	s_waitcnt vmcnt(10)
	s_barrier
	s_waitcnt lgkmcnt(0)
	s_waitcnt lgkmcnt(0)
	v_mfma_f32_16x16x32_bf16 v[116:119], v[200:203], v[168:171], 0
	v_mfma_f32_16x16x32_bf16 v[112:115], v[208:211], v[168:171], 0
	v_mfma_f32_16x16x32_bf16 v[100:103], v[200:203], v[176:179], 0
	v_mfma_f32_16x16x32_bf16 v[96:99], v[208:211], v[176:179], 0
	v_mfma_f32_16x16x32_bf16 v[84:87], v[200:203], v[184:187], 0
	v_mfma_f32_16x16x32_bf16 v[80:83], v[208:211], v[184:187], 0
	v_mfma_f32_16x16x32_bf16 v[68:71], v[200:203], v[192:195], 0
	v_mfma_f32_16x16x32_bf16 v[64:67], v[208:211], v[192:195], 0
	v_mfma_f32_16x16x32_bf16 v[116:119], v[204:207], v[172:175], v[116:119]
	v_mfma_f32_16x16x32_bf16 v[112:115], v[212:215], v[172:175], v[112:115]
	v_mfma_f32_16x16x32_bf16 v[100:103], v[204:207], v[180:183], v[100:103]
	v_mfma_f32_16x16x32_bf16 v[96:99], v[212:215], v[180:183], v[96:99]
	v_mfma_f32_16x16x32_bf16 v[84:87], v[204:207], v[188:191], v[84:87]
	v_mfma_f32_16x16x32_bf16 v[80:83], v[212:215], v[188:191], v[80:83]
	v_mfma_f32_16x16x32_bf16 v[68:71], v[204:207], v[196:199], v[68:71]
	s_barrier
	s_setprio 3
	v_mfma_f32_16x16x32_bf16 v[64:67], v[212:215], v[196:199], v[64:67]
	s_setprio 0
	s_bitcmp1_b32 s30, 8
	s_cbranch_scc0 .Leb893_23
	s_setprio 1
.Leb893_23:
	s_mov_b32 m0, s19
	s_add_u32 s82, s28, 0x80
	s_addc_u32 s83, s29, 0
	ds_read_b128 v[168:171], v149 offset:16384
	ds_read_b128 v[172:175], v149 offset:17408
	ds_read_b128 v[176:179], v149 offset:18432
	ds_read_b128 v[180:183], v149 offset:19456
	ds_read_b128 v[184:187], v149 offset:20480
	ds_read_b128 v[188:191], v149 offset:21504
	ds_read_b128 v[192:195], v149 offset:22528
	ds_read_b128 v[196:199], v149 offset:23552
	global_load_lds_dwordx4 v134, s[28:29]
	s_mov_b32 m0, s42
	s_nop 0
	global_load_lds_dwordx4 v130, s[28:29]
	s_barrier
	s_waitcnt lgkmcnt(0)
	s_waitcnt lgkmcnt(0)
	v_mfma_f32_16x16x32_bf16 v[60:63], v[152:155], v[168:171], 0
	v_mfma_f32_16x16x32_bf16 v[56:59], v[160:163], v[168:171], 0
	v_mfma_f32_16x16x32_bf16 v[44:47], v[152:155], v[176:179], 0
	v_mfma_f32_16x16x32_bf16 v[40:43], v[160:163], v[176:179], 0
	v_mfma_f32_16x16x32_bf16 v[28:31], v[152:155], v[184:187], 0
	v_mfma_f32_16x16x32_bf16 v[24:27], v[160:163], v[184:187], 0
	v_mfma_f32_16x16x32_bf16 v[12:15], v[152:155], v[192:195], 0
	v_mfma_f32_16x16x32_bf16 v[8:11], v[160:163], v[192:195], 0
	v_mfma_f32_16x16x32_bf16 v[60:63], v[156:159], v[172:175], v[60:63]
	v_mfma_f32_16x16x32_bf16 v[56:59], v[164:167], v[172:175], v[56:59]
	v_mfma_f32_16x16x32_bf16 v[44:47], v[156:159], v[180:183], v[44:47]
	v_mfma_f32_16x16x32_bf16 v[40:43], v[164:167], v[180:183], v[40:43]
	v_mfma_f32_16x16x32_bf16 v[28:31], v[156:159], v[188:191], v[28:31]
	v_mfma_f32_16x16x32_bf16 v[24:27], v[164:167], v[188:191], v[24:27]
	v_mfma_f32_16x16x32_bf16 v[12:15], v[156:159], v[196:199], v[12:15]
	s_barrier
	s_setprio 3
	v_mfma_f32_16x16x32_bf16 v[8:11], v[164:167], v[196:199], v[8:11]
	s_setprio 0
	s_bitcmp1_b32 s30, 8
	s_cbranch_scc0 .Leb893_22
	s_setprio 1
.Leb893_22:
	s_add_u32 s58, s26, 0x40000
	s_addc_u32 s59, s27, 0
	s_add_i32 s60, s48, s31
	s_mov_b32 m0, s60
	s_nop 0
	global_load_lds_dwordx4 v132, s[58:59]
	s_add_i32 m0, s60, 0x2000
	s_nop 0
	global_load_lds_dwordx4 v128, s[58:59]
	s_waitcnt vmcnt(8)
	s_barrier
	v_mfma_f32_16x16x32_bf16 v[52:55], v[200:203], v[168:171], 0
	v_mfma_f32_16x16x32_bf16 v[48:51], v[208:211], v[168:171], 0
	v_mfma_f32_16x16x32_bf16 v[36:39], v[200:203], v[176:179], 0
	v_mfma_f32_16x16x32_bf16 v[32:35], v[208:211], v[176:179], 0
	v_mfma_f32_16x16x32_bf16 v[20:23], v[200:203], v[184:187], 0
	v_mfma_f32_16x16x32_bf16 v[16:19], v[208:211], v[184:187], 0
	v_mfma_f32_16x16x32_bf16 v[4:7], v[200:203], v[192:195], 0
	v_mfma_f32_16x16x32_bf16 v[0:3], v[208:211], v[192:195], 0
	v_mfma_f32_16x16x32_bf16 v[52:55], v[204:207], v[172:175], v[52:55]
	v_mfma_f32_16x16x32_bf16 v[48:51], v[212:215], v[172:175], v[48:51]
	v_mfma_f32_16x16x32_bf16 v[36:39], v[204:207], v[180:183], v[36:39]
	v_mfma_f32_16x16x32_bf16 v[32:35], v[212:215], v[180:183], v[32:35]
	v_mfma_f32_16x16x32_bf16 v[20:23], v[204:207], v[188:191], v[20:23]
	v_mfma_f32_16x16x32_bf16 v[16:19], v[212:215], v[188:191], v[16:19]
	v_mfma_f32_16x16x32_bf16 v[4:7], v[204:207], v[196:199], v[4:7]
	s_barrier
	s_setprio 3
	v_mfma_f32_16x16x32_bf16 v[0:3], v[212:215], v[196:199], v[0:3]
	s_setprio 0
	s_bitcmp1_b32 s30, 8
	s_cbranch_scc0 .Leb893_21
	s_setprio 1
.Leb893_21:
	s_add_i32 s58, 0, 0x18000
	v_add_u32_e32 v151, s58, v145
	s_branch .Lg893_mid
.LBB0_893:
	ds_read_b128 v[152:155], v148
	ds_read_b128 v[156:159], v148 offset:1024
	ds_read_b128 v[160:163], v148 offset:2048
	ds_read_b128 v[164:167], v148 offset:3072
	s_add_u32 s26, s20, 0xfffc0080
	s_addc_u32 s27, s21, -1
	s_cmp_eq_u32 s57, 12
	s_cselect_b32 s29, s13, s27
	s_cselect_b32 s28, s53, s26
	s_cselect_b32 s27, s11, s56
	s_cselect_b32 s26, s54, s55
	s_add_i32 m0, s19, 0xc000
	ds_read_b128 v[168:171], v149
	ds_read_b128 v[172:175], v149 offset:1024
	ds_read_b128 v[176:179], v149 offset:2048
	ds_read_b128 v[180:183], v149 offset:3072
	ds_read_b128 v[184:187], v149 offset:4096
	ds_read_b128 v[188:191], v149 offset:5120
	ds_read_b128 v[192:195], v149 offset:6144
	ds_read_b128 v[196:199], v149 offset:7168
	global_load_lds_dwordx4 v136, s[20:21]
	s_add_i32 m0, s19, 0xe000
	s_nop 0
	global_load_lds_dwordx4 v138, s[20:21]
	s_waitcnt lgkmcnt(8)
	s_barrier
	s_waitcnt lgkmcnt(0)
	s_waitcnt lgkmcnt(0)
	v_mfma_f32_16x16x32_bf16 v[124:127], v[152:155], v[168:171], v[124:127]
	v_mfma_f32_16x16x32_bf16 v[120:123], v[160:163], v[168:171], v[120:123]
	v_mfma_f32_16x16x32_bf16 v[108:111], v[152:155], v[176:179], v[108:111]
	v_mfma_f32_16x16x32_bf16 v[104:107], v[160:163], v[176:179], v[104:107]
	v_mfma_f32_16x16x32_bf16 v[92:95], v[152:155], v[184:187], v[92:95]
	v_mfma_f32_16x16x32_bf16 v[88:91], v[160:163], v[184:187], v[88:91]
	v_mfma_f32_16x16x32_bf16 v[76:79], v[152:155], v[192:195], v[76:79]
	v_mfma_f32_16x16x32_bf16 v[72:75], v[160:163], v[192:195], v[72:75]
	v_mfma_f32_16x16x32_bf16 v[124:127], v[156:159], v[172:175], v[124:127]
	v_mfma_f32_16x16x32_bf16 v[120:123], v[164:167], v[172:175], v[120:123]
	v_mfma_f32_16x16x32_bf16 v[108:111], v[156:159], v[180:183], v[108:111]
	v_mfma_f32_16x16x32_bf16 v[104:107], v[164:167], v[180:183], v[104:107]
	v_mfma_f32_16x16x32_bf16 v[92:95], v[156:159], v[188:191], v[92:95]
	v_mfma_f32_16x16x32_bf16 v[88:91], v[164:167], v[188:191], v[88:91]
	v_mfma_f32_16x16x32_bf16 v[76:79], v[156:159], v[196:199], v[76:79]
	s_barrier
	s_setprio 3
	v_mfma_f32_16x16x32_bf16 v[72:75], v[164:167], v[196:199], v[72:75]
	s_setprio 0
	s_bitcmp1_b32 s30, 8
	s_cbranch_scc0 .Leb893_20
	s_setprio 1
.Leb893_20:
	s_add_i32 s58, s47, s31
	s_add_u32 s80, s26, 0x80
	s_addc_u32 s81, s27, 0
	s_mov_b32 m0, s58
	ds_read_b128 v[200:203], v150
	ds_read_b128 v[204:207], v150 offset:1024
	ds_read_b128 v[208:211], v150 offset:2048
	ds_read_b128 v[212:215], v150 offset:3072
	global_load_lds_dwordx4 v132, s[26:27]
	s_add_i32 m0, s58, 0x2000
	s_nop 0
	global_load_lds_dwordx4 v128, s[26:27]
	s_waitcnt vmcnt(10)
	s_barrier
	s_waitcnt lgkmcnt(0)
	s_waitcnt lgkmcnt(0)
	v_mfma_f32_16x16x32_bf16 v[116:119], v[200:203], v[168:171], v[116:119]
	v_mfma_f32_16x16x32_bf16 v[112:115], v[208:211], v[168:171], v[112:115]
	v_mfma_f32_16x16x32_bf16 v[100:103], v[200:203], v[176:179], v[100:103]
	v_mfma_f32_16x16x32_bf16 v[96:99], v[208:211], v[176:179], v[96:99]
	v_mfma_f32_16x16x32_bf16 v[84:87], v[200:203], v[184:187], v[84:87]
	v_mfma_f32_16x16x32_bf16 v[80:83], v[208:211], v[184:187], v[80:83]
	v_mfma_f32_16x16x32_bf16 v[68:71], v[200:203], v[192:195], v[68:71]
	v_mfma_f32_16x16x32_bf16 v[64:67], v[208:211], v[192:195], v[64:67]
	v_mfma_f32_16x16x32_bf16 v[116:119], v[204:207], v[172:175], v[116:119]
	v_mfma_f32_16x16x32_bf16 v[112:115], v[212:215], v[172:175], v[112:115]
	v_mfma_f32_16x16x32_bf16 v[100:103], v[204:207], v[180:183], v[100:103]
	v_mfma_f32_16x16x32_bf16 v[96:99], v[212:215], v[180:183], v[96:99]
	v_mfma_f32_16x16x32_bf16 v[84:87], v[204:207], v[188:191], v[84:87]
	v_mfma_f32_16x16x32_bf16 v[80:83], v[212:215], v[188:191], v[80:83]
	v_mfma_f32_16x16x32_bf16 v[68:71], v[204:207], v[196:199], v[68:71]
	s_barrier
	s_setprio 3
	v_mfma_f32_16x16x32_bf16 v[64:67], v[212:215], v[196:199], v[64:67]
	s_setprio 0
	s_bitcmp1_b32 s30, 8
	s_cbranch_scc0 .Leb893_19
	s_setprio 1
.Leb893_19:
	s_mov_b32 m0, s19
	s_add_u32 s82, s28, 0x80
	s_addc_u32 s83, s29, 0
	ds_read_b128 v[168:171], v149 offset:16384
	ds_read_b128 v[172:175], v149 offset:17408
	ds_read_b128 v[176:179], v149 offset:18432
	ds_read_b128 v[180:183], v149 offset:19456
	ds_read_b128 v[184:187], v149 offset:20480
	ds_read_b128 v[188:191], v149 offset:21504
	ds_read_b128 v[192:195], v149 offset:22528
	ds_read_b128 v[196:199], v149 offset:23552
	global_load_lds_dwordx4 v134, s[28:29]
	s_mov_b32 m0, s42
	s_nop 0
	global_load_lds_dwordx4 v130, s[28:29]
	s_barrier
	s_waitcnt lgkmcnt(0)
	s_waitcnt lgkmcnt(0)
	v_mfma_f32_16x16x32_bf16 v[60:63], v[152:155], v[168:171], v[60:63]
	v_mfma_f32_16x16x32_bf16 v[56:59], v[160:163], v[168:171], v[56:59]
	v_mfma_f32_16x16x32_bf16 v[44:47], v[152:155], v[176:179], v[44:47]
	v_mfma_f32_16x16x32_bf16 v[40:43], v[160:163], v[176:179], v[40:43]
	v_mfma_f32_16x16x32_bf16 v[28:31], v[152:155], v[184:187], v[28:31]
	v_mfma_f32_16x16x32_bf16 v[24:27], v[160:163], v[184:187], v[24:27]
	v_mfma_f32_16x16x32_bf16 v[12:15], v[152:155], v[192:195], v[12:15]
	v_mfma_f32_16x16x32_bf16 v[8:11], v[160:163], v[192:195], v[8:11]
	v_mfma_f32_16x16x32_bf16 v[60:63], v[156:159], v[172:175], v[60:63]
	v_mfma_f32_16x16x32_bf16 v[56:59], v[164:167], v[172:175], v[56:59]
	v_mfma_f32_16x16x32_bf16 v[44:47], v[156:159], v[180:183], v[44:47]
	v_mfma_f32_16x16x32_bf16 v[40:43], v[164:167], v[180:183], v[40:43]
	v_mfma_f32_16x16x32_bf16 v[28:31], v[156:159], v[188:191], v[28:31]
	v_mfma_f32_16x16x32_bf16 v[24:27], v[164:167], v[188:191], v[24:27]
	v_mfma_f32_16x16x32_bf16 v[12:15], v[156:159], v[196:199], v[12:15]
	s_barrier
	s_setprio 3
	v_mfma_f32_16x16x32_bf16 v[8:11], v[164:167], v[196:199], v[8:11]
	s_setprio 0
	s_bitcmp1_b32 s30, 8
	s_cbranch_scc0 .Leb893_18
	s_setprio 1
.Leb893_18:
	s_add_u32 s58, s26, 0x40000
	s_addc_u32 s59, s27, 0
	s_add_i32 s60, s48, s31
	s_mov_b32 m0, s60
	s_nop 0
	global_load_lds_dwordx4 v132, s[58:59]
	s_add_i32 m0, s60, 0x2000
	s_nop 0
	global_load_lds_dwordx4 v128, s[58:59]
	s_waitcnt vmcnt(8)
	s_barrier
	v_mfma_f32_16x16x32_bf16 v[52:55], v[200:203], v[168:171], v[52:55]
	v_mfma_f32_16x16x32_bf16 v[48:51], v[208:211], v[168:171], v[48:51]
	v_mfma_f32_16x16x32_bf16 v[36:39], v[200:203], v[176:179], v[36:39]
	v_mfma_f32_16x16x32_bf16 v[32:35], v[208:211], v[176:179], v[32:35]
	v_mfma_f32_16x16x32_bf16 v[20:23], v[200:203], v[184:187], v[20:23]
	v_mfma_f32_16x16x32_bf16 v[16:19], v[208:211], v[184:187], v[16:19]
	v_mfma_f32_16x16x32_bf16 v[4:7], v[200:203], v[192:195], v[4:7]
	v_mfma_f32_16x16x32_bf16 v[0:3], v[208:211], v[192:195], v[0:3]
	v_mfma_f32_16x16x32_bf16 v[52:55], v[204:207], v[172:175], v[52:55]
	v_mfma_f32_16x16x32_bf16 v[48:51], v[212:215], v[172:175], v[48:51]
	v_mfma_f32_16x16x32_bf16 v[36:39], v[204:207], v[180:183], v[36:39]
	v_mfma_f32_16x16x32_bf16 v[32:35], v[212:215], v[180:183], v[32:35]
	v_mfma_f32_16x16x32_bf16 v[20:23], v[204:207], v[188:191], v[20:23]
	v_mfma_f32_16x16x32_bf16 v[16:19], v[212:215], v[188:191], v[16:19]
	v_mfma_f32_16x16x32_bf16 v[4:7], v[204:207], v[196:199], v[4:7]
	s_barrier
	s_setprio 3
	v_mfma_f32_16x16x32_bf16 v[0:3], v[212:215], v[196:199], v[0:3]
	s_setprio 0
	s_bitcmp1_b32 s30, 8
	s_cbranch_scc0 .Leb893_17
	s_setprio 1
.Leb893_17:
	s_add_i32 s58, 0, 0x18000
	v_add_u32_e32 v151, s58, v145
.Lg893_mid:
	ds_read_b128 v[152:155], v151
	ds_read_b128 v[156:159], v151 offset:1024
	ds_read_b128 v[160:163], v151 offset:2048
	ds_read_b128 v[164:167], v151 offset:3072
	s_add_u32 s28, s28, 0x40000
	s_addc_u32 s29, s29, 0
	s_mov_b32 m0, s43
	ds_read_b128 v[168:171], v149 offset:32768
	ds_read_b128 v[172:175], v149 offset:33792
	ds_read_b128 v[176:179], v149 offset:34816
	ds_read_b128 v[180:183], v149 offset:35840
	ds_read_b128 v[184:187], v149 offset:36864
	ds_read_b128 v[188:191], v149 offset:37888
	ds_read_b128 v[192:195], v149 offset:38912
	ds_read_b128 v[196:199], v149 offset:39936
	global_load_lds_dwordx4 v134, s[28:29]
	s_mov_b32 m0, s44
	s_nop 0
	global_load_lds_dwordx4 v130, s[28:29]
	s_waitcnt lgkmcnt(8)
	s_barrier
	s_waitcnt lgkmcnt(0)
	s_waitcnt lgkmcnt(0)
	v_mfma_f32_16x16x32_bf16 v[124:127], v[152:155], v[168:171], v[124:127]
	v_mfma_f32_16x16x32_bf16 v[120:123], v[160:163], v[168:171], v[120:123]
	v_mfma_f32_16x16x32_bf16 v[108:111], v[152:155], v[176:179], v[108:111]
	v_mfma_f32_16x16x32_bf16 v[104:107], v[160:163], v[176:179], v[104:107]
	v_mfma_f32_16x16x32_bf16 v[92:95], v[152:155], v[184:187], v[92:95]
	v_mfma_f32_16x16x32_bf16 v[88:91], v[160:163], v[184:187], v[88:91]
	v_mfma_f32_16x16x32_bf16 v[76:79], v[152:155], v[192:195], v[76:79]
	v_mfma_f32_16x16x32_bf16 v[72:75], v[160:163], v[192:195], v[72:75]
	v_mfma_f32_16x16x32_bf16 v[124:127], v[156:159], v[172:175], v[124:127]
	v_mfma_f32_16x16x32_bf16 v[120:123], v[164:167], v[172:175], v[120:123]
	v_mfma_f32_16x16x32_bf16 v[108:111], v[156:159], v[180:183], v[108:111]
	v_mfma_f32_16x16x32_bf16 v[104:107], v[164:167], v[180:183], v[104:107]
	v_mfma_f32_16x16x32_bf16 v[92:95], v[156:159], v[188:191], v[92:95]
	v_mfma_f32_16x16x32_bf16 v[88:91], v[164:167], v[188:191], v[88:91]
	v_mfma_f32_16x16x32_bf16 v[76:79], v[156:159], v[196:199], v[76:79]
	s_barrier
	s_setprio 3
	v_mfma_f32_16x16x32_bf16 v[72:75], v[164:167], v[196:199], v[72:75]
	s_setprio 0
	s_bitcmp1_b32 s30, 8
	s_cbranch_scc0 .Leb893_16
	s_setprio 1
.Leb893_16:
	s_add_i32 s28, 0, 0x1c000
	s_add_i32 s29, s58, s31
	v_add_u32_e32 v151, s28, v145
	s_mov_b32 m0, s29
	ds_read_b128 v[200:203], v151
	ds_read_b128 v[204:207], v151 offset:1024
	ds_read_b128 v[208:211], v151 offset:2048
	ds_read_b128 v[212:215], v151 offset:3072
	global_load_lds_dwordx4 v132, s[80:81]
	s_add_i32 m0, s29, 0x2000
	s_nop 0
	global_load_lds_dwordx4 v128, s[80:81]
	s_waitcnt vmcnt(10)
	s_barrier
	s_waitcnt lgkmcnt(0)
	s_waitcnt lgkmcnt(0)
	v_mfma_f32_16x16x32_bf16 v[116:119], v[200:203], v[168:171], v[116:119]
	v_mfma_f32_16x16x32_bf16 v[112:115], v[208:211], v[168:171], v[112:115]
	v_mfma_f32_16x16x32_bf16 v[100:103], v[200:203], v[176:179], v[100:103]
	v_mfma_f32_16x16x32_bf16 v[96:99], v[208:211], v[176:179], v[96:99]
	v_mfma_f32_16x16x32_bf16 v[84:87], v[200:203], v[184:187], v[84:87]
	v_mfma_f32_16x16x32_bf16 v[80:83], v[208:211], v[184:187], v[80:83]
	v_mfma_f32_16x16x32_bf16 v[68:71], v[200:203], v[192:195], v[68:71]
	v_mfma_f32_16x16x32_bf16 v[64:67], v[208:211], v[192:195], v[64:67]
	v_mfma_f32_16x16x32_bf16 v[116:119], v[204:207], v[172:175], v[116:119]
	v_mfma_f32_16x16x32_bf16 v[112:115], v[212:215], v[172:175], v[112:115]
	v_mfma_f32_16x16x32_bf16 v[100:103], v[204:207], v[180:183], v[100:103]
	v_mfma_f32_16x16x32_bf16 v[96:99], v[212:215], v[180:183], v[96:99]
	v_mfma_f32_16x16x32_bf16 v[84:87], v[204:207], v[188:191], v[84:87]
	v_mfma_f32_16x16x32_bf16 v[80:83], v[212:215], v[188:191], v[80:83]
	v_mfma_f32_16x16x32_bf16 v[68:71], v[204:207], v[196:199], v[68:71]
	s_barrier
	s_setprio 3
	v_mfma_f32_16x16x32_bf16 v[64:67], v[212:215], v[196:199], v[64:67]
	s_setprio 0
	s_bitcmp1_b32 s30, 8
	s_cbranch_scc0 .Leb893_15
	s_setprio 1
.Leb893_15:
	s_mov_b32 m0, s45
	ds_read_b128 v[168:171], v149 offset:49152
	ds_read_b128 v[172:175], v149 offset:50176
	ds_read_b128 v[176:179], v149 offset:51200
	ds_read_b128 v[180:183], v149 offset:52224
	ds_read_b128 v[184:187], v149 offset:53248
	ds_read_b128 v[188:191], v149 offset:54272
	ds_read_b128 v[192:195], v149 offset:55296
	ds_read_b128 v[196:199], v149 offset:56320
	global_load_lds_dwordx4 v134, s[82:83]
	s_mov_b32 m0, s46
	s_nop 0
	global_load_lds_dwordx4 v130, s[82:83]
	s_barrier
	s_waitcnt lgkmcnt(0)
	s_waitcnt lgkmcnt(0)
	v_mfma_f32_16x16x32_bf16 v[60:63], v[152:155], v[168:171], v[60:63]
	v_mfma_f32_16x16x32_bf16 v[56:59], v[160:163], v[168:171], v[56:59]
	v_mfma_f32_16x16x32_bf16 v[44:47], v[152:155], v[176:179], v[44:47]
	v_mfma_f32_16x16x32_bf16 v[40:43], v[160:163], v[176:179], v[40:43]
	v_mfma_f32_16x16x32_bf16 v[28:31], v[152:155], v[184:187], v[28:31]
	v_mfma_f32_16x16x32_bf16 v[24:27], v[160:163], v[184:187], v[24:27]
	v_mfma_f32_16x16x32_bf16 v[12:15], v[152:155], v[192:195], v[12:15]
	v_mfma_f32_16x16x32_bf16 v[8:11], v[160:163], v[192:195], v[8:11]
	v_mfma_f32_16x16x32_bf16 v[60:63], v[156:159], v[172:175], v[60:63]
	v_mfma_f32_16x16x32_bf16 v[56:59], v[164:167], v[172:175], v[56:59]
	v_mfma_f32_16x16x32_bf16 v[44:47], v[156:159], v[180:183], v[44:47]
	v_mfma_f32_16x16x32_bf16 v[40:43], v[164:167], v[180:183], v[40:43]
	v_mfma_f32_16x16x32_bf16 v[28:31], v[156:159], v[188:191], v[28:31]
	v_mfma_f32_16x16x32_bf16 v[24:27], v[164:167], v[188:191], v[24:27]
	v_mfma_f32_16x16x32_bf16 v[12:15], v[156:159], v[196:199], v[12:15]
	s_barrier
	s_setprio 3
	v_mfma_f32_16x16x32_bf16 v[8:11], v[164:167], v[196:199], v[8:11]
	s_setprio 0
	s_bitcmp1_b32 s30, 8
	s_cbranch_scc0 .Leb893_14
	s_setprio 1
.Leb893_14:
	s_add_u32 s26, s26, 0x40080
	s_addc_u32 s27, s27, 0
	s_add_i32 s28, s28, s31
	s_mov_b32 m0, s28
	s_nop 0
	global_load_lds_dwordx4 v132, s[26:27]
	s_add_i32 m0, s28, 0x2000
	s_nop 0
	global_load_lds_dwordx4 v128, s[26:27]
	s_waitcnt vmcnt(8)
	s_barrier
	v_mfma_f32_16x16x32_bf16 v[52:55], v[200:203], v[168:171], v[52:55]
	v_mfma_f32_16x16x32_bf16 v[48:51], v[208:211], v[168:171], v[48:51]
	v_mfma_f32_16x16x32_bf16 v[36:39], v[200:203], v[176:179], v[36:39]
	v_mfma_f32_16x16x32_bf16 v[32:35], v[208:211], v[176:179], v[32:35]
	v_mfma_f32_16x16x32_bf16 v[20:23], v[200:203], v[184:187], v[20:23]
	v_mfma_f32_16x16x32_bf16 v[16:19], v[208:211], v[184:187], v[16:19]
	v_mfma_f32_16x16x32_bf16 v[4:7], v[200:203], v[192:195], v[4:7]
	v_mfma_f32_16x16x32_bf16 v[0:3], v[208:211], v[192:195], v[0:3]
	v_mfma_f32_16x16x32_bf16 v[52:55], v[204:207], v[172:175], v[52:55]
	v_mfma_f32_16x16x32_bf16 v[48:51], v[212:215], v[172:175], v[48:51]
	v_mfma_f32_16x16x32_bf16 v[36:39], v[204:207], v[180:183], v[36:39]
	v_mfma_f32_16x16x32_bf16 v[32:35], v[212:215], v[180:183], v[32:35]
	v_mfma_f32_16x16x32_bf16 v[20:23], v[204:207], v[188:191], v[20:23]
	v_mfma_f32_16x16x32_bf16 v[16:19], v[212:215], v[188:191], v[16:19]
	v_mfma_f32_16x16x32_bf16 v[4:7], v[204:207], v[196:199], v[4:7]
	s_barrier
	s_setprio 3
	v_mfma_f32_16x16x32_bf16 v[0:3], v[212:215], v[196:199], v[0:3]
	s_setprio 0
	s_bitcmp1_b32 s30, 8
	s_cbranch_scc0 .Leb893_13
	s_setprio 1
.Leb893_13:
	s_add_i32 s57, s57, 2
	s_add_u32 s20, s20, 0x100
	s_addc_u32 s21, s21, 0
	s_add_u32 s55, s55, 0x100
	s_addc_u32 s56, s56, 0
	s_cmp_gt_u32 s57, 13
	s_cbranch_scc0 .LBB0_893
	s_nop 7
	s_nop 7
	s_setprio 0
	s_cmpk_gt_u32 s30, 0xff
	s_cbranch_scc1 .Lg893_nox
	s_barrier
	s_setprio 1

.Lg973_noy:
	ds_read_b128 v[146:149], v203
	ds_read_b128 v[150:153], v203 offset:1024
	ds_read_b128 v[154:157], v203 offset:2048
	ds_read_b128 v[158:161], v203 offset:3072
	s_add_u32 s22, s20, 0x100
	s_addc_u32 s23, s21, 0
	s_cmp_eq_u32 s56, 40
	s_cselect_b32 s27, s5, s23
	s_cselect_b32 s26, s4, s22
	s_cselect_b32 s25, s7, s55
	s_cselect_b32 s24, s6, s54
	s_add_i32 m0, s37, 0xc000
	ds_read_b128 v[162:165], v204
	ds_read_b128 v[166:169], v204 offset:1024
	ds_read_b128 v[170:173], v204 offset:2048
	ds_read_b128 v[174:177], v204 offset:3072
	ds_read_b128 v[178:181], v204 offset:4096
	ds_read_b128 v[182:185], v204 offset:5120
	ds_read_b128 v[186:189], v204 offset:6144
	ds_read_b128 v[190:193], v204 offset:7168
	global_load_lds_dwordx4 v138, s[20:21]
	s_add_i32 m0, s37, 0xe000
	s_nop 0
	global_load_lds_dwordx4 v140, s[20:21]
	s_waitcnt lgkmcnt(8)
	s_barrier
	s_waitcnt lgkmcnt(0)
	s_waitcnt lgkmcnt(0)
	v_mfma_f32_16x16x32_bf16 v[124:127], v[146:149], v[162:165], 0
	v_mfma_f32_16x16x32_bf16 v[120:123], v[154:157], v[162:165], 0
	v_mfma_f32_16x16x32_bf16 v[108:111], v[146:149], v[170:173], 0
	v_mfma_f32_16x16x32_bf16 v[104:107], v[154:157], v[170:173], 0
	v_mfma_f32_16x16x32_bf16 v[92:95], v[146:149], v[178:181], 0
	v_mfma_f32_16x16x32_bf16 v[88:91], v[154:157], v[178:181], 0
	v_mfma_f32_16x16x32_bf16 v[76:79], v[146:149], v[186:189], 0
	v_mfma_f32_16x16x32_bf16 v[72:75], v[154:157], v[186:189], 0
	v_mfma_f32_16x16x32_bf16 v[124:127], v[150:153], v[166:169], v[124:127]
	v_mfma_f32_16x16x32_bf16 v[120:123], v[158:161], v[166:169], v[120:123]
	v_mfma_f32_16x16x32_bf16 v[108:111], v[150:153], v[174:177], v[108:111]
	v_mfma_f32_16x16x32_bf16 v[104:107], v[158:161], v[174:177], v[104:107]
	v_mfma_f32_16x16x32_bf16 v[92:95], v[150:153], v[182:185], v[92:95]
	v_mfma_f32_16x16x32_bf16 v[88:91], v[158:161], v[182:185], v[88:91]
	v_mfma_f32_16x16x32_bf16 v[76:79], v[150:153], v[190:193], v[76:79]
	s_barrier
	s_setprio 3
	v_mfma_f32_16x16x32_bf16 v[72:75], v[158:161], v[190:193], v[72:75]
	s_setprio 0
	s_bitcmp1_b32 s30, 8
	s_cbranch_scc0 .Leb973_12
	s_setprio 1
.Leb973_12:
	s_add_i32 s20, s47, s36
	s_add_u32 s80, s24, 0x80
	s_addc_u32 s81, s25, 0
	s_mov_b32 m0, s20
	ds_read_b128 v[194:197], v205
	ds_read_b128 v[208:211], v205 offset:1024
	ds_read_b128 v[212:215], v205 offset:2048
	ds_read_b128 v[216:219], v205 offset:3072
	global_load_lds_dwordx4 v130, s[24:25]
	s_add_i32 m0, s20, 0x2000
	s_nop 0
	global_load_lds_dwordx4 v134, s[24:25]
	s_waitcnt vmcnt(10)
	s_barrier
	s_waitcnt lgkmcnt(0)
	s_waitcnt lgkmcnt(0)
	v_mfma_f32_16x16x32_bf16 v[116:119], v[194:197], v[162:165], 0
	v_mfma_f32_16x16x32_bf16 v[112:115], v[212:215], v[162:165], 0
	v_mfma_f32_16x16x32_bf16 v[100:103], v[194:197], v[170:173], 0
	v_mfma_f32_16x16x32_bf16 v[96:99], v[212:215], v[170:173], 0
	v_mfma_f32_16x16x32_bf16 v[84:87], v[194:197], v[178:181], 0
	v_mfma_f32_16x16x32_bf16 v[80:83], v[212:215], v[178:181], 0
	v_mfma_f32_16x16x32_bf16 v[68:71], v[194:197], v[186:189], 0
	v_mfma_f32_16x16x32_bf16 v[64:67], v[212:215], v[186:189], 0
	v_mfma_f32_16x16x32_bf16 v[116:119], v[208:211], v[166:169], v[116:119]
	v_mfma_f32_16x16x32_bf16 v[112:115], v[216:219], v[166:169], v[112:115]
	v_mfma_f32_16x16x32_bf16 v[100:103], v[208:211], v[174:177], v[100:103]
	v_mfma_f32_16x16x32_bf16 v[96:99], v[216:219], v[174:177], v[96:99]
	v_mfma_f32_16x16x32_bf16 v[84:87], v[208:211], v[182:185], v[84:87]
	v_mfma_f32_16x16x32_bf16 v[80:83], v[216:219], v[182:185], v[80:83]
	v_mfma_f32_16x16x32_bf16 v[68:71], v[208:211], v[190:193], v[68:71]
	s_barrier
	s_setprio 3
	v_mfma_f32_16x16x32_bf16 v[64:67], v[216:219], v[190:193], v[64:67]
	s_setprio 0
	s_bitcmp1_b32 s30, 8
	s_cbranch_scc0 .Leb973_11
	s_setprio 1
.Leb973_11:
	s_mov_b32 m0, s37
	s_add_u32 s82, s26, 0x80
	s_addc_u32 s83, s27, 0
	ds_read_b128 v[162:165], v204 offset:16384
	ds_read_b128 v[166:169], v204 offset:17408
	ds_read_b128 v[170:173], v204 offset:18432
	ds_read_b128 v[174:177], v204 offset:19456
	ds_read_b128 v[178:181], v204 offset:20480
	ds_read_b128 v[182:185], v204 offset:21504
	ds_read_b128 v[186:189], v204 offset:22528
	ds_read_b128 v[190:193], v204 offset:23552
	global_load_lds_dwordx4 v128, s[26:27]
	s_mov_b32 m0, s38
	s_nop 0
	global_load_lds_dwordx4 v132, s[26:27]
	s_barrier
	s_waitcnt lgkmcnt(0)
	s_waitcnt lgkmcnt(0)
	v_mfma_f32_16x16x32_bf16 v[60:63], v[146:149], v[162:165], 0
	v_mfma_f32_16x16x32_bf16 v[56:59], v[154:157], v[162:165], 0
	v_mfma_f32_16x16x32_bf16 v[44:47], v[146:149], v[170:173], 0
	v_mfma_f32_16x16x32_bf16 v[40:43], v[154:157], v[170:173], 0
	v_mfma_f32_16x16x32_bf16 v[28:31], v[146:149], v[178:181], 0
	v_mfma_f32_16x16x32_bf16 v[24:27], v[154:157], v[178:181], 0
	v_mfma_f32_16x16x32_bf16 v[12:15], v[146:149], v[186:189], 0
	v_mfma_f32_16x16x32_bf16 v[8:11], v[154:157], v[186:189], 0
	v_mfma_f32_16x16x32_bf16 v[60:63], v[150:153], v[166:169], v[60:63]
	v_mfma_f32_16x16x32_bf16 v[56:59], v[158:161], v[166:169], v[56:59]
	v_mfma_f32_16x16x32_bf16 v[44:47], v[150:153], v[174:177], v[44:47]
	v_mfma_f32_16x16x32_bf16 v[40:43], v[158:161], v[174:177], v[40:43]
	v_mfma_f32_16x16x32_bf16 v[28:31], v[150:153], v[182:185], v[28:31]
	v_mfma_f32_16x16x32_bf16 v[24:27], v[158:161], v[182:185], v[24:27]
	v_mfma_f32_16x16x32_bf16 v[12:15], v[150:153], v[190:193], v[12:15]
	s_barrier
	s_setprio 3
	v_mfma_f32_16x16x32_bf16 v[8:11], v[158:161], v[190:193], v[8:11]
	s_setprio 0
	s_bitcmp1_b32 s30, 8
	s_cbranch_scc0 .Leb973_10
	s_setprio 1
.Leb973_10:
	s_add_u32 s20, s24, 0xb0000
	s_addc_u32 s21, s25, 0
	s_add_i32 s57, s48, s36
	s_mov_b32 m0, s57
	s_nop 0
	global_load_lds_dwordx4 v130, s[20:21]
	s_add_i32 m0, s57, 0x2000
	s_nop 0
	global_load_lds_dwordx4 v134, s[20:21]
	s_waitcnt vmcnt(8)
	s_barrier
	v_mfma_f32_16x16x32_bf16 v[52:55], v[194:197], v[162:165], 0
	v_mfma_f32_16x16x32_bf16 v[48:51], v[212:215], v[162:165], 0
	v_mfma_f32_16x16x32_bf16 v[36:39], v[194:197], v[170:173], 0
	v_mfma_f32_16x16x32_bf16 v[32:35], v[212:215], v[170:173], 0
	v_mfma_f32_16x16x32_bf16 v[20:23], v[194:197], v[178:181], 0
	v_mfma_f32_16x16x32_bf16 v[16:19], v[212:215], v[178:181], 0
	v_mfma_f32_16x16x32_bf16 v[4:7], v[194:197], v[186:189], 0
	v_mfma_f32_16x16x32_bf16 v[0:3], v[212:215], v[186:189], 0
	v_mfma_f32_16x16x32_bf16 v[52:55], v[208:211], v[166:169], v[52:55]
	v_mfma_f32_16x16x32_bf16 v[48:51], v[216:219], v[166:169], v[48:51]
	v_mfma_f32_16x16x32_bf16 v[36:39], v[208:211], v[174:177], v[36:39]
	v_mfma_f32_16x16x32_bf16 v[32:35], v[216:219], v[174:177], v[32:35]
	v_mfma_f32_16x16x32_bf16 v[20:23], v[208:211], v[182:185], v[20:23]
	v_mfma_f32_16x16x32_bf16 v[16:19], v[216:219], v[182:185], v[16:19]
	v_mfma_f32_16x16x32_bf16 v[4:7], v[208:211], v[190:193], v[4:7]
	s_barrier
	s_setprio 3
	v_mfma_f32_16x16x32_bf16 v[0:3], v[216:219], v[190:193], v[0:3]
	s_setprio 0
	s_bitcmp1_b32 s30, 8
	s_cbranch_scc0 .Leb973_9
	s_setprio 1
.Leb973_9:
	s_add_i32 s57, 0, 0x18000
	v_add_u32_e32 v158, s57, v201
	s_branch .Lg973_mid
.LBB0_973:
	ds_read_b128 v[146:149], v203
	ds_read_b128 v[150:153], v203 offset:1024
	ds_read_b128 v[154:157], v203 offset:2048
	ds_read_b128 v[158:161], v203 offset:3072
	s_add_u32 s22, s20, 0x100
	s_addc_u32 s23, s21, 0
	s_cmp_eq_u32 s56, 40
	s_cselect_b32 s27, s5, s23
	s_cselect_b32 s26, s4, s22
	s_cselect_b32 s25, s7, s55
	s_cselect_b32 s24, s6, s54
	s_add_i32 m0, s37, 0xc000
	ds_read_b128 v[162:165], v204
	ds_read_b128 v[166:169], v204 offset:1024
	ds_read_b128 v[170:173], v204 offset:2048
	ds_read_b128 v[174:177], v204 offset:3072
	ds_read_b128 v[178:181], v204 offset:4096
	ds_read_b128 v[182:185], v204 offset:5120
	ds_read_b128 v[186:189], v204 offset:6144
	ds_read_b128 v[190:193], v204 offset:7168
	global_load_lds_dwordx4 v138, s[20:21]
	s_add_i32 m0, s37, 0xe000
	s_nop 0
	global_load_lds_dwordx4 v140, s[20:21]
	s_waitcnt lgkmcnt(8)
	s_barrier
	s_waitcnt lgkmcnt(0)
	s_waitcnt lgkmcnt(0)
	v_mfma_f32_16x16x32_bf16 v[124:127], v[146:149], v[162:165], v[124:127]
	v_mfma_f32_16x16x32_bf16 v[120:123], v[154:157], v[162:165], v[120:123]
	v_mfma_f32_16x16x32_bf16 v[108:111], v[146:149], v[170:173], v[108:111]
	v_mfma_f32_16x16x32_bf16 v[104:107], v[154:157], v[170:173], v[104:107]
	v_mfma_f32_16x16x32_bf16 v[92:95], v[146:149], v[178:181], v[92:95]
	v_mfma_f32_16x16x32_bf16 v[88:91], v[154:157], v[178:181], v[88:91]
	v_mfma_f32_16x16x32_bf16 v[76:79], v[146:149], v[186:189], v[76:79]
	v_mfma_f32_16x16x32_bf16 v[72:75], v[154:157], v[186:189], v[72:75]
	v_mfma_f32_16x16x32_bf16 v[124:127], v[150:153], v[166:169], v[124:127]
	v_mfma_f32_16x16x32_bf16 v[120:123], v[158:161], v[166:169], v[120:123]
	v_mfma_f32_16x16x32_bf16 v[108:111], v[150:153], v[174:177], v[108:111]
	v_mfma_f32_16x16x32_bf16 v[104:107], v[158:161], v[174:177], v[104:107]
	v_mfma_f32_16x16x32_bf16 v[92:95], v[150:153], v[182:185], v[92:95]
	v_mfma_f32_16x16x32_bf16 v[88:91], v[158:161], v[182:185], v[88:91]
	v_mfma_f32_16x16x32_bf16 v[76:79], v[150:153], v[190:193], v[76:79]
	s_barrier
	s_setprio 3
	v_mfma_f32_16x16x32_bf16 v[72:75], v[158:161], v[190:193], v[72:75]
	s_setprio 0
	s_bitcmp1_b32 s30, 8
	s_cbranch_scc0 .Leb973_8
	s_setprio 1
.Leb973_8:
	s_add_i32 s20, s47, s36
	s_add_u32 s80, s24, 0x80
	s_addc_u32 s81, s25, 0
	s_mov_b32 m0, s20
	ds_read_b128 v[194:197], v205
	ds_read_b128 v[208:211], v205 offset:1024
	ds_read_b128 v[212:215], v205 offset:2048
	ds_read_b128 v[216:219], v205 offset:3072
	global_load_lds_dwordx4 v130, s[24:25]
	s_add_i32 m0, s20, 0x2000
	s_nop 0
	global_load_lds_dwordx4 v134, s[24:25]
	s_waitcnt vmcnt(10)
	s_barrier
	s_waitcnt lgkmcnt(0)
	s_waitcnt lgkmcnt(0)
	v_mfma_f32_16x16x32_bf16 v[116:119], v[194:197], v[162:165], v[116:119]
	v_mfma_f32_16x16x32_bf16 v[112:115], v[212:215], v[162:165], v[112:115]
	v_mfma_f32_16x16x32_bf16 v[100:103], v[194:197], v[170:173], v[100:103]
	v_mfma_f32_16x16x32_bf16 v[96:99], v[212:215], v[170:173], v[96:99]
	v_mfma_f32_16x16x32_bf16 v[84:87], v[194:197], v[178:181], v[84:87]
	v_mfma_f32_16x16x32_bf16 v[80:83], v[212:215], v[178:181], v[80:83]
	v_mfma_f32_16x16x32_bf16 v[68:71], v[194:197], v[186:189], v[68:71]
	v_mfma_f32_16x16x32_bf16 v[64:67], v[212:215], v[186:189], v[64:67]
	v_mfma_f32_16x16x32_bf16 v[116:119], v[208:211], v[166:169], v[116:119]
	v_mfma_f32_16x16x32_bf16 v[112:115], v[216:219], v[166:169], v[112:115]
	v_mfma_f32_16x16x32_bf16 v[100:103], v[208:211], v[174:177], v[100:103]
	v_mfma_f32_16x16x32_bf16 v[96:99], v[216:219], v[174:177], v[96:99]
	v_mfma_f32_16x16x32_bf16 v[84:87], v[208:211], v[182:185], v[84:87]
	v_mfma_f32_16x16x32_bf16 v[80:83], v[216:219], v[182:185], v[80:83]
	v_mfma_f32_16x16x32_bf16 v[68:71], v[208:211], v[190:193], v[68:71]
	s_barrier
	s_setprio 3
	v_mfma_f32_16x16x32_bf16 v[64:67], v[216:219], v[190:193], v[64:67]
	s_setprio 0
	s_bitcmp1_b32 s30, 8
	s_cbranch_scc0 .Leb973_7
	s_setprio 1
.Leb973_7:
	s_mov_b32 m0, s37
	s_add_u32 s82, s26, 0x80
	s_addc_u32 s83, s27, 0
	ds_read_b128 v[162:165], v204 offset:16384
	ds_read_b128 v[166:169], v204 offset:17408
	ds_read_b128 v[170:173], v204 offset:18432
	ds_read_b128 v[174:177], v204 offset:19456
	ds_read_b128 v[178:181], v204 offset:20480
	ds_read_b128 v[182:185], v204 offset:21504
	ds_read_b128 v[186:189], v204 offset:22528
	ds_read_b128 v[190:193], v204 offset:23552
	global_load_lds_dwordx4 v128, s[26:27]
	s_mov_b32 m0, s38
	s_nop 0
	global_load_lds_dwordx4 v132, s[26:27]
	s_barrier
	s_waitcnt lgkmcnt(0)
	s_waitcnt lgkmcnt(0)
	v_mfma_f32_16x16x32_bf16 v[60:63], v[146:149], v[162:165], v[60:63]
	v_mfma_f32_16x16x32_bf16 v[56:59], v[154:157], v[162:165], v[56:59]
	v_mfma_f32_16x16x32_bf16 v[44:47], v[146:149], v[170:173], v[44:47]
	v_mfma_f32_16x16x32_bf16 v[40:43], v[154:157], v[170:173], v[40:43]
	v_mfma_f32_16x16x32_bf16 v[28:31], v[146:149], v[178:181], v[28:31]
	v_mfma_f32_16x16x32_bf16 v[24:27], v[154:157], v[178:181], v[24:27]
	v_mfma_f32_16x16x32_bf16 v[12:15], v[146:149], v[186:189], v[12:15]
	v_mfma_f32_16x16x32_bf16 v[8:11], v[154:157], v[186:189], v[8:11]
	v_mfma_f32_16x16x32_bf16 v[60:63], v[150:153], v[166:169], v[60:63]
	v_mfma_f32_16x16x32_bf16 v[56:59], v[158:161], v[166:169], v[56:59]
	v_mfma_f32_16x16x32_bf16 v[44:47], v[150:153], v[174:177], v[44:47]
	v_mfma_f32_16x16x32_bf16 v[40:43], v[158:161], v[174:177], v[40:43]
	v_mfma_f32_16x16x32_bf16 v[28:31], v[150:153], v[182:185], v[28:31]
	v_mfma_f32_16x16x32_bf16 v[24:27], v[158:161], v[182:185], v[24:27]
	v_mfma_f32_16x16x32_bf16 v[12:15], v[150:153], v[190:193], v[12:15]
	s_barrier
	s_setprio 3
	v_mfma_f32_16x16x32_bf16 v[8:11], v[158:161], v[190:193], v[8:11]
	s_setprio 0
	s_bitcmp1_b32 s30, 8
	s_cbranch_scc0 .Leb973_6
	s_setprio 1
.Leb973_6:
	s_add_u32 s20, s24, 0xb0000
	s_addc_u32 s21, s25, 0
	s_add_i32 s57, s48, s36
	s_mov_b32 m0, s57
	s_nop 0
	global_load_lds_dwordx4 v130, s[20:21]
	s_add_i32 m0, s57, 0x2000
	s_nop 0
	global_load_lds_dwordx4 v134, s[20:21]
	s_waitcnt vmcnt(8)
	s_barrier
	v_mfma_f32_16x16x32_bf16 v[52:55], v[194:197], v[162:165], v[52:55]
	v_mfma_f32_16x16x32_bf16 v[48:51], v[212:215], v[162:165], v[48:51]
	v_mfma_f32_16x16x32_bf16 v[36:39], v[194:197], v[170:173], v[36:39]
	v_mfma_f32_16x16x32_bf16 v[32:35], v[212:215], v[170:173], v[32:35]
	v_mfma_f32_16x16x32_bf16 v[20:23], v[194:197], v[178:181], v[20:23]
	v_mfma_f32_16x16x32_bf16 v[16:19], v[212:215], v[178:181], v[16:19]
	v_mfma_f32_16x16x32_bf16 v[4:7], v[194:197], v[186:189], v[4:7]
	v_mfma_f32_16x16x32_bf16 v[0:3], v[212:215], v[186:189], v[0:3]
	v_mfma_f32_16x16x32_bf16 v[52:55], v[208:211], v[166:169], v[52:55]
	v_mfma_f32_16x16x32_bf16 v[48:51], v[216:219], v[166:169], v[48:51]
	v_mfma_f32_16x16x32_bf16 v[36:39], v[208:211], v[174:177], v[36:39]
	v_mfma_f32_16x16x32_bf16 v[32:35], v[216:219], v[174:177], v[32:35]
	v_mfma_f32_16x16x32_bf16 v[20:23], v[208:211], v[182:185], v[20:23]
	v_mfma_f32_16x16x32_bf16 v[16:19], v[216:219], v[182:185], v[16:19]
	v_mfma_f32_16x16x32_bf16 v[4:7], v[208:211], v[190:193], v[4:7]
	s_barrier
	s_setprio 3
	v_mfma_f32_16x16x32_bf16 v[0:3], v[216:219], v[190:193], v[0:3]
	s_setprio 0
	s_bitcmp1_b32 s30, 8
	s_cbranch_scc0 .Leb973_5
	s_setprio 1
.Leb973_5:
	s_add_i32 s57, 0, 0x18000
	v_add_u32_e32 v158, s57, v201
.Lg973_mid:
	ds_read_b128 v[146:149], v158
	ds_read_b128 v[150:153], v158 offset:1024
	ds_read_b128 v[154:157], v158 offset:2048
	ds_read_b128 v[158:161], v158 offset:3072
	s_add_u32 s20, s26, 0xb0000
	s_addc_u32 s21, s27, 0
	s_mov_b32 m0, s39
	ds_read_b128 v[162:165], v204 offset:32768
	ds_read_b128 v[166:169], v204 offset:33792
	ds_read_b128 v[170:173], v204 offset:34816
	ds_read_b128 v[174:177], v204 offset:35840
	ds_read_b128 v[178:181], v204 offset:36864
	ds_read_b128 v[182:185], v204 offset:37888
	ds_read_b128 v[186:189], v204 offset:38912
	ds_read_b128 v[190:193], v204 offset:39936
	global_load_lds_dwordx4 v128, s[20:21]
	s_mov_b32 m0, s40
	s_nop 0
	global_load_lds_dwordx4 v132, s[20:21]
	s_waitcnt lgkmcnt(8)
	s_barrier
	s_waitcnt lgkmcnt(0)
	s_waitcnt lgkmcnt(0)
	v_mfma_f32_16x16x32_bf16 v[124:127], v[146:149], v[162:165], v[124:127]
	v_mfma_f32_16x16x32_bf16 v[120:123], v[154:157], v[162:165], v[120:123]
	v_mfma_f32_16x16x32_bf16 v[108:111], v[146:149], v[170:173], v[108:111]
	v_mfma_f32_16x16x32_bf16 v[104:107], v[154:157], v[170:173], v[104:107]
	v_mfma_f32_16x16x32_bf16 v[92:95], v[146:149], v[178:181], v[92:95]
	v_mfma_f32_16x16x32_bf16 v[88:91], v[154:157], v[178:181], v[88:91]
	v_mfma_f32_16x16x32_bf16 v[76:79], v[146:149], v[186:189], v[76:79]
	v_mfma_f32_16x16x32_bf16 v[72:75], v[154:157], v[186:189], v[72:75]
	v_mfma_f32_16x16x32_bf16 v[124:127], v[150:153], v[166:169], v[124:127]
	v_mfma_f32_16x16x32_bf16 v[120:123], v[158:161], v[166:169], v[120:123]
	v_mfma_f32_16x16x32_bf16 v[108:111], v[150:153], v[174:177], v[108:111]
	v_mfma_f32_16x16x32_bf16 v[104:107], v[158:161], v[174:177], v[104:107]
	v_mfma_f32_16x16x32_bf16 v[92:95], v[150:153], v[182:185], v[92:95]
	v_mfma_f32_16x16x32_bf16 v[88:91], v[158:161], v[182:185], v[88:91]
	v_mfma_f32_16x16x32_bf16 v[76:79], v[150:153], v[190:193], v[76:79]
	s_barrier
	s_setprio 3
	v_mfma_f32_16x16x32_bf16 v[72:75], v[158:161], v[190:193], v[72:75]
	s_setprio 0
	s_bitcmp1_b32 s30, 8
	s_cbranch_scc0 .Leb973_4
	s_setprio 1
.Leb973_4:
	s_add_i32 s26, 0, 0x1c000
	s_add_i32 s20, s57, s36
	v_add_u32_e32 v216, s26, v201
	s_mov_b32 m0, s20
	ds_read_b128 v[194:197], v216
	ds_read_b128 v[208:211], v216 offset:1024
	ds_read_b128 v[212:215], v216 offset:2048
	ds_read_b128 v[216:219], v216 offset:3072
	global_load_lds_dwordx4 v130, s[80:81]
	s_add_i32 m0, s20, 0x2000
	s_nop 0
	global_load_lds_dwordx4 v134, s[80:81]
	s_waitcnt vmcnt(10)
	s_barrier
	s_waitcnt lgkmcnt(0)
	s_waitcnt lgkmcnt(0)
	v_mfma_f32_16x16x32_bf16 v[116:119], v[194:197], v[162:165], v[116:119]
	v_mfma_f32_16x16x32_bf16 v[112:115], v[212:215], v[162:165], v[112:115]
	v_mfma_f32_16x16x32_bf16 v[100:103], v[194:197], v[170:173], v[100:103]
	v_mfma_f32_16x16x32_bf16 v[96:99], v[212:215], v[170:173], v[96:99]
	v_mfma_f32_16x16x32_bf16 v[84:87], v[194:197], v[178:181], v[84:87]
	v_mfma_f32_16x16x32_bf16 v[80:83], v[212:215], v[178:181], v[80:83]
	v_mfma_f32_16x16x32_bf16 v[68:71], v[194:197], v[186:189], v[68:71]
	v_mfma_f32_16x16x32_bf16 v[64:67], v[212:215], v[186:189], v[64:67]
	v_mfma_f32_16x16x32_bf16 v[116:119], v[208:211], v[166:169], v[116:119]
	v_mfma_f32_16x16x32_bf16 v[112:115], v[216:219], v[166:169], v[112:115]
	v_mfma_f32_16x16x32_bf16 v[100:103], v[208:211], v[174:177], v[100:103]
	v_mfma_f32_16x16x32_bf16 v[96:99], v[216:219], v[174:177], v[96:99]
	v_mfma_f32_16x16x32_bf16 v[84:87], v[208:211], v[182:185], v[84:87]
	v_mfma_f32_16x16x32_bf16 v[80:83], v[216:219], v[182:185], v[80:83]
	v_mfma_f32_16x16x32_bf16 v[68:71], v[208:211], v[190:193], v[68:71]
	s_barrier
	s_setprio 3
	v_mfma_f32_16x16x32_bf16 v[64:67], v[216:219], v[190:193], v[64:67]
	s_setprio 0
	s_bitcmp1_b32 s30, 8
	s_cbranch_scc0 .Leb973_3
	s_setprio 1
.Leb973_3:
	s_mov_b32 m0, s42
	ds_read_b128 v[162:165], v204 offset:49152
	ds_read_b128 v[166:169], v204 offset:50176
	ds_read_b128 v[170:173], v204 offset:51200
	ds_read_b128 v[174:177], v204 offset:52224
	ds_read_b128 v[178:181], v204 offset:53248
	ds_read_b128 v[182:185], v204 offset:54272
	ds_read_b128 v[186:189], v204 offset:55296
	ds_read_b128 v[190:193], v204 offset:56320
	global_load_lds_dwordx4 v128, s[82:83]
	s_mov_b32 m0, s43
	s_nop 0
	global_load_lds_dwordx4 v132, s[82:83]
	s_barrier
	s_waitcnt lgkmcnt(0)
	s_waitcnt lgkmcnt(0)
	v_mfma_f32_16x16x32_bf16 v[60:63], v[146:149], v[162:165], v[60:63]
	v_mfma_f32_16x16x32_bf16 v[56:59], v[154:157], v[162:165], v[56:59]
	v_mfma_f32_16x16x32_bf16 v[44:47], v[146:149], v[170:173], v[44:47]
	v_mfma_f32_16x16x32_bf16 v[40:43], v[154:157], v[170:173], v[40:43]
	v_mfma_f32_16x16x32_bf16 v[28:31], v[146:149], v[178:181], v[28:31]
	v_mfma_f32_16x16x32_bf16 v[24:27], v[154:157], v[178:181], v[24:27]
	v_mfma_f32_16x16x32_bf16 v[12:15], v[146:149], v[186:189], v[12:15]
	v_mfma_f32_16x16x32_bf16 v[8:11], v[154:157], v[186:189], v[8:11]
	v_mfma_f32_16x16x32_bf16 v[60:63], v[150:153], v[166:169], v[60:63]
	v_mfma_f32_16x16x32_bf16 v[56:59], v[158:161], v[166:169], v[56:59]
	v_mfma_f32_16x16x32_bf16 v[44:47], v[150:153], v[174:177], v[44:47]
	v_mfma_f32_16x16x32_bf16 v[40:43], v[158:161], v[174:177], v[40:43]
	v_mfma_f32_16x16x32_bf16 v[28:31], v[150:153], v[182:185], v[28:31]
	v_mfma_f32_16x16x32_bf16 v[24:27], v[158:161], v[182:185], v[24:27]
	v_mfma_f32_16x16x32_bf16 v[12:15], v[150:153], v[190:193], v[12:15]
	s_barrier
	s_setprio 3
	v_mfma_f32_16x16x32_bf16 v[8:11], v[158:161], v[190:193], v[8:11]
	s_setprio 0
	s_bitcmp1_b32 s30, 8
	s_cbranch_scc0 .Leb973_2
	s_setprio 1
.Leb973_2:
	s_add_u32 s20, s24, 0xb0080
	s_addc_u32 s21, s25, 0
	s_add_i32 s24, s26, s36
	s_mov_b32 m0, s24
	s_nop 0
	global_load_lds_dwordx4 v130, s[20:21]
	s_add_i32 m0, s24, 0x2000
	s_nop 0
	global_load_lds_dwordx4 v134, s[20:21]
	s_waitcnt vmcnt(8)
	s_barrier
	v_mfma_f32_16x16x32_bf16 v[52:55], v[194:197], v[162:165], v[52:55]
	v_mfma_f32_16x16x32_bf16 v[48:51], v[212:215], v[162:165], v[48:51]
	v_mfma_f32_16x16x32_bf16 v[36:39], v[194:197], v[170:173], v[36:39]
	v_mfma_f32_16x16x32_bf16 v[32:35], v[212:215], v[170:173], v[32:35]
	v_mfma_f32_16x16x32_bf16 v[20:23], v[194:197], v[178:181], v[20:23]
	v_mfma_f32_16x16x32_bf16 v[16:19], v[212:215], v[178:181], v[16:19]
	v_mfma_f32_16x16x32_bf16 v[4:7], v[194:197], v[186:189], v[4:7]
	v_mfma_f32_16x16x32_bf16 v[0:3], v[212:215], v[186:189], v[0:3]
	v_mfma_f32_16x16x32_bf16 v[52:55], v[208:211], v[166:169], v[52:55]
	v_mfma_f32_16x16x32_bf16 v[48:51], v[216:219], v[166:169], v[48:51]
	v_mfma_f32_16x16x32_bf16 v[36:39], v[208:211], v[174:177], v[36:39]
	v_mfma_f32_16x16x32_bf16 v[32:35], v[216:219], v[174:177], v[32:35]
	v_mfma_f32_16x16x32_bf16 v[20:23], v[208:211], v[182:185], v[20:23]
	v_mfma_f32_16x16x32_bf16 v[16:19], v[216:219], v[182:185], v[16:19]
	v_mfma_f32_16x16x32_bf16 v[4:7], v[208:211], v[190:193], v[4:7]
	s_barrier
	s_setprio 3
	v_mfma_f32_16x16x32_bf16 v[0:3], v[216:219], v[190:193], v[0:3]
	s_setprio 0
	s_bitcmp1_b32 s30, 8
	s_cbranch_scc0 .Leb973_1
	s_setprio 1
.Leb973_1:
	s_add_i32 s56, s56, 2
	s_add_u32 s54, s54, 0x100
	s_addc_u32 s55, s55, 0
	s_cmp_gt_u32 s56, 41
	s_mov_b64 s[20:21], s[22:23]
	s_cbranch_scc0 .LBB0_973
	s_nop 7
	s_nop 7
	s_setprio 0
	s_cmpk_gt_u32 s30, 0xff
	s_cbranch_scc1 .Lg973_nox
	s_barrier
	s_setprio 1
